# plus: removed the two no-op waits left before each GEMM MFMA block; packed-softmax temps moved off v244-249
# baseline (speedup 1.0000x reference)
.LBB0_304:
	s_add_u32 s2, s68, 0xfff80080
	s_addc_u32 s17, s69, -1
	s_add_i32 s26, 0, 0x10000
	v_add_u32_e32 v156, s26, v141
	ds_read_b128 v[144:147], v156
	ds_read_b128 v[148:151], v156 offset:1024
	ds_read_b128 v[152:155], v156 offset:2048
	ds_read_b128 v[156:159], v156 offset:3072
	s_cmp_eq_u32 s44, 28
	s_cselect_b32 s73, s55, s17
	s_cselect_b32 s72, s83, s2
	s_cselect_b32 s71, s24, s92
	s_cselect_b32 s70, s25, s43
	v_lshl_add_u64 v[164:165], s[68:69], 0, v[136:137]
	s_add_i32 m0, s58, 0xc000
	ds_read_b128 v[160:163], v143
	ds_read_b128 v[188:191], v143 offset:1024
	ds_read_b128 v[192:195], v143 offset:2048
	ds_read_b128 v[196:199], v143 offset:3072
	ds_read_b128 v[200:203], v143 offset:4096
	ds_read_b128 v[216:219], v143 offset:5120
	ds_read_b128 v[220:223], v143 offset:6144
	ds_read_b128 v[224:227], v143 offset:7168
	global_load_lds_dwordx4 v[164:165], off
	v_lshl_add_u64 v[164:165], s[68:69], 0, v[138:139]
	s_add_i32 m0, s58, 0xe000
	s_nop 0
	global_load_lds_dwordx4 v[164:165], off
	s_waitcnt lgkmcnt(8)
	s_barrier
	s_waitcnt lgkmcnt(7)
	v_mfma_f32_16x16x32_bf16 v[126:129], v[144:147], v[160:163], v[126:129]
	v_mfma_f32_16x16x32_bf16 v[122:125], v[152:155], v[160:163], v[122:125]
	s_waitcnt lgkmcnt(5)
	v_mfma_f32_16x16x32_bf16 v[118:121], v[144:147], v[192:195], v[118:121]
	v_mfma_f32_16x16x32_bf16 v[114:117], v[152:155], v[192:195], v[114:117]
	s_waitcnt lgkmcnt(3)
	v_mfma_f32_16x16x32_bf16 v[102:105], v[144:147], v[200:203], v[102:105]
	v_mfma_f32_16x16x32_bf16 v[98:101], v[152:155], v[200:203], v[98:101]
	s_waitcnt lgkmcnt(1)
	v_mfma_f32_16x16x32_bf16 v[86:89], v[144:147], v[220:223], v[86:89]
	v_mfma_f32_16x16x32_bf16 v[82:85], v[152:155], v[220:223], v[82:85]
	v_mfma_f32_16x16x32_bf16 v[126:129], v[148:151], v[188:191], v[126:129]
	v_mfma_f32_16x16x32_bf16 v[122:125], v[156:159], v[188:191], v[122:125]
	v_mfma_f32_16x16x32_bf16 v[118:121], v[148:151], v[196:199], v[118:121]
	v_mfma_f32_16x16x32_bf16 v[114:117], v[156:159], v[196:199], v[114:117]
	v_mfma_f32_16x16x32_bf16 v[102:105], v[148:151], v[216:219], v[102:105]
	v_mfma_f32_16x16x32_bf16 v[98:101], v[156:159], v[216:219], v[98:101]
	s_waitcnt lgkmcnt(0)
	v_mfma_f32_16x16x32_bf16 v[86:89], v[148:151], v[224:227], v[86:89]
	v_mfma_f32_16x16x32_bf16 v[82:85], v[156:159], v[224:227], v[82:85]
	s_barrier
	s_add_i32 s2, 0, 0x14000
	v_add_u32_e32 v164, s2, v141
	s_add_i32 s17, s26, s3
	ds_read_b128 v[228:231], v164
	ds_read_b128 v[232:235], v164 offset:1024
	ds_read_b128 v[236:239], v164 offset:2048
	ds_read_b128 v[240:243], v164 offset:3072
	v_lshl_add_u64 v[164:165], s[70:71], 0, v[0:1]
	s_mov_b32 m0, s17
	v_lshl_add_u64 v[204:205], s[70:71], 0, v[130:131]
	global_load_lds_dwordx4 v[164:165], off
	s_add_i32 m0, s17, 0x2000
	s_nop 0
	global_load_lds_dwordx4 v[204:205], off
	s_barrier
	s_waitcnt lgkmcnt(3)
	v_mfma_f32_16x16x32_bf16 v[110:113], v[228:231], v[160:163], v[110:113]
	s_waitcnt lgkmcnt(1)
	v_mfma_f32_16x16x32_bf16 v[106:109], v[236:239], v[160:163], v[106:109]
	v_mfma_f32_16x16x32_bf16 v[94:97], v[228:231], v[192:195], v[94:97]
	v_mfma_f32_16x16x32_bf16 v[90:93], v[236:239], v[192:195], v[90:93]
	v_mfma_f32_16x16x32_bf16 v[78:81], v[228:231], v[200:203], v[78:81]
	v_mfma_f32_16x16x32_bf16 v[74:77], v[236:239], v[200:203], v[74:77]
	v_mfma_f32_16x16x32_bf16 v[70:73], v[228:231], v[220:223], v[70:73]
	v_mfma_f32_16x16x32_bf16 v[66:69], v[236:239], v[220:223], v[66:69]
	v_mfma_f32_16x16x32_bf16 v[110:113], v[232:235], v[188:191], v[110:113]
	s_waitcnt lgkmcnt(0)
	v_mfma_f32_16x16x32_bf16 v[106:109], v[240:243], v[188:191], v[106:109]
	v_mfma_f32_16x16x32_bf16 v[94:97], v[232:235], v[196:199], v[94:97]
	v_mfma_f32_16x16x32_bf16 v[90:93], v[240:243], v[196:199], v[90:93]
	v_mfma_f32_16x16x32_bf16 v[78:81], v[232:235], v[216:219], v[78:81]
	v_mfma_f32_16x16x32_bf16 v[74:77], v[240:243], v[216:219], v[74:77]
	v_mfma_f32_16x16x32_bf16 v[70:73], v[232:235], v[224:227], v[70:73]
	v_mfma_f32_16x16x32_bf16 v[66:69], v[240:243], v[224:227], v[66:69]
	s_mov_b32 m0, s58
	v_lshl_add_u64 v[244:245], s[72:73], 0, v[134:135]
	s_barrier
	ds_read_b128 v[160:163], v143 offset:16384
	ds_read_b128 v[188:191], v143 offset:17408
	ds_read_b128 v[192:195], v143 offset:18432
	ds_read_b128 v[196:199], v143 offset:19456
	ds_read_b128 v[200:203], v143 offset:20480
	ds_read_b128 v[216:219], v143 offset:21504
	ds_read_b128 v[220:223], v143 offset:22528
	ds_read_b128 v[224:227], v143 offset:23552
	global_load_lds_dwordx4 v[244:245], off
	v_lshl_add_u64 v[246:247], s[72:73], 0, v[132:133]
	s_mov_b32 m0, s74
	s_nop 0
	global_load_lds_dwordx4 v[246:247], off
	s_barrier
	s_waitcnt lgkmcnt(7)
	v_mfma_f32_16x16x32_bf16 v[62:65], v[144:147], v[160:163], v[62:65]
	v_mfma_f32_16x16x32_bf16 v[58:61], v[152:155], v[160:163], v[58:61]
	s_waitcnt lgkmcnt(5)
	v_mfma_f32_16x16x32_bf16 v[54:57], v[144:147], v[192:195], v[54:57]
	v_mfma_f32_16x16x32_bf16 v[50:53], v[152:155], v[192:195], v[50:53]
	s_waitcnt lgkmcnt(3)
	v_mfma_f32_16x16x32_bf16 v[38:41], v[144:147], v[200:203], v[38:41]
	v_mfma_f32_16x16x32_bf16 v[34:37], v[152:155], v[200:203], v[34:37]
	s_waitcnt lgkmcnt(1)
	v_mfma_f32_16x16x32_bf16 v[22:25], v[144:147], v[220:223], v[22:25]
	v_mfma_f32_16x16x32_bf16 v[18:21], v[152:155], v[220:223], v[18:21]
	v_mfma_f32_16x16x32_bf16 v[62:65], v[148:151], v[188:191], v[62:65]
	v_mfma_f32_16x16x32_bf16 v[58:61], v[156:159], v[188:191], v[58:61]
	v_mfma_f32_16x16x32_bf16 v[54:57], v[148:151], v[196:199], v[54:57]
	v_mfma_f32_16x16x32_bf16 v[50:53], v[156:159], v[196:199], v[50:53]
	v_mfma_f32_16x16x32_bf16 v[38:41], v[148:151], v[216:219], v[38:41]
	v_mfma_f32_16x16x32_bf16 v[34:37], v[156:159], v[216:219], v[34:37]
	s_waitcnt lgkmcnt(0)
	v_mfma_f32_16x16x32_bf16 v[22:25], v[148:151], v[224:227], v[22:25]
	v_mfma_f32_16x16x32_bf16 v[18:21], v[156:159], v[224:227], v[18:21]
	s_barrier
	s_add_u32 s26, s70, 0x80000
	s_addc_u32 s27, s71, 0
	s_add_i32 s2, s2, s3
	v_lshl_add_u64 v[144:145], s[26:27], 0, v[0:1]
	s_mov_b32 m0, s2
	s_nop 0
	global_load_lds_dwordx4 v[144:145], off
	v_lshl_add_u64 v[144:145], s[26:27], 0, v[130:131]
	s_add_i32 m0, s2, 0x2000
	s_nop 0
	global_load_lds_dwordx4 v[144:145], off
	s_waitcnt vmcnt(6)
	s_barrier
	v_mfma_f32_16x16x32_bf16 v[46:49], v[228:231], v[160:163], v[46:49]
	v_mfma_f32_16x16x32_bf16 v[42:45], v[236:239], v[160:163], v[42:45]
	v_mfma_f32_16x16x32_bf16 v[30:33], v[228:231], v[192:195], v[30:33]
	v_mfma_f32_16x16x32_bf16 v[26:29], v[236:239], v[192:195], v[26:29]
	v_mfma_f32_16x16x32_bf16 v[14:17], v[228:231], v[200:203], v[14:17]
	v_mfma_f32_16x16x32_bf16 v[10:13], v[236:239], v[200:203], v[10:13]
	v_mfma_f32_16x16x32_bf16 v[6:9], v[228:231], v[220:223], v[6:9]
	v_mfma_f32_16x16x32_bf16 v[2:5], v[236:239], v[220:223], v[2:5]
	v_mfma_f32_16x16x32_bf16 v[46:49], v[232:235], v[188:191], v[46:49]
	v_mfma_f32_16x16x32_bf16 v[42:45], v[240:243], v[188:191], v[42:45]
	v_mfma_f32_16x16x32_bf16 v[30:33], v[232:235], v[196:199], v[30:33]
	v_mfma_f32_16x16x32_bf16 v[26:29], v[240:243], v[196:199], v[26:29]
	v_mfma_f32_16x16x32_bf16 v[14:17], v[232:235], v[216:219], v[14:17]
	v_mfma_f32_16x16x32_bf16 v[10:13], v[240:243], v[216:219], v[10:13]
	v_mfma_f32_16x16x32_bf16 v[6:9], v[232:235], v[224:227], v[6:9]
	v_mfma_f32_16x16x32_bf16 v[2:5], v[240:243], v[224:227], v[2:5]
	s_add_i32 s2, 0, 0x18000
	v_add_u32_e32 v156, s2, v141
	s_barrier
	ds_read_b128 v[144:147], v156
	ds_read_b128 v[148:151], v156 offset:1024
	ds_read_b128 v[152:155], v156 offset:2048
	ds_read_b128 v[156:159], v156 offset:3072
	s_add_u32 s26, s72, 0x80000
	s_addc_u32 s27, s73, 0
	s_mov_b32 m0, s75
	v_lshl_add_u64 v[228:229], s[26:27], 0, v[134:135]
	ds_read_b128 v[160:163], v143 offset:32768
	ds_read_b128 v[188:191], v143 offset:33792
	ds_read_b128 v[192:195], v143 offset:34816
	ds_read_b128 v[196:199], v143 offset:35840
	ds_read_b128 v[200:203], v143 offset:36864
	ds_read_b128 v[216:219], v143 offset:37888
	ds_read_b128 v[220:223], v143 offset:38912
	ds_read_b128 v[224:227], v143 offset:39936
	global_load_lds_dwordx4 v[228:229], off
	v_lshl_add_u64 v[228:229], s[26:27], 0, v[132:133]
	s_mov_b32 m0, s79
	s_nop 0
	global_load_lds_dwordx4 v[228:229], off
	s_waitcnt lgkmcnt(8)
	s_barrier
	s_waitcnt lgkmcnt(7)
	v_mfma_f32_16x16x32_bf16 v[126:129], v[144:147], v[160:163], v[126:129]
	v_mfma_f32_16x16x32_bf16 v[122:125], v[152:155], v[160:163], v[122:125]
	s_waitcnt lgkmcnt(5)
	v_mfma_f32_16x16x32_bf16 v[118:121], v[144:147], v[192:195], v[118:121]
	v_mfma_f32_16x16x32_bf16 v[114:117], v[152:155], v[192:195], v[114:117]
	s_waitcnt lgkmcnt(3)
	v_mfma_f32_16x16x32_bf16 v[102:105], v[144:147], v[200:203], v[102:105]
	v_mfma_f32_16x16x32_bf16 v[98:101], v[152:155], v[200:203], v[98:101]
	s_waitcnt lgkmcnt(1)
	v_mfma_f32_16x16x32_bf16 v[86:89], v[144:147], v[220:223], v[86:89]
	v_mfma_f32_16x16x32_bf16 v[82:85], v[152:155], v[220:223], v[82:85]
	v_mfma_f32_16x16x32_bf16 v[126:129], v[148:151], v[188:191], v[126:129]
	v_mfma_f32_16x16x32_bf16 v[122:125], v[156:159], v[188:191], v[122:125]
	v_mfma_f32_16x16x32_bf16 v[118:121], v[148:151], v[196:199], v[118:121]
	v_mfma_f32_16x16x32_bf16 v[114:117], v[156:159], v[196:199], v[114:117]
	v_mfma_f32_16x16x32_bf16 v[102:105], v[148:151], v[216:219], v[102:105]
	v_mfma_f32_16x16x32_bf16 v[98:101], v[156:159], v[216:219], v[98:101]
	s_waitcnt lgkmcnt(0)
	v_mfma_f32_16x16x32_bf16 v[86:89], v[148:151], v[224:227], v[86:89]
	v_mfma_f32_16x16x32_bf16 v[82:85], v[156:159], v[224:227], v[82:85]
	s_barrier
	s_add_i32 s17, 0, 0x1c000
	s_add_i32 s2, s2, s3
	v_add_u32_e32 v206, s17, v141
	v_lshl_add_u64 v[164:165], v[164:165], 0, s[28:29]
	s_mov_b32 m0, s2
	ds_read_b128 v[228:231], v206
	ds_read_b128 v[232:235], v206 offset:1024
	ds_read_b128 v[236:239], v206 offset:2048
	ds_read_b128 v[240:243], v206 offset:3072
	global_load_lds_dwordx4 v[164:165], off
	v_lshl_add_u64 v[164:165], v[204:205], 0, s[28:29]
	s_add_i32 m0, s2, 0x2000
	s_nop 0
	global_load_lds_dwordx4 v[164:165], off
	s_barrier
	s_waitcnt lgkmcnt(3)
	v_mfma_f32_16x16x32_bf16 v[110:113], v[228:231], v[160:163], v[110:113]
	s_waitcnt lgkmcnt(1)
	v_mfma_f32_16x16x32_bf16 v[106:109], v[236:239], v[160:163], v[106:109]
	v_mfma_f32_16x16x32_bf16 v[94:97], v[228:231], v[192:195], v[94:97]
	v_mfma_f32_16x16x32_bf16 v[90:93], v[236:239], v[192:195], v[90:93]
	v_mfma_f32_16x16x32_bf16 v[78:81], v[228:231], v[200:203], v[78:81]
	v_mfma_f32_16x16x32_bf16 v[74:77], v[236:239], v[200:203], v[74:77]
	v_mfma_f32_16x16x32_bf16 v[70:73], v[228:231], v[220:223], v[70:73]
	v_mfma_f32_16x16x32_bf16 v[66:69], v[236:239], v[220:223], v[66:69]
	v_mfma_f32_16x16x32_bf16 v[110:113], v[232:235], v[188:191], v[110:113]
	s_waitcnt lgkmcnt(0)
	v_mfma_f32_16x16x32_bf16 v[106:109], v[240:243], v[188:191], v[106:109]
	v_mfma_f32_16x16x32_bf16 v[94:97], v[232:235], v[196:199], v[94:97]
	v_mfma_f32_16x16x32_bf16 v[90:93], v[240:243], v[196:199], v[90:93]
	v_mfma_f32_16x16x32_bf16 v[78:81], v[232:235], v[216:219], v[78:81]
	v_mfma_f32_16x16x32_bf16 v[74:77], v[240:243], v[216:219], v[74:77]
	v_mfma_f32_16x16x32_bf16 v[70:73], v[232:235], v[224:227], v[70:73]
	v_mfma_f32_16x16x32_bf16 v[66:69], v[240:243], v[224:227], v[66:69]
	s_mov_b32 m0, s80
	v_lshl_add_u64 v[164:165], v[244:245], 0, s[28:29]
	s_barrier
	ds_read_b128 v[160:163], v143 offset:49152
	ds_read_b128 v[188:191], v143 offset:50176
	ds_read_b128 v[192:195], v143 offset:51200
	ds_read_b128 v[196:199], v143 offset:52224
	ds_read_b128 v[200:203], v143 offset:53248
	ds_read_b128 v[216:219], v143 offset:54272
	ds_read_b128 v[220:223], v143 offset:55296
	ds_read_b128 v[224:227], v143 offset:56320
	global_load_lds_dwordx4 v[164:165], off
	v_lshl_add_u64 v[164:165], v[246:247], 0, s[28:29]
	s_mov_b32 m0, s81
	s_nop 0
	global_load_lds_dwordx4 v[164:165], off
	s_barrier
	s_waitcnt lgkmcnt(7)
	v_mfma_f32_16x16x32_bf16 v[62:65], v[144:147], v[160:163], v[62:65]
	v_mfma_f32_16x16x32_bf16 v[58:61], v[152:155], v[160:163], v[58:61]
	s_waitcnt lgkmcnt(5)
	v_mfma_f32_16x16x32_bf16 v[54:57], v[144:147], v[192:195], v[54:57]
	v_mfma_f32_16x16x32_bf16 v[50:53], v[152:155], v[192:195], v[50:53]
	s_waitcnt lgkmcnt(3)
	v_mfma_f32_16x16x32_bf16 v[38:41], v[144:147], v[200:203], v[38:41]
	v_mfma_f32_16x16x32_bf16 v[34:37], v[152:155], v[200:203], v[34:37]
	s_waitcnt lgkmcnt(1)
	v_mfma_f32_16x16x32_bf16 v[22:25], v[144:147], v[220:223], v[22:25]
	v_mfma_f32_16x16x32_bf16 v[18:21], v[152:155], v[220:223], v[18:21]
	v_mfma_f32_16x16x32_bf16 v[62:65], v[148:151], v[188:191], v[62:65]
	v_mfma_f32_16x16x32_bf16 v[58:61], v[156:159], v[188:191], v[58:61]
	v_mfma_f32_16x16x32_bf16 v[54:57], v[148:151], v[196:199], v[54:57]
	v_mfma_f32_16x16x32_bf16 v[50:53], v[156:159], v[196:199], v[50:53]
	v_mfma_f32_16x16x32_bf16 v[38:41], v[148:151], v[216:219], v[38:41]
	v_mfma_f32_16x16x32_bf16 v[34:37], v[156:159], v[216:219], v[34:37]
	s_waitcnt lgkmcnt(0)
	v_mfma_f32_16x16x32_bf16 v[22:25], v[148:151], v[224:227], v[22:25]
	v_mfma_f32_16x16x32_bf16 v[18:21], v[156:159], v[224:227], v[18:21]
	s_barrier
	s_add_u32 s26, s70, 0x80080
	s_addc_u32 s27, s71, 0
	s_add_i32 s2, s17, s3
	v_lshl_add_u64 v[144:145], s[26:27], 0, v[0:1]
	s_mov_b32 m0, s2
	s_nop 0
	global_load_lds_dwordx4 v[144:145], off
	v_lshl_add_u64 v[144:145], s[26:27], 0, v[130:131]
	s_add_i32 m0, s2, 0x2000
	s_nop 0
	global_load_lds_dwordx4 v[144:145], off
	s_waitcnt vmcnt(6)
	s_barrier
	v_mfma_f32_16x16x32_bf16 v[46:49], v[228:231], v[160:163], v[46:49]
	v_mfma_f32_16x16x32_bf16 v[42:45], v[236:239], v[160:163], v[42:45]
	v_mfma_f32_16x16x32_bf16 v[30:33], v[228:231], v[192:195], v[30:33]
	v_mfma_f32_16x16x32_bf16 v[26:29], v[236:239], v[192:195], v[26:29]
	v_mfma_f32_16x16x32_bf16 v[14:17], v[228:231], v[200:203], v[14:17]
	v_mfma_f32_16x16x32_bf16 v[10:13], v[236:239], v[200:203], v[10:13]
	v_mfma_f32_16x16x32_bf16 v[6:9], v[228:231], v[220:223], v[6:9]
	v_mfma_f32_16x16x32_bf16 v[2:5], v[236:239], v[220:223], v[2:5]
	v_mfma_f32_16x16x32_bf16 v[46:49], v[232:235], v[188:191], v[46:49]
	v_mfma_f32_16x16x32_bf16 v[42:45], v[240:243], v[188:191], v[42:45]
	v_mfma_f32_16x16x32_bf16 v[30:33], v[232:235], v[196:199], v[30:33]
	v_mfma_f32_16x16x32_bf16 v[26:29], v[240:243], v[196:199], v[26:29]
	v_mfma_f32_16x16x32_bf16 v[14:17], v[232:235], v[216:219], v[14:17]
	v_mfma_f32_16x16x32_bf16 v[10:13], v[240:243], v[216:219], v[10:13]
	v_mfma_f32_16x16x32_bf16 v[6:9], v[232:235], v[224:227], v[6:9]
	v_mfma_f32_16x16x32_bf16 v[2:5], v[240:243], v[224:227], v[2:5]
	s_add_i32 s44, s44, 2
	s_add_u32 s68, s68, 0x100
	s_addc_u32 s69, s69, 0
	s_add_u32 s43, s43, 0x100
	s_addc_u32 s92, s92, 0
	s_cmp_gt_u32 s44, 29
	s_barrier
	s_cbranch_scc0 .LBB0_304
	v_lshl_add_u32 v146, s47, 8, v140
	v_lshl_or_b32 v144, s46, 8, v142
	v_cvt_pk_bf16_f32 v126, v126, v127
	v_cvt_pk_bf16_f32 v127, v128, v129
	v_cvt_pk_bf16_f32 v128, v122, v123
	v_mov_b64_e32 v[122:123], s[22:23]
	v_ashrrev_i32_e32 v145, 31, v144
	v_cvt_pk_bf16_f32 v70, v70, v71
	v_cvt_pk_bf16_f32 v71, v72, v73
	v_cvt_pk_bf16_f32 v72, v66, v67
	v_add_u32_e32 v66, 0x80, v146
	v_cvt_pk_bf16_f32 v129, v124, v125
	v_mad_i64_i32 v[124:125], s[24:25], v146, s97, v[122:123]
	v_lshlrev_b64 v[144:145], 1, v[144:145]
	v_cvt_pk_bf16_f32 v62, v62, v63
	v_cvt_pk_bf16_f32 v63, v64, v65
	v_cvt_pk_bf16_f32 v64, v58, v59
	v_mad_i64_i32 v[58:59], s[24:25], v66, s97, v[122:123]
	v_lshl_add_u64 v[124:125], v[124:125], 0, v[144:145]
	v_cvt_pk_bf16_f32 v110, v110, v111
	v_cvt_pk_bf16_f32 v111, v112, v113
	v_cvt_pk_bf16_f32 v112, v106, v107
	v_cvt_pk_bf16_f32 v113, v108, v109
	v_lshl_add_u64 v[58:59], v[58:59], 0, v[144:145]
	v_cvt_pk_bf16_f32 v46, v46, v47
	v_cvt_pk_bf16_f32 v47, v48, v49
	v_cvt_pk_bf16_f32 v48, v42, v43
	v_cvt_pk_bf16_f32 v49, v44, v45
	global_store_dwordx4 v[124:125], v[110:113], off offset:256
	global_store_dwordx4 v[58:59], v[46:49], off offset:256
	v_cvt_pk_bf16_f32 v94, v94, v95
	v_or_b32_e32 v110, 16, v146
	v_add_u32_e32 v46, 0x90, v146
	v_mad_i64_i32 v[110:111], s[24:25], v110, s97, v[122:123]
	v_mad_i64_i32 v[46:47], s[24:25], v46, s97, v[122:123]
	v_lshl_add_u64 v[110:111], v[110:111], 0, v[144:145]
	v_cvt_pk_bf16_f32 v95, v96, v97
	v_cvt_pk_bf16_f32 v96, v90, v91
	v_cvt_pk_bf16_f32 v97, v92, v93
	v_lshl_add_u64 v[46:47], v[46:47], 0, v[144:145]
	v_cvt_pk_bf16_f32 v30, v30, v31
	v_cvt_pk_bf16_f32 v31, v32, v33
	v_cvt_pk_bf16_f32 v32, v26, v27
	v_cvt_pk_bf16_f32 v33, v28, v29
	global_store_dwordx4 v[110:111], v[94:97], off offset:256
	global_store_dwordx4 v[46:47], v[30:33], off offset:256
	v_cvt_pk_bf16_f32 v78, v78, v79
	v_or_b32_e32 v94, 32, v146
	v_add_u32_e32 v30, 0xa0, v146
	v_mad_i64_i32 v[94:95], s[24:25], v94, s97, v[122:123]
	v_mad_i64_i32 v[30:31], s[24:25], v30, s97, v[122:123]
	v_lshl_add_u64 v[94:95], v[94:95], 0, v[144:145]
	v_cvt_pk_bf16_f32 v79, v80, v81
	v_cvt_pk_bf16_f32 v80, v74, v75
	v_cvt_pk_bf16_f32 v81, v76, v77
	v_lshl_add_u64 v[30:31], v[30:31], 0, v[144:145]
	v_cvt_pk_bf16_f32 v14, v14, v15
	v_cvt_pk_bf16_f32 v15, v16, v17
	v_cvt_pk_bf16_f32 v16, v10, v11
	v_cvt_pk_bf16_f32 v17, v12, v13
	global_store_dwordx4 v[94:95], v[78:81], off offset:256
	global_store_dwordx4 v[30:31], v[14:17], off offset:256
	v_cvt_pk_bf16_f32 v106, v118, v119
	v_or_b32_e32 v78, 48, v146
	v_add_u32_e32 v14, 0xb0, v146
	v_mad_i64_i32 v[78:79], s[24:25], v78, s97, v[122:123]
	v_mad_i64_i32 v[14:15], s[24:25], v14, s97, v[122:123]
	v_cvt_pk_bf16_f32 v107, v120, v121
	v_cvt_pk_bf16_f32 v108, v114, v115
	v_cvt_pk_bf16_f32 v109, v116, v117
	v_cvt_pk_bf16_f32 v90, v102, v103
	v_cvt_pk_bf16_f32 v91, v104, v105
	v_cvt_pk_bf16_f32 v92, v98, v99
	v_cvt_pk_bf16_f32 v93, v100, v101
	v_cvt_pk_bf16_f32 v74, v86, v87
	v_cvt_pk_bf16_f32 v75, v88, v89
	v_cvt_pk_bf16_f32 v76, v82, v83
	v_cvt_pk_bf16_f32 v77, v84, v85
	v_lshl_add_u64 v[78:79], v[78:79], 0, v[144:145]
	v_cvt_pk_bf16_f32 v73, v68, v69
	v_cvt_pk_bf16_f32 v65, v60, v61
	v_cvt_pk_bf16_f32 v42, v54, v55
	v_cvt_pk_bf16_f32 v43, v56, v57
	v_cvt_pk_bf16_f32 v44, v50, v51
	v_cvt_pk_bf16_f32 v45, v52, v53
	v_cvt_pk_bf16_f32 v26, v38, v39
	v_cvt_pk_bf16_f32 v27, v40, v41
	v_cvt_pk_bf16_f32 v28, v34, v35
	v_cvt_pk_bf16_f32 v29, v36, v37
	v_cvt_pk_bf16_f32 v10, v22, v23
	v_cvt_pk_bf16_f32 v11, v24, v25
	v_cvt_pk_bf16_f32 v12, v18, v19
	v_cvt_pk_bf16_f32 v13, v20, v21
	v_lshl_add_u64 v[14:15], v[14:15], 0, v[144:145]
	v_cvt_pk_bf16_f32 v6, v6, v7
	v_cvt_pk_bf16_f32 v7, v8, v9
	v_cvt_pk_bf16_f32 v8, v2, v3
	v_cvt_pk_bf16_f32 v9, v4, v5
	s_and_b64 vcc, exec, s[0:1]
	s_mov_b32 s46, s42
	s_mov_b32 s47, s54
	s_mov_b64 s[70:71], s[64:65]
	s_mov_b64 s[68:69], s[62:63]
	global_store_dwordx4 v[124:125], v[126:129], off
	global_store_dwordx4 v[110:111], v[106:109], off
	global_store_dwordx4 v[94:95], v[90:93], off
	global_store_dwordx4 v[78:79], v[74:77], off
	global_store_dwordx4 v[78:79], v[70:73], off offset:256
	global_store_dwordx4 v[58:59], v[62:65], off
	global_store_dwordx4 v[46:47], v[42:45], off
	global_store_dwordx4 v[30:31], v[26:29], off
	global_store_dwordx4 v[14:15], v[10:13], off
	global_store_dwordx4 v[14:15], v[6:9], off offset:256
	s_cbranch_vccz .LBB0_301
	v_readlane_b32 s0, v254, 12
	s_waitcnt vmcnt(0)
	v_readlane_b32 s1, v254, 13
	v_readlane_b32 s84, v251, 38
	v_readlane_b32 s18, v253, 0
	s_andn2_b64 vcc, exec, s[0:1]
	v_readlane_b32 s85, v251, 39
	v_readlane_b32 s86, v251, 40
	v_readlane_b32 s87, v251, 41
	v_readlane_b32 s14, v250, 63
	v_readlane_b32 s19, v253, 1
	s_cbranch_vccnz .LBB0_308
	s_barrier

.LBB0_433:
	s_add_u32 s6, s78, 0x100
	s_addc_u32 s7, s79, 0
	s_add_i32 s2, 0, 0x10000
	v_add_u32_e32 v0, s2, v153
	ds_read_b128 v[142:145], v0
	ds_read_b128 v[146:149], v0 offset:1024
	ds_read_b128 v[156:159], v0 offset:2048
	ds_read_b128 v[160:163], v0 offset:3072
	s_cmp_eq_u32 s44, 4
	s_cselect_b32 s83, s75, s7
	s_cselect_b32 s82, s74, s6
	s_cselect_b32 s81, s11, s46
	s_cselect_b32 s80, s24, s25
	v_lshl_add_u64 v[150:151], s[78:79], 0, v[138:139]
	s_add_i32 m0, s58, 0xc000
	ds_read_b128 v[188:191], v155
	ds_read_b128 v[192:195], v155 offset:1024
	ds_read_b128 v[196:199], v155 offset:2048
	ds_read_b128 v[200:203], v155 offset:3072
	ds_read_b128 v[216:219], v155 offset:4096
	ds_read_b128 v[220:223], v155 offset:5120
	ds_read_b128 v[224:227], v155 offset:6144
	ds_read_b128 v[228:231], v155 offset:7168
	global_load_lds_dwordx4 v[150:151], off
	v_lshl_add_u64 v[150:151], s[78:79], 0, v[140:141]
	s_add_i32 m0, s58, 0xe000
	s_nop 0
	global_load_lds_dwordx4 v[150:151], off
	s_waitcnt lgkmcnt(8)
	s_barrier
	s_waitcnt lgkmcnt(7)
	v_mfma_f32_16x16x32_bf16 v[126:129], v[142:145], v[188:191], v[126:129]
	v_mfma_f32_16x16x32_bf16 v[122:125], v[156:159], v[188:191], v[122:125]
	s_waitcnt lgkmcnt(5)
	v_mfma_f32_16x16x32_bf16 v[110:113], v[142:145], v[196:199], v[110:113]
	v_mfma_f32_16x16x32_bf16 v[106:109], v[156:159], v[196:199], v[106:109]
	s_waitcnt lgkmcnt(3)
	v_mfma_f32_16x16x32_bf16 v[94:97], v[142:145], v[216:219], v[94:97]
	v_mfma_f32_16x16x32_bf16 v[90:93], v[156:159], v[216:219], v[90:93]
	s_waitcnt lgkmcnt(1)
	v_mfma_f32_16x16x32_bf16 v[78:81], v[142:145], v[224:227], v[78:81]
	v_mfma_f32_16x16x32_bf16 v[74:77], v[156:159], v[224:227], v[74:77]
	v_mfma_f32_16x16x32_bf16 v[126:129], v[146:149], v[192:195], v[126:129]
	v_mfma_f32_16x16x32_bf16 v[122:125], v[160:163], v[192:195], v[122:125]
	v_mfma_f32_16x16x32_bf16 v[110:113], v[146:149], v[200:203], v[110:113]
	v_mfma_f32_16x16x32_bf16 v[106:109], v[160:163], v[200:203], v[106:109]
	v_mfma_f32_16x16x32_bf16 v[94:97], v[146:149], v[220:223], v[94:97]
	v_mfma_f32_16x16x32_bf16 v[90:93], v[160:163], v[220:223], v[90:93]
	s_waitcnt lgkmcnt(0)
	v_mfma_f32_16x16x32_bf16 v[78:81], v[146:149], v[228:231], v[78:81]
	v_mfma_f32_16x16x32_bf16 v[74:77], v[160:163], v[228:231], v[74:77]
	s_barrier
	s_add_i32 s17, 0, 0x14000
	s_add_i32 s2, s2, s3
	v_add_u32_e32 v0, s17, v153
	v_lshl_add_u64 v[150:151], s[80:81], 0, v[134:135]
	s_mov_b32 m0, s2
	ds_read_b128 v[232:235], v0
	ds_read_b128 v[236:239], v0 offset:1024
	ds_read_b128 v[240:243], v0 offset:2048
	ds_read_b128 v[244:247], v0 offset:3072
	global_load_lds_dwordx4 v[150:151], off
	v_lshl_add_u64 v[164:165], s[80:81], 0, v[130:131]
	s_add_i32 m0, s2, 0x2000
	s_nop 0
	global_load_lds_dwordx4 v[164:165], off
	s_barrier
	s_waitcnt lgkmcnt(3)
	v_mfma_f32_16x16x32_bf16 v[118:121], v[232:235], v[188:191], v[118:121]
	s_waitcnt lgkmcnt(1)
	v_mfma_f32_16x16x32_bf16 v[114:117], v[240:243], v[188:191], v[114:117]
	v_mfma_f32_16x16x32_bf16 v[102:105], v[232:235], v[196:199], v[102:105]
	v_mfma_f32_16x16x32_bf16 v[98:101], v[240:243], v[196:199], v[98:101]
	v_mfma_f32_16x16x32_bf16 v[86:89], v[232:235], v[216:219], v[86:89]
	v_mfma_f32_16x16x32_bf16 v[82:85], v[240:243], v[216:219], v[82:85]
	v_mfma_f32_16x16x32_bf16 v[70:73], v[232:235], v[224:227], v[70:73]
	v_mfma_f32_16x16x32_bf16 v[66:69], v[240:243], v[224:227], v[66:69]
	v_mfma_f32_16x16x32_bf16 v[118:121], v[236:239], v[192:195], v[118:121]
	s_waitcnt lgkmcnt(0)
	v_mfma_f32_16x16x32_bf16 v[114:117], v[244:247], v[192:195], v[114:117]
	v_mfma_f32_16x16x32_bf16 v[102:105], v[236:239], v[200:203], v[102:105]
	v_mfma_f32_16x16x32_bf16 v[98:101], v[244:247], v[200:203], v[98:101]
	v_mfma_f32_16x16x32_bf16 v[86:89], v[236:239], v[220:223], v[86:89]
	v_mfma_f32_16x16x32_bf16 v[82:85], v[244:247], v[220:223], v[82:85]
	v_mfma_f32_16x16x32_bf16 v[70:73], v[236:239], v[228:231], v[70:73]
	v_mfma_f32_16x16x32_bf16 v[66:69], v[244:247], v[228:231], v[66:69]
	s_mov_b32 m0, s58
	v_lshl_add_u64 v[204:205], s[82:83], 0, v[136:137]
	s_barrier
	ds_read_b128 v[188:191], v155 offset:16384
	ds_read_b128 v[192:195], v155 offset:17408
	ds_read_b128 v[196:199], v155 offset:18432
	ds_read_b128 v[200:203], v155 offset:19456
	ds_read_b128 v[216:219], v155 offset:20480
	ds_read_b128 v[220:223], v155 offset:21504
	ds_read_b128 v[224:227], v155 offset:22528
	ds_read_b128 v[228:231], v155 offset:23552
	global_load_lds_dwordx4 v[204:205], off
	v_lshl_add_u64 v[248:249], s[82:83], 0, v[132:133]
	s_mov_b32 m0, s69
	s_nop 0
	global_load_lds_dwordx4 v[248:249], off
	s_barrier
	s_waitcnt lgkmcnt(7)
	v_mfma_f32_16x16x32_bf16 v[62:65], v[142:145], v[188:191], v[62:65]
	v_mfma_f32_16x16x32_bf16 v[58:61], v[156:159], v[188:191], v[58:61]
	s_waitcnt lgkmcnt(5)
	v_mfma_f32_16x16x32_bf16 v[46:49], v[142:145], v[196:199], v[46:49]
	v_mfma_f32_16x16x32_bf16 v[42:45], v[156:159], v[196:199], v[42:45]
	s_waitcnt lgkmcnt(3)
	v_mfma_f32_16x16x32_bf16 v[30:33], v[142:145], v[216:219], v[30:33]
	v_mfma_f32_16x16x32_bf16 v[26:29], v[156:159], v[216:219], v[26:29]
	s_waitcnt lgkmcnt(1)
	v_mfma_f32_16x16x32_bf16 v[14:17], v[142:145], v[224:227], v[14:17]
	v_mfma_f32_16x16x32_bf16 v[10:13], v[156:159], v[224:227], v[10:13]
	v_mfma_f32_16x16x32_bf16 v[62:65], v[146:149], v[192:195], v[62:65]
	v_mfma_f32_16x16x32_bf16 v[58:61], v[160:163], v[192:195], v[58:61]
	v_mfma_f32_16x16x32_bf16 v[46:49], v[146:149], v[200:203], v[46:49]
	v_mfma_f32_16x16x32_bf16 v[42:45], v[160:163], v[200:203], v[42:45]
	v_mfma_f32_16x16x32_bf16 v[30:33], v[146:149], v[220:223], v[30:33]
	v_mfma_f32_16x16x32_bf16 v[26:29], v[160:163], v[220:223], v[26:29]
	s_waitcnt lgkmcnt(0)
	v_mfma_f32_16x16x32_bf16 v[14:17], v[146:149], v[228:231], v[14:17]
	v_mfma_f32_16x16x32_bf16 v[10:13], v[160:163], v[228:231], v[10:13]
	s_barrier
	s_add_u32 s26, s80, 0x20000
	s_addc_u32 s27, s81, 0
	s_add_i32 s2, s17, s3
	v_lshl_add_u64 v[142:143], s[26:27], 0, v[134:135]
	s_mov_b32 m0, s2
	s_nop 0
	global_load_lds_dwordx4 v[142:143], off
	v_lshl_add_u64 v[142:143], s[26:27], 0, v[130:131]
	s_add_i32 m0, s2, 0x2000
	s_nop 0
	global_load_lds_dwordx4 v[142:143], off
	s_waitcnt vmcnt(6)
	s_barrier
	v_mfma_f32_16x16x32_bf16 v[54:57], v[232:235], v[188:191], v[54:57]
	v_mfma_f32_16x16x32_bf16 v[50:53], v[240:243], v[188:191], v[50:53]
	v_mfma_f32_16x16x32_bf16 v[38:41], v[232:235], v[196:199], v[38:41]
	v_mfma_f32_16x16x32_bf16 v[34:37], v[240:243], v[196:199], v[34:37]
	v_mfma_f32_16x16x32_bf16 v[22:25], v[232:235], v[216:219], v[22:25]
	v_mfma_f32_16x16x32_bf16 v[18:21], v[240:243], v[216:219], v[18:21]
	v_mfma_f32_16x16x32_bf16 v[6:9], v[232:235], v[224:227], v[6:9]
	v_mfma_f32_16x16x32_bf16 v[2:5], v[240:243], v[224:227], v[2:5]
	v_mfma_f32_16x16x32_bf16 v[54:57], v[236:239], v[192:195], v[54:57]
	v_mfma_f32_16x16x32_bf16 v[50:53], v[244:247], v[192:195], v[50:53]
	v_mfma_f32_16x16x32_bf16 v[38:41], v[236:239], v[200:203], v[38:41]
	v_mfma_f32_16x16x32_bf16 v[34:37], v[244:247], v[200:203], v[34:37]
	v_mfma_f32_16x16x32_bf16 v[22:25], v[236:239], v[220:223], v[22:25]
	v_mfma_f32_16x16x32_bf16 v[18:21], v[244:247], v[220:223], v[18:21]
	v_mfma_f32_16x16x32_bf16 v[6:9], v[236:239], v[228:231], v[6:9]
	v_mfma_f32_16x16x32_bf16 v[2:5], v[244:247], v[228:231], v[2:5]
	s_add_i32 s2, 0, 0x18000
	v_add_u32_e32 v0, s2, v153
	s_barrier
	ds_read_b128 v[142:145], v0
	ds_read_b128 v[146:149], v0 offset:1024
	ds_read_b128 v[156:159], v0 offset:2048
	ds_read_b128 v[160:163], v0 offset:3072
	s_add_u32 s26, s82, 0xd0000
	s_addc_u32 s27, s83, 0
	s_mov_b32 m0, s92
	v_lshl_add_u64 v[232:233], s[26:27], 0, v[136:137]
	ds_read_b128 v[188:191], v155 offset:32768
	ds_read_b128 v[192:195], v155 offset:33792
	ds_read_b128 v[196:199], v155 offset:34816
	ds_read_b128 v[200:203], v155 offset:35840
	ds_read_b128 v[216:219], v155 offset:36864
	ds_read_b128 v[220:223], v155 offset:37888
	ds_read_b128 v[224:227], v155 offset:38912
	ds_read_b128 v[228:231], v155 offset:39936
	global_load_lds_dwordx4 v[232:233], off
	v_lshl_add_u64 v[232:233], s[26:27], 0, v[132:133]
	s_mov_b32 m0, s93
	s_nop 0
	global_load_lds_dwordx4 v[232:233], off
	s_waitcnt lgkmcnt(8)
	s_barrier
	s_waitcnt lgkmcnt(7)
	v_mfma_f32_16x16x32_bf16 v[126:129], v[142:145], v[188:191], v[126:129]
	v_mfma_f32_16x16x32_bf16 v[122:125], v[156:159], v[188:191], v[122:125]
	s_waitcnt lgkmcnt(5)
	v_mfma_f32_16x16x32_bf16 v[110:113], v[142:145], v[196:199], v[110:113]
	v_mfma_f32_16x16x32_bf16 v[106:109], v[156:159], v[196:199], v[106:109]
	s_waitcnt lgkmcnt(3)
	v_mfma_f32_16x16x32_bf16 v[94:97], v[142:145], v[216:219], v[94:97]
	v_mfma_f32_16x16x32_bf16 v[90:93], v[156:159], v[216:219], v[90:93]
	s_waitcnt lgkmcnt(1)
	v_mfma_f32_16x16x32_bf16 v[78:81], v[142:145], v[224:227], v[78:81]
	v_mfma_f32_16x16x32_bf16 v[74:77], v[156:159], v[224:227], v[74:77]
	v_mfma_f32_16x16x32_bf16 v[126:129], v[146:149], v[192:195], v[126:129]
	v_mfma_f32_16x16x32_bf16 v[122:125], v[160:163], v[192:195], v[122:125]
	v_mfma_f32_16x16x32_bf16 v[110:113], v[146:149], v[200:203], v[110:113]
	v_mfma_f32_16x16x32_bf16 v[106:109], v[160:163], v[200:203], v[106:109]
	v_mfma_f32_16x16x32_bf16 v[94:97], v[146:149], v[220:223], v[94:97]
	v_mfma_f32_16x16x32_bf16 v[90:93], v[160:163], v[220:223], v[90:93]
	s_waitcnt lgkmcnt(0)
	v_mfma_f32_16x16x32_bf16 v[78:81], v[146:149], v[228:231], v[78:81]
	v_mfma_f32_16x16x32_bf16 v[74:77], v[160:163], v[228:231], v[74:77]
	s_barrier
	s_add_i32 s17, 0, 0x1c000
	s_add_i32 s2, s2, s3
	v_add_u32_e32 v0, s17, v153
	v_lshl_add_u64 v[150:151], v[150:151], 0, s[28:29]
	s_mov_b32 m0, s2
	ds_read_b128 v[232:235], v0
	ds_read_b128 v[236:239], v0 offset:1024
	ds_read_b128 v[240:243], v0 offset:2048
	ds_read_b128 v[244:247], v0 offset:3072
	global_load_lds_dwordx4 v[150:151], off
	v_lshl_add_u64 v[150:151], v[164:165], 0, s[28:29]
	s_add_i32 m0, s2, 0x2000
	s_nop 0
	global_load_lds_dwordx4 v[150:151], off
	s_barrier
	s_waitcnt lgkmcnt(3)
	v_mfma_f32_16x16x32_bf16 v[118:121], v[232:235], v[188:191], v[118:121]
	s_waitcnt lgkmcnt(1)
	v_mfma_f32_16x16x32_bf16 v[114:117], v[240:243], v[188:191], v[114:117]
	v_mfma_f32_16x16x32_bf16 v[102:105], v[232:235], v[196:199], v[102:105]
	v_mfma_f32_16x16x32_bf16 v[98:101], v[240:243], v[196:199], v[98:101]
	v_mfma_f32_16x16x32_bf16 v[86:89], v[232:235], v[216:219], v[86:89]
	v_mfma_f32_16x16x32_bf16 v[82:85], v[240:243], v[216:219], v[82:85]
	v_mfma_f32_16x16x32_bf16 v[70:73], v[232:235], v[224:227], v[70:73]
	v_mfma_f32_16x16x32_bf16 v[66:69], v[240:243], v[224:227], v[66:69]
	v_mfma_f32_16x16x32_bf16 v[118:121], v[236:239], v[192:195], v[118:121]
	s_waitcnt lgkmcnt(0)
	v_mfma_f32_16x16x32_bf16 v[114:117], v[244:247], v[192:195], v[114:117]
	v_mfma_f32_16x16x32_bf16 v[102:105], v[236:239], v[200:203], v[102:105]
	v_mfma_f32_16x16x32_bf16 v[98:101], v[244:247], v[200:203], v[98:101]
	v_mfma_f32_16x16x32_bf16 v[86:89], v[236:239], v[220:223], v[86:89]
	v_mfma_f32_16x16x32_bf16 v[82:85], v[244:247], v[220:223], v[82:85]
	v_mfma_f32_16x16x32_bf16 v[70:73], v[236:239], v[228:231], v[70:73]
	v_mfma_f32_16x16x32_bf16 v[66:69], v[244:247], v[228:231], v[66:69]
	s_mov_b32 m0, s72
	v_lshl_add_u64 v[150:151], v[204:205], 0, s[28:29]
	s_barrier
	ds_read_b128 v[188:191], v155 offset:49152
	ds_read_b128 v[192:195], v155 offset:50176
	ds_read_b128 v[196:199], v155 offset:51200
	ds_read_b128 v[200:203], v155 offset:52224
	ds_read_b128 v[216:219], v155 offset:53248
	ds_read_b128 v[220:223], v155 offset:54272
	ds_read_b128 v[224:227], v155 offset:55296
	ds_read_b128 v[228:231], v155 offset:56320
	global_load_lds_dwordx4 v[150:151], off
	v_lshl_add_u64 v[150:151], v[248:249], 0, s[28:29]
	s_mov_b32 m0, s73
	s_nop 0
	global_load_lds_dwordx4 v[150:151], off
	s_barrier
	s_waitcnt lgkmcnt(7)
	v_mfma_f32_16x16x32_bf16 v[62:65], v[142:145], v[188:191], v[62:65]
	v_mfma_f32_16x16x32_bf16 v[58:61], v[156:159], v[188:191], v[58:61]
	s_waitcnt lgkmcnt(5)
	v_mfma_f32_16x16x32_bf16 v[46:49], v[142:145], v[196:199], v[46:49]
	v_mfma_f32_16x16x32_bf16 v[42:45], v[156:159], v[196:199], v[42:45]
	s_waitcnt lgkmcnt(3)
	v_mfma_f32_16x16x32_bf16 v[30:33], v[142:145], v[216:219], v[30:33]
	v_mfma_f32_16x16x32_bf16 v[26:29], v[156:159], v[216:219], v[26:29]
	s_waitcnt lgkmcnt(1)
	v_mfma_f32_16x16x32_bf16 v[14:17], v[142:145], v[224:227], v[14:17]
	v_mfma_f32_16x16x32_bf16 v[10:13], v[156:159], v[224:227], v[10:13]
	v_mfma_f32_16x16x32_bf16 v[62:65], v[146:149], v[192:195], v[62:65]
	v_mfma_f32_16x16x32_bf16 v[58:61], v[160:163], v[192:195], v[58:61]
	v_mfma_f32_16x16x32_bf16 v[46:49], v[146:149], v[200:203], v[46:49]
	v_mfma_f32_16x16x32_bf16 v[42:45], v[160:163], v[200:203], v[42:45]
	v_mfma_f32_16x16x32_bf16 v[30:33], v[146:149], v[220:223], v[30:33]
	v_mfma_f32_16x16x32_bf16 v[26:29], v[160:163], v[220:223], v[26:29]
	s_waitcnt lgkmcnt(0)
	v_mfma_f32_16x16x32_bf16 v[14:17], v[146:149], v[228:231], v[14:17]
	v_mfma_f32_16x16x32_bf16 v[10:13], v[160:163], v[228:231], v[10:13]
	s_barrier
	s_add_u32 s26, s80, 0x20080
	s_addc_u32 s27, s81, 0
	s_add_i32 s2, s17, s3
	v_lshl_add_u64 v[142:143], s[26:27], 0, v[134:135]
	s_mov_b32 m0, s2
	s_nop 0
	global_load_lds_dwordx4 v[142:143], off
	v_lshl_add_u64 v[142:143], s[26:27], 0, v[130:131]
	s_add_i32 m0, s2, 0x2000
	s_nop 0
	global_load_lds_dwordx4 v[142:143], off
	s_waitcnt vmcnt(6)
	s_barrier
	v_mfma_f32_16x16x32_bf16 v[54:57], v[232:235], v[188:191], v[54:57]
	v_mfma_f32_16x16x32_bf16 v[50:53], v[240:243], v[188:191], v[50:53]
	v_mfma_f32_16x16x32_bf16 v[38:41], v[232:235], v[196:199], v[38:41]
	v_mfma_f32_16x16x32_bf16 v[34:37], v[240:243], v[196:199], v[34:37]
	v_mfma_f32_16x16x32_bf16 v[22:25], v[232:235], v[216:219], v[22:25]
	v_mfma_f32_16x16x32_bf16 v[18:21], v[240:243], v[216:219], v[18:21]
	v_mfma_f32_16x16x32_bf16 v[6:9], v[232:235], v[224:227], v[6:9]
	v_mfma_f32_16x16x32_bf16 v[2:5], v[240:243], v[224:227], v[2:5]
	v_mfma_f32_16x16x32_bf16 v[54:57], v[236:239], v[192:195], v[54:57]
	v_mfma_f32_16x16x32_bf16 v[50:53], v[244:247], v[192:195], v[50:53]
	v_mfma_f32_16x16x32_bf16 v[38:41], v[236:239], v[200:203], v[38:41]
	v_mfma_f32_16x16x32_bf16 v[34:37], v[244:247], v[200:203], v[34:37]
	v_mfma_f32_16x16x32_bf16 v[22:25], v[236:239], v[220:223], v[22:25]
	v_mfma_f32_16x16x32_bf16 v[18:21], v[244:247], v[220:223], v[18:21]
	v_mfma_f32_16x16x32_bf16 v[6:9], v[236:239], v[228:231], v[6:9]
	v_mfma_f32_16x16x32_bf16 v[2:5], v[244:247], v[228:231], v[2:5]
	s_add_i32 s44, s44, 2
	s_add_u32 s25, s25, 0x100
	s_addc_u32 s46, s46, 0
	s_cmp_gt_u32 s44, 5
	s_mov_b64 s[78:79], s[6:7]
	s_barrier
	s_cbranch_scc0 .LBB0_433
	v_lshl_add_u32 v144, s41, 8, v152
	v_ashrrev_i32_e32 v145, 31, v144
	v_lshl_add_u64 v[146:147], v[144:145], 2, s[50:51]
	global_load_dword v216, v[146:147], off
	global_load_dword v217, v[146:147], off offset:64
	global_load_dword v218, v[146:147], off offset:128
	global_load_dword v219, v[146:147], off offset:192
	global_load_dword v220, v[146:147], off offset:512
	global_load_dword v221, v[146:147], off offset:576
	global_load_dword v222, v[146:147], off offset:640
	global_load_dword v223, v[146:147], off offset:704
	v_lshl_or_b32 v142, s40, 8, v154
	s_mov_b32 s2, 0x2aaaaaab
	v_mul_hi_i32 v143, v142, s2
	v_lshlrev_b64 v[148:149], 8, v[144:145]
	v_lshrrev_b32_e32 v145, 31, v143
	v_lshrrev_b32_e32 v143, 5, v143
	v_add_u32_e32 v143, v143, v145
	s_movk_i32 s2, 0xc0
	v_mul_lo_u32 v143, v143, s2
	v_sub_u32_e32 v143, v142, v143
	s_movk_i32 s2, 0x7f
	v_cmp_lt_i32_e32 vcc, s2, v143
	v_add_u32_e32 v143, 0xffffff80, v143
	v_lshl_add_u64 v[148:149], s[20:21], 0, v[148:149]
	s_waitcnt vmcnt(0)
	v_mov_b32_e32 v0, v216
	v_mul_f32_e32 v150, 0x3dd53b94, v0
	v_pk_mul_f32 v[128:129], v[128:129], v[150:151] op_sel_hi:[1,0]
	v_pk_mul_f32 v[126:127], v[126:127], v[150:151] op_sel_hi:[1,0]
	v_pk_mul_f32 v[124:125], v[124:125], v[150:151] op_sel_hi:[1,0]
	v_pk_mul_f32 v[122:123], v[122:123], v[150:151] op_sel_hi:[1,0]
	v_lshrrev_b32_e32 v0, 1, v143
	s_and_saveexec_b64 s[6:7], vcc
	s_cbranch_execz .LBB0_436
	v_lshl_add_u64 v[160:161], v[0:1], 3, v[148:149]
	global_load_dwordx4 v[156:159], v[160:161], off offset:16
	s_nop 0
	global_load_dwordx4 v[160:163], v[160:161], off
	s_waitcnt vmcnt(0)
	v_pk_mul_f32 v[190:191], v[122:123], v[156:157] op_sel:[1,1] op_sel_hi:[0,1]
	v_pk_mul_f32 v[188:189], v[126:127], v[160:161] op_sel:[1,1] op_sel_hi:[0,1]
	v_pk_mul_f32 v[164:165], v[126:127], v[160:161]
	v_pk_fma_f32 v[126:127], v[126:127], v[160:161], v[188:189] op_sel_hi:[1,0,1]
	s_nop 0
	v_mul_f32_e32 v126, v129, v163
	v_pk_fma_f32 v[160:161], v[128:129], v[162:163], v[126:127] op_sel_hi:[1,1,0] neg_lo:[0,0,1] neg_hi:[0,0,1]
	v_mul_f32_e32 v126, v128, v163
	v_pk_fma_f32 v[162:163], v[128:129], v[162:163], v[126:127] op_sel:[1,0,0] op_sel_hi:[0,1,0]
	v_pk_mul_f32 v[128:129], v[122:123], v[156:157]
	v_pk_fma_f32 v[122:123], v[122:123], v[156:157], v[190:191] op_sel_hi:[1,0,1]
	v_sub_f32_e32 v126, v164, v188
	v_mul_f32_e32 v122, v125, v159
	v_pk_fma_f32 v[156:157], v[124:125], v[158:159], v[122:123] op_sel_hi:[1,1,0] neg_lo:[0,0,1] neg_hi:[0,0,1]
	v_mul_f32_e32 v122, v124, v159
	v_pk_fma_f32 v[158:159], v[124:125], v[158:159], v[122:123] op_sel:[1,0,0] op_sel_hi:[0,1,0]
	v_sub_f32_e32 v122, v128, v190
	v_mov_b32_e32 v128, v160
	v_mov_b32_e32 v129, v162
	v_mov_b32_e32 v124, v156
	v_mov_b32_e32 v125, v158

.LBB0_482:
	s_add_u32 s10, s80, 0x100
	s_addc_u32 s11, s81, 0
	s_add_i32 s2, 0, 0x10000
	v_add_u32_e32 v156, s2, v145
	ds_read_b128 v[140:143], v156
	ds_read_b128 v[148:151], v156 offset:1024
	ds_read_b128 v[152:155], v156 offset:2048
	ds_read_b128 v[156:159], v156 offset:3072
	s_cmp_eq_u32 s44, 4
	s_cselect_b32 s93, s77, s11
	s_cselect_b32 s92, s76, s10
	s_cselect_b32 s83, s24, s47
	s_cselect_b32 s82, s25, s46
	v_lshl_add_u64 v[164:165], s[80:81], 0, v[136:137]
	s_add_i32 m0, s58, 0xc000
	ds_read_b128 v[160:163], v147
	ds_read_b128 v[188:191], v147 offset:1024
	ds_read_b128 v[192:195], v147 offset:2048
	ds_read_b128 v[196:199], v147 offset:3072
	ds_read_b128 v[200:203], v147 offset:4096
	ds_read_b128 v[216:219], v147 offset:5120
	ds_read_b128 v[220:223], v147 offset:6144
	ds_read_b128 v[224:227], v147 offset:7168
	global_load_lds_dwordx4 v[164:165], off
	v_lshl_add_u64 v[164:165], s[80:81], 0, v[138:139]
	s_add_i32 m0, s58, 0xe000
	s_nop 0
	global_load_lds_dwordx4 v[164:165], off
	s_waitcnt lgkmcnt(8)
	s_barrier
	s_waitcnt lgkmcnt(7)
	v_mfma_f32_16x16x32_bf16 v[126:129], v[140:143], v[160:163], v[126:129]
	v_mfma_f32_16x16x32_bf16 v[122:125], v[152:155], v[160:163], v[122:125]
	s_waitcnt lgkmcnt(5)
	v_mfma_f32_16x16x32_bf16 v[110:113], v[140:143], v[192:195], v[110:113]
	v_mfma_f32_16x16x32_bf16 v[106:109], v[152:155], v[192:195], v[106:109]
	s_waitcnt lgkmcnt(3)
	v_mfma_f32_16x16x32_bf16 v[94:97], v[140:143], v[200:203], v[94:97]
	v_mfma_f32_16x16x32_bf16 v[90:93], v[152:155], v[200:203], v[90:93]
	s_waitcnt lgkmcnt(1)
	v_mfma_f32_16x16x32_bf16 v[78:81], v[140:143], v[220:223], v[78:81]
	v_mfma_f32_16x16x32_bf16 v[74:77], v[152:155], v[220:223], v[74:77]
	v_mfma_f32_16x16x32_bf16 v[126:129], v[148:151], v[188:191], v[126:129]
	v_mfma_f32_16x16x32_bf16 v[122:125], v[156:159], v[188:191], v[122:125]
	v_mfma_f32_16x16x32_bf16 v[110:113], v[148:151], v[196:199], v[110:113]
	v_mfma_f32_16x16x32_bf16 v[106:109], v[156:159], v[196:199], v[106:109]
	v_mfma_f32_16x16x32_bf16 v[94:97], v[148:151], v[216:219], v[94:97]
	v_mfma_f32_16x16x32_bf16 v[90:93], v[156:159], v[216:219], v[90:93]
	s_waitcnt lgkmcnt(0)
	v_mfma_f32_16x16x32_bf16 v[78:81], v[148:151], v[224:227], v[78:81]
	v_mfma_f32_16x16x32_bf16 v[74:77], v[156:159], v[224:227], v[74:77]
	s_barrier
	s_add_i32 s17, 0, 0x14000
	v_add_u32_e32 v164, s17, v145
	s_add_i32 s2, s2, s3
	ds_read_b128 v[228:231], v164
	ds_read_b128 v[232:235], v164 offset:1024
	ds_read_b128 v[236:239], v164 offset:2048
	ds_read_b128 v[240:243], v164 offset:3072
	v_lshl_add_u64 v[164:165], s[82:83], 0, v[0:1]
	s_mov_b32 m0, s2
	v_lshl_add_u64 v[204:205], s[82:83], 0, v[130:131]
	global_load_lds_dwordx4 v[164:165], off
	s_add_i32 m0, s2, 0x2000
	s_nop 0
	global_load_lds_dwordx4 v[204:205], off
	s_barrier
	s_waitcnt lgkmcnt(3)
	v_mfma_f32_16x16x32_bf16 v[118:121], v[228:231], v[160:163], v[118:121]
	s_waitcnt lgkmcnt(1)
	v_mfma_f32_16x16x32_bf16 v[114:117], v[236:239], v[160:163], v[114:117]
	v_mfma_f32_16x16x32_bf16 v[102:105], v[228:231], v[192:195], v[102:105]
	v_mfma_f32_16x16x32_bf16 v[98:101], v[236:239], v[192:195], v[98:101]
	v_mfma_f32_16x16x32_bf16 v[86:89], v[228:231], v[200:203], v[86:89]
	v_mfma_f32_16x16x32_bf16 v[82:85], v[236:239], v[200:203], v[82:85]
	v_mfma_f32_16x16x32_bf16 v[70:73], v[228:231], v[220:223], v[70:73]
	v_mfma_f32_16x16x32_bf16 v[66:69], v[236:239], v[220:223], v[66:69]
	v_mfma_f32_16x16x32_bf16 v[118:121], v[232:235], v[188:191], v[118:121]
	s_waitcnt lgkmcnt(0)
	v_mfma_f32_16x16x32_bf16 v[114:117], v[240:243], v[188:191], v[114:117]
	v_mfma_f32_16x16x32_bf16 v[102:105], v[232:235], v[196:199], v[102:105]
	v_mfma_f32_16x16x32_bf16 v[98:101], v[240:243], v[196:199], v[98:101]
	v_mfma_f32_16x16x32_bf16 v[86:89], v[232:235], v[216:219], v[86:89]
	v_mfma_f32_16x16x32_bf16 v[82:85], v[240:243], v[216:219], v[82:85]
	v_mfma_f32_16x16x32_bf16 v[70:73], v[232:235], v[224:227], v[70:73]
	v_mfma_f32_16x16x32_bf16 v[66:69], v[240:243], v[224:227], v[66:69]
	s_mov_b32 m0, s58
	v_lshl_add_u64 v[244:245], s[92:93], 0, v[134:135]
	s_barrier
	ds_read_b128 v[160:163], v147 offset:16384
	ds_read_b128 v[188:191], v147 offset:17408
	ds_read_b128 v[192:195], v147 offset:18432
	ds_read_b128 v[196:199], v147 offset:19456
	ds_read_b128 v[200:203], v147 offset:20480
	ds_read_b128 v[216:219], v147 offset:21504
	ds_read_b128 v[220:223], v147 offset:22528
	ds_read_b128 v[224:227], v147 offset:23552
	global_load_lds_dwordx4 v[244:245], off
	v_lshl_add_u64 v[246:247], s[92:93], 0, v[132:133]
	s_mov_b32 m0, s69
	s_nop 0
	global_load_lds_dwordx4 v[246:247], off
	s_barrier
	s_waitcnt lgkmcnt(7)
	v_mfma_f32_16x16x32_bf16 v[62:65], v[140:143], v[160:163], v[62:65]
	v_mfma_f32_16x16x32_bf16 v[58:61], v[152:155], v[160:163], v[58:61]
	s_waitcnt lgkmcnt(5)
	v_mfma_f32_16x16x32_bf16 v[46:49], v[140:143], v[192:195], v[46:49]
	v_mfma_f32_16x16x32_bf16 v[42:45], v[152:155], v[192:195], v[42:45]
	s_waitcnt lgkmcnt(3)
	v_mfma_f32_16x16x32_bf16 v[30:33], v[140:143], v[200:203], v[30:33]
	v_mfma_f32_16x16x32_bf16 v[26:29], v[152:155], v[200:203], v[26:29]
	s_waitcnt lgkmcnt(1)
	v_mfma_f32_16x16x32_bf16 v[14:17], v[140:143], v[220:223], v[14:17]
	v_mfma_f32_16x16x32_bf16 v[10:13], v[152:155], v[220:223], v[10:13]
	v_mfma_f32_16x16x32_bf16 v[62:65], v[148:151], v[188:191], v[62:65]
	v_mfma_f32_16x16x32_bf16 v[58:61], v[156:159], v[188:191], v[58:61]
	v_mfma_f32_16x16x32_bf16 v[46:49], v[148:151], v[196:199], v[46:49]
	v_mfma_f32_16x16x32_bf16 v[42:45], v[156:159], v[196:199], v[42:45]
	v_mfma_f32_16x16x32_bf16 v[30:33], v[148:151], v[216:219], v[30:33]
	v_mfma_f32_16x16x32_bf16 v[26:29], v[156:159], v[216:219], v[26:29]
	s_waitcnt lgkmcnt(0)
	v_mfma_f32_16x16x32_bf16 v[14:17], v[148:151], v[224:227], v[14:17]
	v_mfma_f32_16x16x32_bf16 v[10:13], v[156:159], v[224:227], v[10:13]
	s_barrier
	s_add_u32 s26, s82, 0x20000
	s_addc_u32 s27, s83, 0
	s_add_i32 s2, s17, s3
	v_lshl_add_u64 v[140:141], s[26:27], 0, v[0:1]
	s_mov_b32 m0, s2
	s_nop 0
	global_load_lds_dwordx4 v[140:141], off
	v_lshl_add_u64 v[140:141], s[26:27], 0, v[130:131]
	s_add_i32 m0, s2, 0x2000
	s_nop 0
	global_load_lds_dwordx4 v[140:141], off
	s_waitcnt vmcnt(6)
	s_barrier
	v_mfma_f32_16x16x32_bf16 v[54:57], v[228:231], v[160:163], v[54:57]
	v_mfma_f32_16x16x32_bf16 v[50:53], v[236:239], v[160:163], v[50:53]
	v_mfma_f32_16x16x32_bf16 v[38:41], v[228:231], v[192:195], v[38:41]
	v_mfma_f32_16x16x32_bf16 v[34:37], v[236:239], v[192:195], v[34:37]
	v_mfma_f32_16x16x32_bf16 v[22:25], v[228:231], v[200:203], v[22:25]
	v_mfma_f32_16x16x32_bf16 v[18:21], v[236:239], v[200:203], v[18:21]
	v_mfma_f32_16x16x32_bf16 v[6:9], v[228:231], v[220:223], v[6:9]
	v_mfma_f32_16x16x32_bf16 v[2:5], v[236:239], v[220:223], v[2:5]
	v_mfma_f32_16x16x32_bf16 v[54:57], v[232:235], v[188:191], v[54:57]
	v_mfma_f32_16x16x32_bf16 v[50:53], v[240:243], v[188:191], v[50:53]
	v_mfma_f32_16x16x32_bf16 v[38:41], v[232:235], v[196:199], v[38:41]
	v_mfma_f32_16x16x32_bf16 v[34:37], v[240:243], v[196:199], v[34:37]
	v_mfma_f32_16x16x32_bf16 v[22:25], v[232:235], v[216:219], v[22:25]
	v_mfma_f32_16x16x32_bf16 v[18:21], v[240:243], v[216:219], v[18:21]
	v_mfma_f32_16x16x32_bf16 v[6:9], v[232:235], v[224:227], v[6:9]
	v_mfma_f32_16x16x32_bf16 v[2:5], v[240:243], v[224:227], v[2:5]
	s_add_i32 s2, 0, 0x18000
	v_add_u32_e32 v156, s2, v145
	s_barrier
	ds_read_b128 v[140:143], v156
	ds_read_b128 v[148:151], v156 offset:1024
	ds_read_b128 v[152:155], v156 offset:2048
	ds_read_b128 v[156:159], v156 offset:3072
	s_add_u32 s26, s92, 0xd0000
	s_addc_u32 s27, s93, 0
	s_mov_b32 m0, s70
	v_lshl_add_u64 v[228:229], s[26:27], 0, v[134:135]
	ds_read_b128 v[160:163], v147 offset:32768
	ds_read_b128 v[188:191], v147 offset:33792
	ds_read_b128 v[192:195], v147 offset:34816
	ds_read_b128 v[196:199], v147 offset:35840
	ds_read_b128 v[200:203], v147 offset:36864
	ds_read_b128 v[216:219], v147 offset:37888
	ds_read_b128 v[220:223], v147 offset:38912
	ds_read_b128 v[224:227], v147 offset:39936
	global_load_lds_dwordx4 v[228:229], off
	v_lshl_add_u64 v[228:229], s[26:27], 0, v[132:133]
	s_mov_b32 m0, s71
	s_nop 0
	global_load_lds_dwordx4 v[228:229], off
	s_waitcnt lgkmcnt(8)
	s_barrier
	s_waitcnt lgkmcnt(7)
	v_mfma_f32_16x16x32_bf16 v[126:129], v[140:143], v[160:163], v[126:129]
	v_mfma_f32_16x16x32_bf16 v[122:125], v[152:155], v[160:163], v[122:125]
	s_waitcnt lgkmcnt(5)
	v_mfma_f32_16x16x32_bf16 v[110:113], v[140:143], v[192:195], v[110:113]
	v_mfma_f32_16x16x32_bf16 v[106:109], v[152:155], v[192:195], v[106:109]
	s_waitcnt lgkmcnt(3)
	v_mfma_f32_16x16x32_bf16 v[94:97], v[140:143], v[200:203], v[94:97]
	v_mfma_f32_16x16x32_bf16 v[90:93], v[152:155], v[200:203], v[90:93]
	s_waitcnt lgkmcnt(1)
	v_mfma_f32_16x16x32_bf16 v[78:81], v[140:143], v[220:223], v[78:81]
	v_mfma_f32_16x16x32_bf16 v[74:77], v[152:155], v[220:223], v[74:77]
	v_mfma_f32_16x16x32_bf16 v[126:129], v[148:151], v[188:191], v[126:129]
	v_mfma_f32_16x16x32_bf16 v[122:125], v[156:159], v[188:191], v[122:125]
	v_mfma_f32_16x16x32_bf16 v[110:113], v[148:151], v[196:199], v[110:113]
	v_mfma_f32_16x16x32_bf16 v[106:109], v[156:159], v[196:199], v[106:109]
	v_mfma_f32_16x16x32_bf16 v[94:97], v[148:151], v[216:219], v[94:97]
	v_mfma_f32_16x16x32_bf16 v[90:93], v[156:159], v[216:219], v[90:93]
	s_waitcnt lgkmcnt(0)
	v_mfma_f32_16x16x32_bf16 v[78:81], v[148:151], v[224:227], v[78:81]
	v_mfma_f32_16x16x32_bf16 v[74:77], v[156:159], v[224:227], v[74:77]
	s_barrier
	s_add_i32 s17, 0, 0x1c000
	s_add_i32 s2, s2, s3
	v_add_u32_e32 v206, s17, v145
	v_lshl_add_u64 v[164:165], v[164:165], 0, s[28:29]
	s_mov_b32 m0, s2
	ds_read_b128 v[228:231], v206
	ds_read_b128 v[232:235], v206 offset:1024
	ds_read_b128 v[236:239], v206 offset:2048
	ds_read_b128 v[240:243], v206 offset:3072
	global_load_lds_dwordx4 v[164:165], off
	v_lshl_add_u64 v[164:165], v[204:205], 0, s[28:29]
	s_add_i32 m0, s2, 0x2000
	s_nop 0
	global_load_lds_dwordx4 v[164:165], off
	s_barrier
	s_waitcnt lgkmcnt(3)
	v_mfma_f32_16x16x32_bf16 v[118:121], v[228:231], v[160:163], v[118:121]
	s_waitcnt lgkmcnt(1)
	v_mfma_f32_16x16x32_bf16 v[114:117], v[236:239], v[160:163], v[114:117]
	v_mfma_f32_16x16x32_bf16 v[102:105], v[228:231], v[192:195], v[102:105]
	v_mfma_f32_16x16x32_bf16 v[98:101], v[236:239], v[192:195], v[98:101]
	v_mfma_f32_16x16x32_bf16 v[86:89], v[228:231], v[200:203], v[86:89]
	v_mfma_f32_16x16x32_bf16 v[82:85], v[236:239], v[200:203], v[82:85]
	v_mfma_f32_16x16x32_bf16 v[70:73], v[228:231], v[220:223], v[70:73]
	v_mfma_f32_16x16x32_bf16 v[66:69], v[236:239], v[220:223], v[66:69]
	v_mfma_f32_16x16x32_bf16 v[118:121], v[232:235], v[188:191], v[118:121]
	s_waitcnt lgkmcnt(0)
	v_mfma_f32_16x16x32_bf16 v[114:117], v[240:243], v[188:191], v[114:117]
	v_mfma_f32_16x16x32_bf16 v[102:105], v[232:235], v[196:199], v[102:105]
	v_mfma_f32_16x16x32_bf16 v[98:101], v[240:243], v[196:199], v[98:101]
	v_mfma_f32_16x16x32_bf16 v[86:89], v[232:235], v[216:219], v[86:89]
	v_mfma_f32_16x16x32_bf16 v[82:85], v[240:243], v[216:219], v[82:85]
	v_mfma_f32_16x16x32_bf16 v[70:73], v[232:235], v[224:227], v[70:73]
	v_mfma_f32_16x16x32_bf16 v[66:69], v[240:243], v[224:227], v[66:69]
	s_mov_b32 m0, s72
	v_lshl_add_u64 v[164:165], v[244:245], 0, s[28:29]
	s_barrier
	ds_read_b128 v[160:163], v147 offset:49152
	ds_read_b128 v[188:191], v147 offset:50176
	ds_read_b128 v[192:195], v147 offset:51200
	ds_read_b128 v[196:199], v147 offset:52224
	ds_read_b128 v[200:203], v147 offset:53248
	ds_read_b128 v[216:219], v147 offset:54272
	ds_read_b128 v[220:223], v147 offset:55296
	ds_read_b128 v[224:227], v147 offset:56320
	global_load_lds_dwordx4 v[164:165], off
	v_lshl_add_u64 v[164:165], v[246:247], 0, s[28:29]
	s_mov_b32 m0, s73
	s_nop 0
	global_load_lds_dwordx4 v[164:165], off
	s_barrier
	s_waitcnt lgkmcnt(7)
	v_mfma_f32_16x16x32_bf16 v[62:65], v[140:143], v[160:163], v[62:65]
	v_mfma_f32_16x16x32_bf16 v[58:61], v[152:155], v[160:163], v[58:61]
	s_waitcnt lgkmcnt(5)
	v_mfma_f32_16x16x32_bf16 v[46:49], v[140:143], v[192:195], v[46:49]
	v_mfma_f32_16x16x32_bf16 v[42:45], v[152:155], v[192:195], v[42:45]
	s_waitcnt lgkmcnt(3)
	v_mfma_f32_16x16x32_bf16 v[30:33], v[140:143], v[200:203], v[30:33]
	v_mfma_f32_16x16x32_bf16 v[26:29], v[152:155], v[200:203], v[26:29]
	s_waitcnt lgkmcnt(1)
	v_mfma_f32_16x16x32_bf16 v[14:17], v[140:143], v[220:223], v[14:17]
	v_mfma_f32_16x16x32_bf16 v[10:13], v[152:155], v[220:223], v[10:13]
	v_mfma_f32_16x16x32_bf16 v[62:65], v[148:151], v[188:191], v[62:65]
	v_mfma_f32_16x16x32_bf16 v[58:61], v[156:159], v[188:191], v[58:61]
	v_mfma_f32_16x16x32_bf16 v[46:49], v[148:151], v[196:199], v[46:49]
	v_mfma_f32_16x16x32_bf16 v[42:45], v[156:159], v[196:199], v[42:45]
	v_mfma_f32_16x16x32_bf16 v[30:33], v[148:151], v[216:219], v[30:33]
	v_mfma_f32_16x16x32_bf16 v[26:29], v[156:159], v[216:219], v[26:29]
	s_waitcnt lgkmcnt(0)
	v_mfma_f32_16x16x32_bf16 v[14:17], v[148:151], v[224:227], v[14:17]
	v_mfma_f32_16x16x32_bf16 v[10:13], v[156:159], v[224:227], v[10:13]
	s_barrier
	s_add_u32 s26, s82, 0x20080
	s_addc_u32 s27, s83, 0
	s_add_i32 s2, s17, s3
	v_lshl_add_u64 v[140:141], s[26:27], 0, v[0:1]
	s_mov_b32 m0, s2
	s_nop 0
	global_load_lds_dwordx4 v[140:141], off
	v_lshl_add_u64 v[140:141], s[26:27], 0, v[130:131]
	s_add_i32 m0, s2, 0x2000
	s_nop 0
	global_load_lds_dwordx4 v[140:141], off
	s_waitcnt vmcnt(6)
	s_barrier
	v_mfma_f32_16x16x32_bf16 v[54:57], v[228:231], v[160:163], v[54:57]
	v_mfma_f32_16x16x32_bf16 v[50:53], v[236:239], v[160:163], v[50:53]
	v_mfma_f32_16x16x32_bf16 v[38:41], v[228:231], v[192:195], v[38:41]
	v_mfma_f32_16x16x32_bf16 v[34:37], v[236:239], v[192:195], v[34:37]
	v_mfma_f32_16x16x32_bf16 v[22:25], v[228:231], v[200:203], v[22:25]
	v_mfma_f32_16x16x32_bf16 v[18:21], v[236:239], v[200:203], v[18:21]
	v_mfma_f32_16x16x32_bf16 v[6:9], v[228:231], v[220:223], v[6:9]
	v_mfma_f32_16x16x32_bf16 v[2:5], v[236:239], v[220:223], v[2:5]
	v_mfma_f32_16x16x32_bf16 v[54:57], v[232:235], v[188:191], v[54:57]
	v_mfma_f32_16x16x32_bf16 v[50:53], v[240:243], v[188:191], v[50:53]
	v_mfma_f32_16x16x32_bf16 v[38:41], v[232:235], v[196:199], v[38:41]
	v_mfma_f32_16x16x32_bf16 v[34:37], v[240:243], v[196:199], v[34:37]
	v_mfma_f32_16x16x32_bf16 v[22:25], v[232:235], v[216:219], v[22:25]
	v_mfma_f32_16x16x32_bf16 v[18:21], v[240:243], v[216:219], v[18:21]
	v_mfma_f32_16x16x32_bf16 v[6:9], v[232:235], v[224:227], v[6:9]
	v_mfma_f32_16x16x32_bf16 v[2:5], v[240:243], v[224:227], v[2:5]
	s_add_i32 s44, s44, 2
	s_add_u32 s46, s46, 0x100
	s_addc_u32 s47, s47, 0
	s_cmp_gt_u32 s44, 5
	s_mov_b64 s[80:81], s[10:11]
	s_barrier
	s_cbranch_scc0 .LBB0_482
	v_lshl_add_u32 v142, s63, 8, v144
	v_ashrrev_i32_e32 v143, 31, v142
	v_lshl_add_u64 v[140:141], v[142:143], 2, s[38:39]
	global_load_dword v216, v[140:141], off
	global_load_dword v218, v[140:141], off offset:64
	global_load_dword v220, v[140:141], off offset:128
	global_load_dword v222, v[140:141], off offset:192
	global_load_dword v224, v[140:141], off offset:512
	global_load_dword v226, v[140:141], off offset:576
	global_load_dword v228, v[140:141], off offset:640
	global_load_dword v230, v[140:141], off offset:704
	v_lshl_or_b32 v148, s62, 8, v146
	v_ashrrev_i32_e32 v149, 31, v148
	s_mov_b32 s2, 0x80000
	s_mov_b64 s[4:5], 0x80000
	s_mov_b32 s62, s74
	s_mov_b32 s63, s41
	s_mov_b64 s[82:83], s[78:79]
	s_mov_b64 s[80:81], s[76:77]
	v_readlane_b32 s93, v251, 60
	s_waitcnt vmcnt(7)
	v_mov_b32_e32 v150, v216
	v_pk_mul_f32 v[128:129], v[128:129], v[150:151] op_sel_hi:[1,0]
	v_pk_mul_f32 v[126:127], v[126:127], v[150:151] op_sel_hi:[1,0]
	v_pk_mul_f32 v[122:123], v[122:123], v[150:151] op_sel_hi:[1,0]
	v_pk_mul_f32 v[124:125], v[124:125], v[150:151] op_sel_hi:[1,0]
	v_cvt_pk_bf16_f32 v126, v126, v127
	v_cvt_pk_bf16_f32 v127, v128, v129
	v_cvt_pk_bf16_f32 v128, v122, v123
	v_lshlrev_b64 v[122:123], 12, v[142:143]
	v_cvt_pk_bf16_f32 v129, v124, v125
	v_lshl_add_u64 v[122:123], s[56:57], 0, v[122:123]
	v_lshlrev_b64 v[124:125], 1, v[148:149]
	v_lshl_add_u64 v[122:123], v[122:123], 0, v[124:125]
	global_store_dwordx4 v[122:123], v[126:129], off
	v_pk_mul_f32 v[120:121], v[120:121], v[150:151] op_sel_hi:[1,0]
	v_pk_mul_f32 v[118:119], v[118:119], v[150:151] op_sel_hi:[1,0]
	v_pk_mul_f32 v[126:127], v[116:117], v[150:151] op_sel_hi:[1,0]
	v_pk_mul_f32 v[116:117], v[114:115], v[150:151] op_sel_hi:[1,0]
	v_cvt_pk_bf16_f32 v114, v118, v119
	v_cvt_pk_bf16_f32 v115, v120, v121
	v_cvt_pk_bf16_f32 v116, v116, v117
	v_cvt_pk_bf16_f32 v117, v126, v127
	global_store_dwordx4 v[122:123], v[114:117], off offset:256
	s_nop 1
	v_or_b32_e32 v114, 16, v142
	v_ashrrev_i32_e32 v115, 31, v114
	v_lshl_add_u64 v[116:117], v[114:115], 2, s[38:39]
	s_waitcnt vmcnt(8)
	v_mov_b32_e32 v116, v218
	v_pk_mul_f32 v[110:111], v[110:111], v[116:117] op_sel_hi:[1,0]
	v_pk_mul_f32 v[118:119], v[108:109], v[116:117] op_sel_hi:[1,0]
	v_pk_mul_f32 v[108:109], v[106:107], v[116:117] op_sel_hi:[1,0]
	v_cvt_pk_bf16_f32 v106, v110, v111
	v_lshlrev_b64 v[110:111], 12, v[114:115]
	v_pk_mul_f32 v[112:113], v[112:113], v[116:117] op_sel_hi:[1,0]
	v_lshl_add_u64 v[110:111], s[56:57], 0, v[110:111]
	v_cvt_pk_bf16_f32 v107, v112, v113
	v_cvt_pk_bf16_f32 v108, v108, v109
	v_cvt_pk_bf16_f32 v109, v118, v119
	v_lshl_add_u64 v[110:111], v[110:111], 0, v[124:125]
	global_store_dwordx4 v[110:111], v[106:109], off
	v_pk_mul_f32 v[104:105], v[104:105], v[116:117] op_sel_hi:[1,0]
	v_pk_mul_f32 v[102:103], v[102:103], v[116:117] op_sel_hi:[1,0]
	v_pk_mul_f32 v[106:107], v[100:101], v[116:117] op_sel_hi:[1,0]
	v_pk_mul_f32 v[100:101], v[98:99], v[116:117] op_sel_hi:[1,0]
	v_cvt_pk_bf16_f32 v98, v102, v103
	v_cvt_pk_bf16_f32 v99, v104, v105
	v_cvt_pk_bf16_f32 v100, v100, v101
	v_cvt_pk_bf16_f32 v101, v106, v107
	global_store_dwordx4 v[110:111], v[98:101], off offset:256
	s_nop 1
	v_or_b32_e32 v98, 32, v142
	v_ashrrev_i32_e32 v99, 31, v98
	v_lshl_add_u64 v[100:101], v[98:99], 2, s[38:39]
	s_waitcnt vmcnt(9)
	v_mov_b32_e32 v100, v220
	v_pk_mul_f32 v[94:95], v[94:95], v[100:101] op_sel_hi:[1,0]
	v_pk_mul_f32 v[102:103], v[92:93], v[100:101] op_sel_hi:[1,0]
	v_pk_mul_f32 v[92:93], v[90:91], v[100:101] op_sel_hi:[1,0]
	v_cvt_pk_bf16_f32 v90, v94, v95
	v_lshlrev_b64 v[94:95], 12, v[98:99]
	v_pk_mul_f32 v[96:97], v[96:97], v[100:101] op_sel_hi:[1,0]
	v_lshl_add_u64 v[94:95], s[56:57], 0, v[94:95]
	v_cvt_pk_bf16_f32 v91, v96, v97
	v_cvt_pk_bf16_f32 v92, v92, v93
	v_cvt_pk_bf16_f32 v93, v102, v103
	v_lshl_add_u64 v[94:95], v[94:95], 0, v[124:125]
	global_store_dwordx4 v[94:95], v[90:93], off
	v_pk_mul_f32 v[88:89], v[88:89], v[100:101] op_sel_hi:[1,0]
	v_pk_mul_f32 v[86:87], v[86:87], v[100:101] op_sel_hi:[1,0]
	v_pk_mul_f32 v[90:91], v[84:85], v[100:101] op_sel_hi:[1,0]
	v_pk_mul_f32 v[84:85], v[82:83], v[100:101] op_sel_hi:[1,0]
	v_cvt_pk_bf16_f32 v82, v86, v87
	v_cvt_pk_bf16_f32 v83, v88, v89
	v_cvt_pk_bf16_f32 v84, v84, v85
	v_cvt_pk_bf16_f32 v85, v90, v91
	global_store_dwordx4 v[94:95], v[82:85], off offset:256
	s_nop 1
	v_or_b32_e32 v82, 48, v142
	v_ashrrev_i32_e32 v83, 31, v82
	v_lshl_add_u64 v[84:85], v[82:83], 2, s[38:39]
	s_waitcnt vmcnt(10)
	v_mov_b32_e32 v84, v222
	v_pk_mul_f32 v[78:79], v[78:79], v[84:85] op_sel_hi:[1,0]
	v_pk_mul_f32 v[86:87], v[76:77], v[84:85] op_sel_hi:[1,0]
	v_pk_mul_f32 v[76:77], v[74:75], v[84:85] op_sel_hi:[1,0]
	v_cvt_pk_bf16_f32 v74, v78, v79
	v_lshlrev_b64 v[78:79], 12, v[82:83]
	v_pk_mul_f32 v[80:81], v[80:81], v[84:85] op_sel_hi:[1,0]
	v_lshl_add_u64 v[78:79], s[56:57], 0, v[78:79]
	v_cvt_pk_bf16_f32 v75, v80, v81
	v_cvt_pk_bf16_f32 v76, v76, v77
	v_cvt_pk_bf16_f32 v77, v86, v87
	v_lshl_add_u64 v[78:79], v[78:79], 0, v[124:125]
	global_store_dwordx4 v[78:79], v[74:77], off
	v_pk_mul_f32 v[72:73], v[72:73], v[84:85] op_sel_hi:[1,0]
	v_pk_mul_f32 v[70:71], v[70:71], v[84:85] op_sel_hi:[1,0]
	v_pk_mul_f32 v[74:75], v[68:69], v[84:85] op_sel_hi:[1,0]
	v_pk_mul_f32 v[68:69], v[66:67], v[84:85] op_sel_hi:[1,0]
	v_cvt_pk_bf16_f32 v66, v70, v71
	v_cvt_pk_bf16_f32 v67, v72, v73
	v_cvt_pk_bf16_f32 v68, v68, v69
	v_cvt_pk_bf16_f32 v69, v74, v75
	global_store_dwordx4 v[78:79], v[66:69], off offset:256
	s_waitcnt vmcnt(11)
	v_mov_b32_e32 v66, v224
	v_pk_mul_f32 v[64:65], v[64:65], v[66:67] op_sel_hi:[1,0]
	v_pk_mul_f32 v[62:63], v[62:63], v[66:67] op_sel_hi:[1,0]
	v_pk_mul_f32 v[68:69], v[60:61], v[66:67] op_sel_hi:[1,0]
	v_pk_mul_f32 v[60:61], v[58:59], v[66:67] op_sel_hi:[1,0]
	v_cvt_pk_bf16_f32 v59, v64, v65
	v_add_co_u32_e32 v64, vcc, s2, v122
	v_cvt_pk_bf16_f32 v58, v62, v63
	v_cvt_pk_bf16_f32 v60, v60, v61
	v_cvt_pk_bf16_f32 v61, v68, v69
	v_addc_co_u32_e32 v65, vcc, 0, v123, vcc
	global_store_dwordx4 v[64:65], v[58:61], off
	v_pk_mul_f32 v[56:57], v[56:57], v[66:67] op_sel_hi:[1,0]
	v_pk_mul_f32 v[54:55], v[54:55], v[66:67] op_sel_hi:[1,0]
	v_pk_mul_f32 v[58:59], v[52:53], v[66:67] op_sel_hi:[1,0]
	v_pk_mul_f32 v[52:53], v[50:51], v[66:67] op_sel_hi:[1,0]
	v_lshl_add_u64 v[62:63], v[122:123], 0, s[4:5]
	v_cvt_pk_bf16_f32 v50, v54, v55
	v_cvt_pk_bf16_f32 v51, v56, v57
	v_cvt_pk_bf16_f32 v52, v52, v53
	v_cvt_pk_bf16_f32 v53, v58, v59
	global_store_dwordx4 v[62:63], v[50:53], off offset:256
	s_mov_b32 s2, 0x90000
	s_mov_b64 s[4:5], 0x90000
	s_waitcnt vmcnt(12)
	v_mov_b32_e32 v50, v226
	v_pk_mul_f32 v[48:49], v[48:49], v[50:51] op_sel_hi:[1,0]
	v_pk_mul_f32 v[46:47], v[46:47], v[50:51] op_sel_hi:[1,0]
	v_pk_mul_f32 v[52:53], v[44:45], v[50:51] op_sel_hi:[1,0]
	v_pk_mul_f32 v[44:45], v[42:43], v[50:51] op_sel_hi:[1,0]
	v_cvt_pk_bf16_f32 v43, v48, v49
	v_add_co_u32_e32 v48, vcc, s2, v122
	v_cvt_pk_bf16_f32 v42, v46, v47
	v_cvt_pk_bf16_f32 v44, v44, v45
	v_cvt_pk_bf16_f32 v45, v52, v53
	v_addc_co_u32_e32 v49, vcc, 0, v123, vcc
	global_store_dwordx4 v[48:49], v[42:45], off
	v_pk_mul_f32 v[40:41], v[40:41], v[50:51] op_sel_hi:[1,0]
	v_pk_mul_f32 v[38:39], v[38:39], v[50:51] op_sel_hi:[1,0]
	v_pk_mul_f32 v[42:43], v[36:37], v[50:51] op_sel_hi:[1,0]
	v_pk_mul_f32 v[36:37], v[34:35], v[50:51] op_sel_hi:[1,0]
	v_lshl_add_u64 v[46:47], v[122:123], 0, s[4:5]
	v_cvt_pk_bf16_f32 v34, v38, v39
	v_cvt_pk_bf16_f32 v35, v40, v41
	v_cvt_pk_bf16_f32 v36, v36, v37
	v_cvt_pk_bf16_f32 v37, v42, v43
	global_store_dwordx4 v[46:47], v[34:37], off offset:256
	s_mov_b32 s2, 0xa0000
	s_mov_b64 s[4:5], 0xa0000
	s_waitcnt vmcnt(13)
	v_mov_b32_e32 v34, v228
	v_pk_mul_f32 v[32:33], v[32:33], v[34:35] op_sel_hi:[1,0]
	v_pk_mul_f32 v[30:31], v[30:31], v[34:35] op_sel_hi:[1,0]
	v_pk_mul_f32 v[36:37], v[28:29], v[34:35] op_sel_hi:[1,0]
	v_pk_mul_f32 v[28:29], v[26:27], v[34:35] op_sel_hi:[1,0]
	v_cvt_pk_bf16_f32 v27, v32, v33
	v_add_co_u32_e32 v32, vcc, s2, v122
	v_cvt_pk_bf16_f32 v26, v30, v31
	v_cvt_pk_bf16_f32 v28, v28, v29
	v_cvt_pk_bf16_f32 v29, v36, v37
	v_addc_co_u32_e32 v33, vcc, 0, v123, vcc
	global_store_dwordx4 v[32:33], v[26:29], off
	v_pk_mul_f32 v[24:25], v[24:25], v[34:35] op_sel_hi:[1,0]
	v_pk_mul_f32 v[22:23], v[22:23], v[34:35] op_sel_hi:[1,0]
	v_pk_mul_f32 v[26:27], v[20:21], v[34:35] op_sel_hi:[1,0]
	v_pk_mul_f32 v[20:21], v[18:19], v[34:35] op_sel_hi:[1,0]
	v_lshl_add_u64 v[30:31], v[122:123], 0, s[4:5]
	v_cvt_pk_bf16_f32 v18, v22, v23
	v_cvt_pk_bf16_f32 v19, v24, v25
	v_cvt_pk_bf16_f32 v20, v20, v21
	v_cvt_pk_bf16_f32 v21, v26, v27
	global_store_dwordx4 v[30:31], v[18:21], off offset:256
	s_mov_b32 s2, 0xb0000
	s_mov_b64 s[4:5], 0xb0000
	s_waitcnt vmcnt(14)
	v_mov_b32_e32 v18, v230
	v_pk_mul_f32 v[16:17], v[16:17], v[18:19] op_sel_hi:[1,0]
	v_pk_mul_f32 v[14:15], v[14:15], v[18:19] op_sel_hi:[1,0]
	v_pk_mul_f32 v[20:21], v[12:13], v[18:19] op_sel_hi:[1,0]
	v_pk_mul_f32 v[12:13], v[10:11], v[18:19] op_sel_hi:[1,0]
	v_cvt_pk_bf16_f32 v11, v16, v17
	v_add_co_u32_e32 v16, vcc, s2, v122
	v_cvt_pk_bf16_f32 v10, v14, v15
	v_cvt_pk_bf16_f32 v12, v12, v13
	v_cvt_pk_bf16_f32 v13, v20, v21
	v_addc_co_u32_e32 v17, vcc, 0, v123, vcc
	global_store_dwordx4 v[16:17], v[10:13], off
	v_pk_mul_f32 v[8:9], v[8:9], v[18:19] op_sel_hi:[1,0]
	v_pk_mul_f32 v[6:7], v[6:7], v[18:19] op_sel_hi:[1,0]
	v_pk_mul_f32 v[10:11], v[4:5], v[18:19] op_sel_hi:[1,0]
	v_pk_mul_f32 v[4:5], v[2:3], v[18:19] op_sel_hi:[1,0]
	v_lshl_add_u64 v[14:15], v[122:123], 0, s[4:5]
	v_cvt_pk_bf16_f32 v2, v6, v7
	v_cvt_pk_bf16_f32 v3, v8, v9
	v_cvt_pk_bf16_f32 v4, v4, v5
	v_cvt_pk_bf16_f32 v5, v10, v11
	s_and_b64 vcc, exec, s[6:7]
	global_store_dwordx4 v[14:15], v[2:5], off offset:256
	s_cbranch_vccz .LBB0_473
	v_readlane_b32 s4, v254, 12
	s_waitcnt vmcnt(0)
	v_readlane_b32 s5, v254, 13
	v_readlane_b32 s84, v251, 38
	v_readlane_b32 s18, v253, 0
	s_andn2_b64 vcc, exec, s[4:5]
	v_readlane_b32 s85, v251, 39
	v_readlane_b32 s86, v251, 40
	v_readlane_b32 s87, v251, 41
	v_readlane_b32 s14, v250, 63
	v_readlane_b32 s19, v253, 1
	s_cbranch_vccnz .LBB0_486
	s_barrier

.LBB0_500:
	s_add_u32 s2, s6, 0xfffe0080
	s_addc_u32 s17, s7, -1
	s_add_i32 s26, 0, 0x10000
	v_add_u32_e32 v156, s26, v145
	ds_read_b128 v[140:143], v156
	ds_read_b128 v[148:151], v156 offset:1024
	ds_read_b128 v[152:155], v156 offset:2048
	ds_read_b128 v[156:159], v156 offset:3072
	s_cmp_eq_u32 s44, 4
	s_cselect_b32 s81, s11, s17
	s_cselect_b32 s80, s24, s2
	s_cselect_b32 s79, s75, s46
	s_cselect_b32 s78, s74, s25
	v_lshl_add_u64 v[164:165], s[6:7], 0, v[136:137]
	s_add_i32 m0, s58, 0xc000
	ds_read_b128 v[160:163], v147
	ds_read_b128 v[188:191], v147 offset:1024
	ds_read_b128 v[192:195], v147 offset:2048
	ds_read_b128 v[196:199], v147 offset:3072
	ds_read_b128 v[200:203], v147 offset:4096
	ds_read_b128 v[216:219], v147 offset:5120
	ds_read_b128 v[220:223], v147 offset:6144
	ds_read_b128 v[224:227], v147 offset:7168
	global_load_lds_dwordx4 v[164:165], off
	v_lshl_add_u64 v[164:165], s[6:7], 0, v[138:139]
	s_add_i32 m0, s58, 0xe000
	s_nop 0
	global_load_lds_dwordx4 v[164:165], off
	s_waitcnt lgkmcnt(8)
	s_barrier
	s_waitcnt lgkmcnt(7)
	v_mfma_f32_16x16x32_bf16 v[126:129], v[140:143], v[160:163], v[126:129]
	v_mfma_f32_16x16x32_bf16 v[122:125], v[152:155], v[160:163], v[122:125]
	s_waitcnt lgkmcnt(5)
	v_mfma_f32_16x16x32_bf16 v[110:113], v[140:143], v[192:195], v[110:113]
	v_mfma_f32_16x16x32_bf16 v[106:109], v[152:155], v[192:195], v[106:109]
	s_waitcnt lgkmcnt(3)
	v_mfma_f32_16x16x32_bf16 v[94:97], v[140:143], v[200:203], v[94:97]
	v_mfma_f32_16x16x32_bf16 v[90:93], v[152:155], v[200:203], v[90:93]
	s_waitcnt lgkmcnt(1)
	v_mfma_f32_16x16x32_bf16 v[78:81], v[140:143], v[220:223], v[78:81]
	v_mfma_f32_16x16x32_bf16 v[74:77], v[152:155], v[220:223], v[74:77]
	v_mfma_f32_16x16x32_bf16 v[126:129], v[148:151], v[188:191], v[126:129]
	v_mfma_f32_16x16x32_bf16 v[122:125], v[156:159], v[188:191], v[122:125]
	v_mfma_f32_16x16x32_bf16 v[110:113], v[148:151], v[196:199], v[110:113]
	v_mfma_f32_16x16x32_bf16 v[106:109], v[156:159], v[196:199], v[106:109]
	v_mfma_f32_16x16x32_bf16 v[94:97], v[148:151], v[216:219], v[94:97]
	v_mfma_f32_16x16x32_bf16 v[90:93], v[156:159], v[216:219], v[90:93]
	s_waitcnt lgkmcnt(0)
	v_mfma_f32_16x16x32_bf16 v[78:81], v[148:151], v[224:227], v[78:81]
	v_mfma_f32_16x16x32_bf16 v[74:77], v[156:159], v[224:227], v[74:77]
	s_barrier
	s_add_i32 s2, 0, 0x14000
	v_add_u32_e32 v164, s2, v145
	s_add_i32 s17, s26, s3
	ds_read_b128 v[228:231], v164
	ds_read_b128 v[232:235], v164 offset:1024
	ds_read_b128 v[236:239], v164 offset:2048
	ds_read_b128 v[240:243], v164 offset:3072
	v_lshl_add_u64 v[164:165], s[78:79], 0, v[0:1]
	s_mov_b32 m0, s17
	v_lshl_add_u64 v[204:205], s[78:79], 0, v[130:131]
	global_load_lds_dwordx4 v[164:165], off
	s_add_i32 m0, s17, 0x2000
	s_nop 0
	global_load_lds_dwordx4 v[204:205], off
	s_barrier
	s_waitcnt lgkmcnt(3)
	v_mfma_f32_16x16x32_bf16 v[118:121], v[228:231], v[160:163], v[118:121]
	s_waitcnt lgkmcnt(1)
	v_mfma_f32_16x16x32_bf16 v[114:117], v[236:239], v[160:163], v[114:117]
	v_mfma_f32_16x16x32_bf16 v[102:105], v[228:231], v[192:195], v[102:105]
	v_mfma_f32_16x16x32_bf16 v[98:101], v[236:239], v[192:195], v[98:101]
	v_mfma_f32_16x16x32_bf16 v[86:89], v[228:231], v[200:203], v[86:89]
	v_mfma_f32_16x16x32_bf16 v[82:85], v[236:239], v[200:203], v[82:85]
	v_mfma_f32_16x16x32_bf16 v[70:73], v[228:231], v[220:223], v[70:73]
	v_mfma_f32_16x16x32_bf16 v[66:69], v[236:239], v[220:223], v[66:69]
	v_mfma_f32_16x16x32_bf16 v[118:121], v[232:235], v[188:191], v[118:121]
	s_waitcnt lgkmcnt(0)
	v_mfma_f32_16x16x32_bf16 v[114:117], v[240:243], v[188:191], v[114:117]
	v_mfma_f32_16x16x32_bf16 v[102:105], v[232:235], v[196:199], v[102:105]
	v_mfma_f32_16x16x32_bf16 v[98:101], v[240:243], v[196:199], v[98:101]
	v_mfma_f32_16x16x32_bf16 v[86:89], v[232:235], v[216:219], v[86:89]
	v_mfma_f32_16x16x32_bf16 v[82:85], v[240:243], v[216:219], v[82:85]
	v_mfma_f32_16x16x32_bf16 v[70:73], v[232:235], v[224:227], v[70:73]
	v_mfma_f32_16x16x32_bf16 v[66:69], v[240:243], v[224:227], v[66:69]
	s_mov_b32 m0, s58
	v_lshl_add_u64 v[244:245], s[80:81], 0, v[134:135]
	s_barrier
	ds_read_b128 v[160:163], v147 offset:16384
	ds_read_b128 v[188:191], v147 offset:17408
	ds_read_b128 v[192:195], v147 offset:18432
	ds_read_b128 v[196:199], v147 offset:19456
	ds_read_b128 v[200:203], v147 offset:20480
	ds_read_b128 v[216:219], v147 offset:21504
	ds_read_b128 v[220:223], v147 offset:22528
	ds_read_b128 v[224:227], v147 offset:23552
	global_load_lds_dwordx4 v[244:245], off
	v_lshl_add_u64 v[246:247], s[80:81], 0, v[132:133]
	s_mov_b32 m0, s69
	s_nop 0
	global_load_lds_dwordx4 v[246:247], off
	s_barrier
	s_waitcnt lgkmcnt(7)
	v_mfma_f32_16x16x32_bf16 v[62:65], v[140:143], v[160:163], v[62:65]
	v_mfma_f32_16x16x32_bf16 v[58:61], v[152:155], v[160:163], v[58:61]
	s_waitcnt lgkmcnt(5)
	v_mfma_f32_16x16x32_bf16 v[54:57], v[140:143], v[192:195], v[54:57]
	v_mfma_f32_16x16x32_bf16 v[46:49], v[152:155], v[192:195], v[46:49]
	s_waitcnt lgkmcnt(3)
	v_mfma_f32_16x16x32_bf16 v[38:41], v[140:143], v[200:203], v[38:41]
	v_mfma_f32_16x16x32_bf16 v[30:33], v[152:155], v[200:203], v[30:33]
	s_waitcnt lgkmcnt(1)
	v_mfma_f32_16x16x32_bf16 v[22:25], v[140:143], v[220:223], v[22:25]
	v_mfma_f32_16x16x32_bf16 v[14:17], v[152:155], v[220:223], v[14:17]
	v_mfma_f32_16x16x32_bf16 v[62:65], v[148:151], v[188:191], v[62:65]
	v_mfma_f32_16x16x32_bf16 v[58:61], v[156:159], v[188:191], v[58:61]
	v_mfma_f32_16x16x32_bf16 v[54:57], v[148:151], v[196:199], v[54:57]
	v_mfma_f32_16x16x32_bf16 v[46:49], v[156:159], v[196:199], v[46:49]
	v_mfma_f32_16x16x32_bf16 v[38:41], v[148:151], v[216:219], v[38:41]
	v_mfma_f32_16x16x32_bf16 v[30:33], v[156:159], v[216:219], v[30:33]
	s_waitcnt lgkmcnt(0)
	v_mfma_f32_16x16x32_bf16 v[22:25], v[148:151], v[224:227], v[22:25]
	v_mfma_f32_16x16x32_bf16 v[14:17], v[156:159], v[224:227], v[14:17]
	s_barrier
	s_add_u32 s26, s78, 0xd0000
	s_addc_u32 s27, s79, 0
	s_add_i32 s2, s2, s3
	v_lshl_add_u64 v[140:141], s[26:27], 0, v[0:1]
	s_mov_b32 m0, s2
	s_nop 0
	global_load_lds_dwordx4 v[140:141], off
	v_lshl_add_u64 v[140:141], s[26:27], 0, v[130:131]
	s_add_i32 m0, s2, 0x2000
	s_nop 0
	global_load_lds_dwordx4 v[140:141], off
	s_waitcnt vmcnt(6)
	s_barrier
	v_mfma_f32_16x16x32_bf16 v[50:53], v[228:231], v[160:163], v[50:53]
	v_mfma_f32_16x16x32_bf16 v[42:45], v[236:239], v[160:163], v[42:45]
	v_mfma_f32_16x16x32_bf16 v[34:37], v[228:231], v[192:195], v[34:37]
	v_mfma_f32_16x16x32_bf16 v[26:29], v[236:239], v[192:195], v[26:29]
	v_mfma_f32_16x16x32_bf16 v[18:21], v[228:231], v[200:203], v[18:21]
	v_mfma_f32_16x16x32_bf16 v[10:13], v[236:239], v[200:203], v[10:13]
	v_mfma_f32_16x16x32_bf16 v[6:9], v[228:231], v[220:223], v[6:9]
	v_mfma_f32_16x16x32_bf16 v[2:5], v[236:239], v[220:223], v[2:5]
	v_mfma_f32_16x16x32_bf16 v[50:53], v[232:235], v[188:191], v[50:53]
	v_mfma_f32_16x16x32_bf16 v[42:45], v[240:243], v[188:191], v[42:45]
	v_mfma_f32_16x16x32_bf16 v[34:37], v[232:235], v[196:199], v[34:37]
	v_mfma_f32_16x16x32_bf16 v[26:29], v[240:243], v[196:199], v[26:29]
	v_mfma_f32_16x16x32_bf16 v[18:21], v[232:235], v[216:219], v[18:21]
	v_mfma_f32_16x16x32_bf16 v[10:13], v[240:243], v[216:219], v[10:13]
	v_mfma_f32_16x16x32_bf16 v[6:9], v[232:235], v[224:227], v[6:9]
	v_mfma_f32_16x16x32_bf16 v[2:5], v[240:243], v[224:227], v[2:5]
	s_add_i32 s2, 0, 0x18000
	v_add_u32_e32 v156, s2, v145
	s_barrier
	ds_read_b128 v[140:143], v156
	ds_read_b128 v[148:151], v156 offset:1024
	ds_read_b128 v[152:155], v156 offset:2048
	ds_read_b128 v[156:159], v156 offset:3072
	s_add_u32 s26, s80, 0x20000
	s_addc_u32 s27, s81, 0
	s_mov_b32 m0, s70
	v_lshl_add_u64 v[228:229], s[26:27], 0, v[134:135]
	ds_read_b128 v[160:163], v147 offset:32768
	ds_read_b128 v[188:191], v147 offset:33792
	ds_read_b128 v[192:195], v147 offset:34816
	ds_read_b128 v[196:199], v147 offset:35840
	ds_read_b128 v[200:203], v147 offset:36864
	ds_read_b128 v[216:219], v147 offset:37888
	ds_read_b128 v[220:223], v147 offset:38912
	ds_read_b128 v[224:227], v147 offset:39936
	global_load_lds_dwordx4 v[228:229], off
	v_lshl_add_u64 v[228:229], s[26:27], 0, v[132:133]
	s_mov_b32 m0, s71
	s_nop 0
	global_load_lds_dwordx4 v[228:229], off
	s_waitcnt lgkmcnt(8)
	s_barrier
	s_waitcnt lgkmcnt(7)
	v_mfma_f32_16x16x32_bf16 v[126:129], v[140:143], v[160:163], v[126:129]
	v_mfma_f32_16x16x32_bf16 v[122:125], v[152:155], v[160:163], v[122:125]
	s_waitcnt lgkmcnt(5)
	v_mfma_f32_16x16x32_bf16 v[110:113], v[140:143], v[192:195], v[110:113]
	v_mfma_f32_16x16x32_bf16 v[106:109], v[152:155], v[192:195], v[106:109]
	s_waitcnt lgkmcnt(3)
	v_mfma_f32_16x16x32_bf16 v[94:97], v[140:143], v[200:203], v[94:97]
	v_mfma_f32_16x16x32_bf16 v[90:93], v[152:155], v[200:203], v[90:93]
	s_waitcnt lgkmcnt(1)
	v_mfma_f32_16x16x32_bf16 v[78:81], v[140:143], v[220:223], v[78:81]
	v_mfma_f32_16x16x32_bf16 v[74:77], v[152:155], v[220:223], v[74:77]
	v_mfma_f32_16x16x32_bf16 v[126:129], v[148:151], v[188:191], v[126:129]
	v_mfma_f32_16x16x32_bf16 v[122:125], v[156:159], v[188:191], v[122:125]
	v_mfma_f32_16x16x32_bf16 v[110:113], v[148:151], v[196:199], v[110:113]
	v_mfma_f32_16x16x32_bf16 v[106:109], v[156:159], v[196:199], v[106:109]
	v_mfma_f32_16x16x32_bf16 v[94:97], v[148:151], v[216:219], v[94:97]
	v_mfma_f32_16x16x32_bf16 v[90:93], v[156:159], v[216:219], v[90:93]
	s_waitcnt lgkmcnt(0)
	v_mfma_f32_16x16x32_bf16 v[78:81], v[148:151], v[224:227], v[78:81]
	v_mfma_f32_16x16x32_bf16 v[74:77], v[156:159], v[224:227], v[74:77]
	s_barrier
	s_add_i32 s17, 0, 0x1c000
	s_add_i32 s2, s2, s3
	v_add_u32_e32 v206, s17, v145
	v_lshl_add_u64 v[164:165], v[164:165], 0, s[28:29]
	s_mov_b32 m0, s2
	ds_read_b128 v[228:231], v206
	ds_read_b128 v[232:235], v206 offset:1024
	ds_read_b128 v[236:239], v206 offset:2048
	ds_read_b128 v[240:243], v206 offset:3072
	global_load_lds_dwordx4 v[164:165], off
	v_lshl_add_u64 v[164:165], v[204:205], 0, s[28:29]
	s_add_i32 m0, s2, 0x2000
	s_nop 0
	global_load_lds_dwordx4 v[164:165], off
	s_barrier
	s_waitcnt lgkmcnt(3)
	v_mfma_f32_16x16x32_bf16 v[118:121], v[228:231], v[160:163], v[118:121]
	s_waitcnt lgkmcnt(1)
	v_mfma_f32_16x16x32_bf16 v[114:117], v[236:239], v[160:163], v[114:117]
	v_mfma_f32_16x16x32_bf16 v[102:105], v[228:231], v[192:195], v[102:105]
	v_mfma_f32_16x16x32_bf16 v[98:101], v[236:239], v[192:195], v[98:101]
	v_mfma_f32_16x16x32_bf16 v[86:89], v[228:231], v[200:203], v[86:89]
	v_mfma_f32_16x16x32_bf16 v[82:85], v[236:239], v[200:203], v[82:85]
	v_mfma_f32_16x16x32_bf16 v[70:73], v[228:231], v[220:223], v[70:73]
	v_mfma_f32_16x16x32_bf16 v[66:69], v[236:239], v[220:223], v[66:69]
	v_mfma_f32_16x16x32_bf16 v[118:121], v[232:235], v[188:191], v[118:121]
	s_waitcnt lgkmcnt(0)
	v_mfma_f32_16x16x32_bf16 v[114:117], v[240:243], v[188:191], v[114:117]
	v_mfma_f32_16x16x32_bf16 v[102:105], v[232:235], v[196:199], v[102:105]
	v_mfma_f32_16x16x32_bf16 v[98:101], v[240:243], v[196:199], v[98:101]
	v_mfma_f32_16x16x32_bf16 v[86:89], v[232:235], v[216:219], v[86:89]
	v_mfma_f32_16x16x32_bf16 v[82:85], v[240:243], v[216:219], v[82:85]
	v_mfma_f32_16x16x32_bf16 v[70:73], v[232:235], v[224:227], v[70:73]
	v_mfma_f32_16x16x32_bf16 v[66:69], v[240:243], v[224:227], v[66:69]
	s_mov_b32 m0, s72
	v_lshl_add_u64 v[164:165], v[244:245], 0, s[28:29]
	s_barrier
	ds_read_b128 v[160:163], v147 offset:49152
	ds_read_b128 v[188:191], v147 offset:50176
	ds_read_b128 v[192:195], v147 offset:51200
	ds_read_b128 v[196:199], v147 offset:52224
	ds_read_b128 v[200:203], v147 offset:53248
	ds_read_b128 v[216:219], v147 offset:54272
	ds_read_b128 v[220:223], v147 offset:55296
	ds_read_b128 v[224:227], v147 offset:56320
	global_load_lds_dwordx4 v[164:165], off
	v_lshl_add_u64 v[164:165], v[246:247], 0, s[28:29]
	s_mov_b32 m0, s73
	s_nop 0
	global_load_lds_dwordx4 v[164:165], off
	s_barrier
	s_waitcnt lgkmcnt(7)
	v_mfma_f32_16x16x32_bf16 v[62:65], v[140:143], v[160:163], v[62:65]
	v_mfma_f32_16x16x32_bf16 v[58:61], v[152:155], v[160:163], v[58:61]
	s_waitcnt lgkmcnt(5)
	v_mfma_f32_16x16x32_bf16 v[54:57], v[140:143], v[192:195], v[54:57]
	v_mfma_f32_16x16x32_bf16 v[46:49], v[152:155], v[192:195], v[46:49]
	s_waitcnt lgkmcnt(3)
	v_mfma_f32_16x16x32_bf16 v[38:41], v[140:143], v[200:203], v[38:41]
	v_mfma_f32_16x16x32_bf16 v[30:33], v[152:155], v[200:203], v[30:33]
	s_waitcnt lgkmcnt(1)
	v_mfma_f32_16x16x32_bf16 v[22:25], v[140:143], v[220:223], v[22:25]
	v_mfma_f32_16x16x32_bf16 v[14:17], v[152:155], v[220:223], v[14:17]
	v_mfma_f32_16x16x32_bf16 v[62:65], v[148:151], v[188:191], v[62:65]
	v_mfma_f32_16x16x32_bf16 v[58:61], v[156:159], v[188:191], v[58:61]
	v_mfma_f32_16x16x32_bf16 v[54:57], v[148:151], v[196:199], v[54:57]
	v_mfma_f32_16x16x32_bf16 v[46:49], v[156:159], v[196:199], v[46:49]
	v_mfma_f32_16x16x32_bf16 v[38:41], v[148:151], v[216:219], v[38:41]
	v_mfma_f32_16x16x32_bf16 v[30:33], v[156:159], v[216:219], v[30:33]
	s_waitcnt lgkmcnt(0)
	v_mfma_f32_16x16x32_bf16 v[22:25], v[148:151], v[224:227], v[22:25]
	v_mfma_f32_16x16x32_bf16 v[14:17], v[156:159], v[224:227], v[14:17]
	s_barrier
	s_add_u32 s26, s78, 0xd0080
	s_addc_u32 s27, s79, 0
	s_add_i32 s2, s17, s3
	v_lshl_add_u64 v[140:141], s[26:27], 0, v[0:1]
	s_mov_b32 m0, s2
	s_nop 0
	global_load_lds_dwordx4 v[140:141], off
	v_lshl_add_u64 v[140:141], s[26:27], 0, v[130:131]
	s_add_i32 m0, s2, 0x2000
	s_nop 0
	global_load_lds_dwordx4 v[140:141], off
	s_waitcnt vmcnt(6)
	s_barrier
	v_mfma_f32_16x16x32_bf16 v[50:53], v[228:231], v[160:163], v[50:53]
	v_mfma_f32_16x16x32_bf16 v[42:45], v[236:239], v[160:163], v[42:45]
	v_mfma_f32_16x16x32_bf16 v[34:37], v[228:231], v[192:195], v[34:37]
	v_mfma_f32_16x16x32_bf16 v[26:29], v[236:239], v[192:195], v[26:29]
	v_mfma_f32_16x16x32_bf16 v[18:21], v[228:231], v[200:203], v[18:21]
	v_mfma_f32_16x16x32_bf16 v[10:13], v[236:239], v[200:203], v[10:13]
	v_mfma_f32_16x16x32_bf16 v[6:9], v[228:231], v[220:223], v[6:9]
	v_mfma_f32_16x16x32_bf16 v[2:5], v[236:239], v[220:223], v[2:5]
	v_mfma_f32_16x16x32_bf16 v[50:53], v[232:235], v[188:191], v[50:53]
	v_mfma_f32_16x16x32_bf16 v[42:45], v[240:243], v[188:191], v[42:45]
	v_mfma_f32_16x16x32_bf16 v[34:37], v[232:235], v[196:199], v[34:37]
	v_mfma_f32_16x16x32_bf16 v[26:29], v[240:243], v[196:199], v[26:29]
	v_mfma_f32_16x16x32_bf16 v[18:21], v[232:235], v[216:219], v[18:21]
	v_mfma_f32_16x16x32_bf16 v[10:13], v[240:243], v[216:219], v[10:13]
	v_mfma_f32_16x16x32_bf16 v[6:9], v[232:235], v[224:227], v[6:9]
	v_mfma_f32_16x16x32_bf16 v[2:5], v[240:243], v[224:227], v[2:5]
	s_add_i32 s44, s44, 2
	s_add_u32 s6, s6, 0x100
	s_addc_u32 s7, s7, 0
	s_add_u32 s25, s25, 0x100
	s_addc_u32 s46, s46, 0
	s_cmp_gt_u32 s44, 5
	s_barrier
	s_cbranch_scc0 .LBB0_500
	v_lshl_or_b32 v156, s62, 8, v146
	v_ashrrev_i32_e32 v157, 31, v156
	v_lshl_add_u64 v[140:141], v[156:157], 2, s[38:39]
	global_load_dwordx4 v[200:203], v[140:141], off offset:16
	global_load_dwordx4 v[220:223], v[140:141], off
	global_load_dwordx4 v[228:231], v[140:141], off offset:528
	global_load_dwordx4 v[236:239], v[140:141], off offset:512
	v_lshl_add_u32 v142, s63, 8, v144
	v_ashrrev_i32_e32 v143, 31, v142
	s_mov_b32 s2, 0x400000
	s_mov_b64 s[6:7], 0x400000
	s_mov_b32 s62, s41
	s_mov_b32 s63, s10
	s_mov_b64 s[78:79], s[74:75]
	s_mov_b64 s[80:81], s[76:77]
	s_waitcnt vmcnt(0)
	v_mov_b32_e32 v148, v200
	v_mov_b32_e32 v149, v201
	v_mov_b32_e32 v150, v202
	v_mov_b32_e32 v151, v203
	v_mov_b32_e32 v152, v220
	v_mov_b32_e32 v153, v221
	v_mov_b32_e32 v154, v222
	v_mov_b32_e32 v155, v223
	v_pk_mul_f32 v[122:123], v[122:123], v[148:149]
	v_pk_mul_f32 v[126:127], v[126:127], v[152:153]
	v_pk_mul_f32 v[124:125], v[124:125], v[150:151]
	v_cvt_pk_bf16_f32 v150, v122, v123
	v_lshlrev_b64 v[122:123], 15, v[142:143]
	v_pk_mul_f32 v[128:129], v[128:129], v[154:155]
	v_cvt_pk_bf16_f32 v148, v126, v127
	v_cvt_pk_bf16_f32 v151, v124, v125
	v_lshl_add_u64 v[122:123], s[60:61], 0, v[122:123]
	v_lshlrev_b64 v[126:127], 1, v[156:157]
	v_or_b32_e32 v124, 0x80, v156
	v_cvt_pk_bf16_f32 v149, v128, v129
	v_lshl_add_u64 v[122:123], v[122:123], 0, v[126:127]
	v_ashrrev_i32_e32 v125, 31, v124
	global_store_dwordx4 v[122:123], v[148:151], off
	v_lshl_add_u64 v[124:125], v[124:125], 2, s[38:39]
	s_nop 1
	v_mov_b32_e32 v148, v228
	v_mov_b32_e32 v149, v229
	v_mov_b32_e32 v150, v230
	v_mov_b32_e32 v151, v231
	s_nop 1
	v_mov_b32_e32 v152, v236
	v_mov_b32_e32 v153, v237
	v_mov_b32_e32 v154, v238
	v_mov_b32_e32 v155, v239
	s_nop 0
	v_pk_mul_f32 v[128:129], v[116:117], v[150:151]
	v_pk_mul_f32 v[120:121], v[120:121], v[154:155]
	v_pk_mul_f32 v[118:119], v[118:119], v[152:153]
	v_pk_mul_f32 v[116:117], v[114:115], v[148:149]
	v_cvt_pk_bf16_f32 v114, v118, v119
	v_cvt_pk_bf16_f32 v115, v120, v121
	v_cvt_pk_bf16_f32 v116, v116, v117
	v_cvt_pk_bf16_f32 v117, v128, v129
	global_store_dwordx4 v[122:123], v[114:117], off offset:256
	s_nop 1
	v_mov_b32_e32 v114, v200
	v_mov_b32_e32 v115, v201
	v_mov_b32_e32 v116, v202
	v_mov_b32_e32 v117, v203
	s_nop 0
	s_nop 1
	v_mov_b32_e32 v118, v220
	v_mov_b32_e32 v119, v221
	v_mov_b32_e32 v120, v222
	v_mov_b32_e32 v121, v223
	v_or_b32_e32 v128, 16, v142
	v_ashrrev_i32_e32 v129, 31, v128
	s_nop 0
	v_pk_mul_f32 v[116:117], v[108:109], v[116:117]
	v_pk_mul_f32 v[110:111], v[110:111], v[118:119]
	v_pk_mul_f32 v[108:109], v[106:107], v[114:115]
	v_cvt_pk_bf16_f32 v106, v110, v111
	v_lshlrev_b64 v[110:111], 15, v[128:129]
	v_pk_mul_f32 v[112:113], v[112:113], v[120:121]
	v_lshl_add_u64 v[110:111], s[60:61], 0, v[110:111]
	v_cvt_pk_bf16_f32 v107, v112, v113
	v_cvt_pk_bf16_f32 v108, v108, v109
	v_cvt_pk_bf16_f32 v109, v116, v117
	v_lshl_add_u64 v[114:115], v[110:111], 0, v[126:127]
	global_store_dwordx4 v[114:115], v[106:109], off
	s_nop 1
	v_mov_b32_e32 v106, v228
	v_mov_b32_e32 v107, v229
	v_mov_b32_e32 v108, v230
	v_mov_b32_e32 v109, v231
	s_nop 0
	s_nop 1
	v_mov_b32_e32 v110, v236
	v_mov_b32_e32 v111, v237
	v_mov_b32_e32 v112, v238
	v_mov_b32_e32 v113, v239
	s_nop 0
	v_pk_mul_f32 v[108:109], v[100:101], v[108:109]
	v_pk_mul_f32 v[104:105], v[104:105], v[112:113]
	v_pk_mul_f32 v[102:103], v[102:103], v[110:111]
	v_pk_mul_f32 v[100:101], v[98:99], v[106:107]
	v_cvt_pk_bf16_f32 v98, v102, v103
	v_cvt_pk_bf16_f32 v99, v104, v105
	v_cvt_pk_bf16_f32 v100, v100, v101
	v_cvt_pk_bf16_f32 v101, v108, v109
	global_store_dwordx4 v[114:115], v[98:101], off offset:256
	s_nop 1
	v_mov_b32_e32 v98, v200
	v_mov_b32_e32 v99, v201
	v_mov_b32_e32 v100, v202
	v_mov_b32_e32 v101, v203
	s_nop 0
	s_nop 1
	v_mov_b32_e32 v102, v220
	v_mov_b32_e32 v103, v221
	v_mov_b32_e32 v104, v222
	v_mov_b32_e32 v105, v223
	v_or_b32_e32 v106, 32, v142
	v_ashrrev_i32_e32 v107, 31, v106
	s_nop 0
	v_pk_mul_f32 v[100:101], v[92:93], v[100:101]
	v_pk_mul_f32 v[94:95], v[94:95], v[102:103]
	v_pk_mul_f32 v[92:93], v[90:91], v[98:99]
	v_cvt_pk_bf16_f32 v90, v94, v95
	v_lshlrev_b64 v[94:95], 15, v[106:107]
	v_pk_mul_f32 v[96:97], v[96:97], v[104:105]
	v_lshl_add_u64 v[94:95], s[60:61], 0, v[94:95]
	v_cvt_pk_bf16_f32 v91, v96, v97
	v_cvt_pk_bf16_f32 v92, v92, v93
	v_cvt_pk_bf16_f32 v93, v100, v101
	v_lshl_add_u64 v[98:99], v[94:95], 0, v[126:127]
	global_store_dwordx4 v[98:99], v[90:93], off
	s_nop 1
	v_mov_b32_e32 v90, v228
	v_mov_b32_e32 v91, v229
	v_mov_b32_e32 v92, v230
	v_mov_b32_e32 v93, v231
	s_nop 0
	s_nop 1
	v_mov_b32_e32 v94, v236
	v_mov_b32_e32 v95, v237
	v_mov_b32_e32 v96, v238
	v_mov_b32_e32 v97, v239
	s_nop 0
	v_pk_mul_f32 v[92:93], v[84:85], v[92:93]
	v_pk_mul_f32 v[88:89], v[88:89], v[96:97]
	v_pk_mul_f32 v[86:87], v[86:87], v[94:95]
	v_pk_mul_f32 v[84:85], v[82:83], v[90:91]
	v_cvt_pk_bf16_f32 v82, v86, v87
	v_cvt_pk_bf16_f32 v83, v88, v89
	v_cvt_pk_bf16_f32 v84, v84, v85
	v_cvt_pk_bf16_f32 v85, v92, v93
	global_store_dwordx4 v[98:99], v[82:85], off offset:256
	s_nop 1
	v_mov_b32_e32 v82, v200
	v_mov_b32_e32 v83, v201
	v_mov_b32_e32 v84, v202
	v_mov_b32_e32 v85, v203
	s_nop 0
	s_nop 1
	v_mov_b32_e32 v86, v220
	v_mov_b32_e32 v87, v221
	v_mov_b32_e32 v88, v222
	v_mov_b32_e32 v89, v223
	v_or_b32_e32 v90, 48, v142
	v_ashrrev_i32_e32 v91, 31, v90
	s_nop 0
	v_pk_mul_f32 v[84:85], v[76:77], v[84:85]
	v_pk_mul_f32 v[78:79], v[78:79], v[86:87]
	v_pk_mul_f32 v[76:77], v[74:75], v[82:83]
	v_cvt_pk_bf16_f32 v74, v78, v79
	v_lshlrev_b64 v[78:79], 15, v[90:91]
	v_pk_mul_f32 v[80:81], v[80:81], v[88:89]
	v_lshl_add_u64 v[78:79], s[60:61], 0, v[78:79]
	v_cvt_pk_bf16_f32 v75, v80, v81
	v_cvt_pk_bf16_f32 v76, v76, v77
	v_cvt_pk_bf16_f32 v77, v84, v85
	v_lshl_add_u64 v[82:83], v[78:79], 0, v[126:127]
	global_store_dwordx4 v[82:83], v[74:77], off
	s_nop 1
	v_mov_b32_e32 v74, v228
	v_mov_b32_e32 v75, v229
	v_mov_b32_e32 v76, v230
	v_mov_b32_e32 v77, v231
	s_nop 0
	s_nop 1
	v_mov_b32_e32 v78, v236
	v_mov_b32_e32 v79, v237
	v_mov_b32_e32 v80, v238
	v_mov_b32_e32 v81, v239
	s_nop 0
	v_pk_mul_f32 v[76:77], v[68:69], v[76:77]
	v_pk_mul_f32 v[72:73], v[72:73], v[80:81]
	v_pk_mul_f32 v[70:71], v[70:71], v[78:79]
	v_pk_mul_f32 v[68:69], v[66:67], v[74:75]
	v_cvt_pk_bf16_f32 v66, v70, v71
	v_cvt_pk_bf16_f32 v67, v72, v73
	v_cvt_pk_bf16_f32 v68, v68, v69
	v_cvt_pk_bf16_f32 v69, v76, v77
	global_store_dwordx4 v[82:83], v[66:69], off offset:256
	s_nop 1
	v_mov_b32_e32 v66, v200
	v_mov_b32_e32 v67, v201
	v_mov_b32_e32 v68, v202
	v_mov_b32_e32 v69, v203
	s_nop 0
	s_nop 1
	v_mov_b32_e32 v70, v220
	v_mov_b32_e32 v71, v221
	v_mov_b32_e32 v72, v222
	v_mov_b32_e32 v73, v223
	s_nop 0
	v_pk_mul_f32 v[68:69], v[60:61], v[68:69]
	v_pk_mul_f32 v[62:63], v[62:63], v[70:71]
	v_pk_mul_f32 v[64:65], v[64:65], v[72:73]
	v_pk_mul_f32 v[60:61], v[58:59], v[66:67]
	v_cvt_pk_bf16_f32 v58, v62, v63
	v_add_co_u32_e32 v62, vcc, s2, v122
	v_cvt_pk_bf16_f32 v59, v64, v65
	v_cvt_pk_bf16_f32 v60, v60, v61
	v_cvt_pk_bf16_f32 v61, v68, v69
	v_addc_co_u32_e32 v63, vcc, 0, v123, vcc
	global_store_dwordx4 v[62:63], v[58:61], off
	s_nop 1
	v_mov_b32_e32 v58, v228
	v_mov_b32_e32 v59, v229
	v_mov_b32_e32 v60, v230
	v_mov_b32_e32 v61, v231
	s_nop 0
	s_nop 1
	v_mov_b32_e32 v62, v236
	v_mov_b32_e32 v63, v237
	v_mov_b32_e32 v64, v238
	v_mov_b32_e32 v65, v239
	v_lshl_add_u64 v[66:67], v[122:123], 0, s[6:7]
	s_mov_b32 s2, 0x480000
	s_mov_b64 s[6:7], 0x480000
	s_nop 0
	v_pk_mul_f32 v[60:61], v[44:45], v[60:61]
	v_pk_mul_f32 v[52:53], v[52:53], v[64:65]
	v_pk_mul_f32 v[50:51], v[50:51], v[62:63]
	v_pk_mul_f32 v[44:45], v[42:43], v[58:59]
	v_cvt_pk_bf16_f32 v42, v50, v51
	v_cvt_pk_bf16_f32 v43, v52, v53
	v_cvt_pk_bf16_f32 v44, v44, v45
	v_cvt_pk_bf16_f32 v45, v60, v61
	global_store_dwordx4 v[66:67], v[42:45], off offset:256
	s_nop 1
	v_mov_b32_e32 v42, v200
	v_mov_b32_e32 v43, v201
	v_mov_b32_e32 v44, v202
	v_mov_b32_e32 v45, v203
	s_nop 0
	s_nop 1
	v_mov_b32_e32 v50, v220
	v_mov_b32_e32 v51, v221
	v_mov_b32_e32 v52, v222
	v_mov_b32_e32 v53, v223
	s_nop 0
	v_pk_mul_f32 v[48:49], v[48:49], v[44:45]
	v_pk_mul_f32 v[52:53], v[56:57], v[52:53]
	v_pk_mul_f32 v[50:51], v[54:55], v[50:51]
	v_pk_mul_f32 v[44:45], v[46:47], v[42:43]
	v_add_co_u32_e32 v46, vcc, s2, v122
	v_cvt_pk_bf16_f32 v42, v50, v51
	v_cvt_pk_bf16_f32 v43, v52, v53
	v_cvt_pk_bf16_f32 v44, v44, v45
	v_cvt_pk_bf16_f32 v45, v48, v49
	v_addc_co_u32_e32 v47, vcc, 0, v123, vcc
	global_store_dwordx4 v[46:47], v[42:45], off
	s_nop 1
	v_mov_b32_e32 v42, v228
	v_mov_b32_e32 v43, v229
	v_mov_b32_e32 v44, v230
	v_mov_b32_e32 v45, v231
	s_nop 0
	s_nop 1
	v_mov_b32_e32 v46, v236
	v_mov_b32_e32 v47, v237
	v_mov_b32_e32 v48, v238
	v_mov_b32_e32 v49, v239
	v_lshl_add_u64 v[50:51], v[122:123], 0, s[6:7]
	s_mov_b32 s2, 0x500000
	s_mov_b64 s[6:7], 0x500000
	s_nop 0
	v_pk_mul_f32 v[44:45], v[28:29], v[44:45]
	v_pk_mul_f32 v[36:37], v[36:37], v[48:49]
	v_pk_mul_f32 v[34:35], v[34:35], v[46:47]
	v_pk_mul_f32 v[28:29], v[26:27], v[42:43]
	v_cvt_pk_bf16_f32 v26, v34, v35
	v_cvt_pk_bf16_f32 v27, v36, v37
	v_cvt_pk_bf16_f32 v28, v28, v29
	v_cvt_pk_bf16_f32 v29, v44, v45
	global_store_dwordx4 v[50:51], v[26:29], off offset:256
	s_nop 1
	v_mov_b32_e32 v26, v200
	v_mov_b32_e32 v27, v201
	v_mov_b32_e32 v28, v202
	v_mov_b32_e32 v29, v203
	s_nop 0
	s_nop 1
	v_mov_b32_e32 v34, v220
	v_mov_b32_e32 v35, v221
	v_mov_b32_e32 v36, v222
	v_mov_b32_e32 v37, v223
	s_nop 0
	v_pk_mul_f32 v[32:33], v[32:33], v[28:29]
	v_pk_mul_f32 v[36:37], v[40:41], v[36:37]
	v_pk_mul_f32 v[34:35], v[38:39], v[34:35]
	v_pk_mul_f32 v[28:29], v[30:31], v[26:27]
	v_add_co_u32_e32 v30, vcc, s2, v122
	v_cvt_pk_bf16_f32 v26, v34, v35
	v_cvt_pk_bf16_f32 v27, v36, v37
	v_cvt_pk_bf16_f32 v28, v28, v29
	v_cvt_pk_bf16_f32 v29, v32, v33
	v_addc_co_u32_e32 v31, vcc, 0, v123, vcc
	global_store_dwordx4 v[30:31], v[26:29], off
	s_nop 1
	v_mov_b32_e32 v26, v228
	v_mov_b32_e32 v27, v229
	v_mov_b32_e32 v28, v230
	v_mov_b32_e32 v29, v231
	s_nop 0
	s_nop 1
	v_mov_b32_e32 v30, v236
	v_mov_b32_e32 v31, v237
	v_mov_b32_e32 v32, v238
	v_mov_b32_e32 v33, v239
	v_lshl_add_u64 v[34:35], v[122:123], 0, s[6:7]
	s_mov_b32 s2, 0x580000
	s_mov_b64 s[6:7], 0x580000
	s_nop 0
	v_pk_mul_f32 v[28:29], v[12:13], v[28:29]
	v_pk_mul_f32 v[20:21], v[20:21], v[32:33]
	v_pk_mul_f32 v[18:19], v[18:19], v[30:31]
	v_pk_mul_f32 v[12:13], v[10:11], v[26:27]
	v_cvt_pk_bf16_f32 v10, v18, v19
	v_cvt_pk_bf16_f32 v11, v20, v21
	v_cvt_pk_bf16_f32 v12, v12, v13
	v_cvt_pk_bf16_f32 v13, v28, v29
	global_store_dwordx4 v[34:35], v[10:13], off offset:256
	s_nop 1
	v_mov_b32_e32 v10, v200
	v_mov_b32_e32 v11, v201
	v_mov_b32_e32 v12, v202
	v_mov_b32_e32 v13, v203
	s_nop 0
	s_nop 1
	v_mov_b32_e32 v18, v220
	v_mov_b32_e32 v19, v221
	v_mov_b32_e32 v20, v222
	v_mov_b32_e32 v21, v223
	s_nop 0
	v_pk_mul_f32 v[16:17], v[16:17], v[12:13]
	v_pk_mul_f32 v[20:21], v[24:25], v[20:21]
	v_pk_mul_f32 v[18:19], v[22:23], v[18:19]
	v_pk_mul_f32 v[12:13], v[14:15], v[10:11]
	v_add_co_u32_e32 v14, vcc, s2, v122
	v_cvt_pk_bf16_f32 v10, v18, v19
	v_cvt_pk_bf16_f32 v11, v20, v21
	v_cvt_pk_bf16_f32 v12, v12, v13
	v_cvt_pk_bf16_f32 v13, v16, v17
	v_addc_co_u32_e32 v15, vcc, 0, v123, vcc
	global_store_dwordx4 v[14:15], v[10:13], off
	s_nop 1
	v_mov_b32_e32 v10, v228
	v_mov_b32_e32 v11, v229
	v_mov_b32_e32 v12, v230
	v_mov_b32_e32 v13, v231
	s_nop 0
	s_nop 1
	v_mov_b32_e32 v14, v236
	v_mov_b32_e32 v15, v237
	v_mov_b32_e32 v16, v238
	v_mov_b32_e32 v17, v239
	v_lshl_add_u64 v[18:19], v[122:123], 0, s[6:7]
	s_and_b64 vcc, exec, s[0:1]
	s_nop 0
	v_pk_mul_f32 v[12:13], v[4:5], v[12:13]
	v_pk_mul_f32 v[8:9], v[8:9], v[16:17]
	v_pk_mul_f32 v[6:7], v[6:7], v[14:15]
	v_pk_mul_f32 v[4:5], v[2:3], v[10:11]
	v_cvt_pk_bf16_f32 v2, v6, v7
	v_cvt_pk_bf16_f32 v3, v8, v9
	v_cvt_pk_bf16_f32 v4, v4, v5
	v_cvt_pk_bf16_f32 v5, v12, v13
	global_store_dwordx4 v[18:19], v[2:5], off offset:256
	s_cbranch_vccz .LBB0_491
	v_readlane_b32 s0, v254, 12
	s_waitcnt vmcnt(0)
	v_readlane_b32 s1, v254, 13
	v_readlane_b32 s84, v251, 38
	v_readlane_b32 s18, v253, 0
	s_andn2_b64 vcc, exec, s[0:1]
	v_readlane_b32 s85, v251, 39
	v_readlane_b32 s86, v251, 40
	v_readlane_b32 s87, v251, 41
	v_readlane_b32 s14, v250, 63
	v_readlane_b32 s19, v253, 1
	s_cbranch_vccnz .LBB0_504
	s_barrier

.LBB0_582:
	v_pk_add_f32 v[134:135], v[134:135], v[224:225] op_sel_hi:[1,0] neg_lo:[0,1] neg_hi:[0,1]
	v_pk_add_f32 v[136:137], v[136:137], v[224:225] op_sel_hi:[1,0] neg_lo:[0,1] neg_hi:[0,1]
	v_exp_f32_e32 v134, v134
	v_exp_f32_e32 v135, v135
	v_pk_add_f32 v[138:139], v[138:139], v[224:225] op_sel_hi:[1,0] neg_lo:[0,1] neg_hi:[0,1]
	v_exp_f32_e32 v136, v136
	v_exp_f32_e32 v137, v137
	v_pk_add_f32 v[140:141], v[140:141], v[224:225] op_sel_hi:[1,0] neg_lo:[0,1] neg_hi:[0,1]
	v_exp_f32_e32 v138, v138
	v_exp_f32_e32 v139, v139
	v_pk_add_f32 v[234:235], v[146:147], v[224:225] op_sel_hi:[1,0] neg_lo:[0,1] neg_hi:[0,1]
	v_pk_add_f32 v[146:147], v[134:135], v[136:137]
	v_exp_f32_e32 v140, v140
	v_exp_f32_e32 v141, v141
	v_pk_add_f32 v[236:237], v[148:149], v[224:225] op_sel_hi:[1,0] neg_lo:[0,1] neg_hi:[0,1]
	v_pk_add_f32 v[146:147], v[146:147], v[138:139]
	v_exp_f32_e32 v234, v234
	v_exp_f32_e32 v235, v235
	v_pk_add_f32 v[238:239], v[142:143], v[224:225] op_sel_hi:[1,0] neg_lo:[0,1] neg_hi:[0,1]
	v_pk_add_f32 v[146:147], v[146:147], v[140:141]
	v_exp_f32_e32 v236, v236
	v_exp_f32_e32 v237, v237
	v_pk_add_f32 v[242:243], v[144:145], v[224:225] op_sel_hi:[1,0] neg_lo:[0,1] neg_hi:[0,1]
	v_pk_add_f32 v[146:147], v[146:147], v[234:235]
	v_exp_f32_e32 v238, v238
	v_exp_f32_e32 v239, v239
	v_pk_add_f32 v[226:227], v[150:151], v[222:223] op_sel:[0,1] op_sel_hi:[1,1] neg_lo:[0,1] neg_hi:[0,1]
	v_pk_add_f32 v[146:147], v[146:147], v[236:237]
	v_exp_f32_e32 v242, v242
	v_exp_f32_e32 v243, v243
	v_pk_add_f32 v[228:229], v[152:153], v[222:223] op_sel:[0,1] op_sel_hi:[1,1] neg_lo:[0,1] neg_hi:[0,1]
	v_pk_add_f32 v[146:147], v[146:147], v[238:239]
	v_exp_f32_e32 v226, v226
	v_exp_f32_e32 v227, v227
	v_pk_add_f32 v[230:231], v[154:155], v[222:223] op_sel:[0,1] op_sel_hi:[1,1] neg_lo:[0,1] neg_hi:[0,1]
	v_pk_add_f32 v[146:147], v[146:147], v[242:243]
	v_exp_f32_e32 v228, v228
	v_exp_f32_e32 v229, v229
	v_pk_add_f32 v[232:233], v[156:157], v[222:223] op_sel:[0,1] op_sel_hi:[1,1] neg_lo:[0,1] neg_hi:[0,1]
	v_exp_f32_e32 v230, v230
	v_exp_f32_e32 v231, v231
	v_pk_add_f32 v[158:159], v[158:159], v[222:223] op_sel:[0,1] op_sel_hi:[1,1] neg_lo:[0,1] neg_hi:[0,1]
	v_pk_add_f32 v[148:149], v[226:227], v[228:229]
	v_exp_f32_e32 v232, v232
	v_exp_f32_e32 v233, v233
	v_pk_add_f32 v[160:161], v[160:161], v[222:223] op_sel:[0,1] op_sel_hi:[1,1] neg_lo:[0,1] neg_hi:[0,1]
	v_pk_add_f32 v[148:149], v[148:149], v[230:231]
	v_exp_f32_e32 v158, v158
	v_exp_f32_e32 v159, v159
	v_pk_add_f32 v[162:163], v[162:163], v[222:223] op_sel:[0,1] op_sel_hi:[1,1] neg_lo:[0,1] neg_hi:[0,1]
	v_pk_add_f32 v[148:149], v[148:149], v[232:233]
	v_exp_f32_e32 v160, v160
	v_exp_f32_e32 v161, v161
	v_pk_add_f32 v[164:165], v[164:165], v[222:223] op_sel:[0,1] op_sel_hi:[1,1] neg_lo:[0,1] neg_hi:[0,1]
	v_pk_add_f32 v[148:149], v[148:149], v[158:159]
	v_exp_f32_e32 v162, v162
	v_exp_f32_e32 v163, v163
	v_pk_add_f32 v[148:149], v[148:149], v[160:161]
	v_exp_f32_e32 v164, v164
	v_exp_f32_e32 v165, v165
	v_pk_add_f32 v[148:149], v[148:149], v[162:163]
	v_add_f32_e32 v241, v146, v147
	v_fmac_f32_e32 v241, v191, v208
	s_nop 1
	v_pk_add_f32 v[148:149], v[148:149], v[164:165]
	v_add_f32_e32 v191, v148, v149
	s_mul_i32 s0, s24, 0x4800
	v_fmac_f32_e32 v191, v203, v206
	v_add_u32_e32 v203, s0, v197
	v_cvt_pk_bf16_f32 v154, v158, v159
	v_add_u32_e32 v206, 0xc800, v203
	v_add_u32_e32 v158, 0xd000, v203
	v_cvt_pk_bf16_f32 v155, v160, v161
	v_cvt_pk_bf16_f32 v134, v134, v135
	v_cvt_pk_bf16_f32 v135, v136, v137
	v_cvt_pk_bf16_f32 v136, v138, v139
	v_cvt_pk_bf16_f32 v137, v140, v141
	ds_read2_b64 v[138:141], v206 offset1:4
	ds_read2_b64 v[142:145], v206 offset0:8 offset1:12
	ds_read2_b64 v[146:149], v158 offset0:32 offset1:36
	ds_read2_b64 v[158:161], v158 offset0:40 offset1:44
	v_cvt_pk_bf16_f32 v150, v226, v227
	v_cvt_pk_bf16_f32 v151, v228, v229
	v_cvt_pk_bf16_f32 v152, v230, v231
	v_cvt_pk_bf16_f32 v153, v232, v233
	v_cvt_pk_bf16_f32 v156, v162, v163
	v_cvt_pk_bf16_f32 v157, v164, v165
	v_cvt_pk_bf16_f32 v162, v234, v235
	v_cvt_pk_bf16_f32 v163, v236, v237
	v_cvt_pk_bf16_f32 v164, v238, v239
	v_cvt_pk_bf16_f32 v165, v242, v243
	s_waitcnt lgkmcnt(3)
	v_mfma_f32_16x16x32_bf16 v[62:65], v[138:141], v[150:153], v[62:65]
	v_mfma_f32_16x16x32_bf16 v[30:33], v[138:141], v[134:137], v[30:33]
	s_waitcnt lgkmcnt(2)
	v_mfma_f32_16x16x32_bf16 v[62:65], v[142:145], v[154:157], v[62:65]
	v_mfma_f32_16x16x32_bf16 v[30:33], v[142:145], v[162:165], v[30:33]
	v_add_u32_e32 v142, 0xd800, v203
	ds_read2_b64 v[138:141], v142 offset0:64 offset1:68
	ds_read2_b64 v[142:145], v142 offset0:72 offset1:76
	s_waitcnt lgkmcnt(3)
	v_mfma_f32_16x16x32_bf16 v[58:61], v[146:149], v[150:153], v[58:61]
	v_mfma_f32_16x16x32_bf16 v[26:29], v[146:149], v[134:137], v[26:29]
	s_waitcnt lgkmcnt(2)
	v_mfma_f32_16x16x32_bf16 v[58:61], v[158:161], v[154:157], v[58:61]
	v_mfma_f32_16x16x32_bf16 v[26:29], v[158:161], v[162:165], v[26:29]
	v_add_u32_e32 v158, 0xe000, v203
	ds_read2_b64 v[146:149], v158 offset0:96 offset1:100
	ds_read2_b64 v[158:161], v158 offset0:104 offset1:108
	s_waitcnt lgkmcnt(3)
	v_mfma_f32_16x16x32_bf16 v[54:57], v[138:141], v[150:153], v[54:57]
	v_mfma_f32_16x16x32_bf16 v[22:25], v[138:141], v[134:137], v[22:25]
	s_waitcnt lgkmcnt(2)
	v_mfma_f32_16x16x32_bf16 v[54:57], v[142:145], v[154:157], v[54:57]
	v_mfma_f32_16x16x32_bf16 v[22:25], v[142:145], v[162:165], v[22:25]
	v_add_u32_e32 v142, 0xe800, v203
	ds_read2_b64 v[138:141], v142 offset0:128 offset1:132
	ds_read2_b64 v[142:145], v142 offset0:136 offset1:140
	s_waitcnt lgkmcnt(3)
	v_mfma_f32_16x16x32_bf16 v[50:53], v[146:149], v[150:153], v[50:53]
	v_mfma_f32_16x16x32_bf16 v[18:21], v[146:149], v[134:137], v[18:21]
	s_waitcnt lgkmcnt(2)
	v_mfma_f32_16x16x32_bf16 v[50:53], v[158:161], v[154:157], v[50:53]
	v_mfma_f32_16x16x32_bf16 v[18:21], v[158:161], v[162:165], v[18:21]
	v_add_u32_e32 v158, 0xf000, v203
	ds_read2_b64 v[146:149], v158 offset0:160 offset1:164
	ds_read2_b64 v[158:161], v158 offset0:168 offset1:172
	s_waitcnt lgkmcnt(3)
	v_mfma_f32_16x16x32_bf16 v[46:49], v[138:141], v[150:153], v[46:49]
	v_mfma_f32_16x16x32_bf16 v[14:17], v[138:141], v[134:137], v[14:17]
	s_waitcnt lgkmcnt(2)
	v_mfma_f32_16x16x32_bf16 v[46:49], v[142:145], v[154:157], v[46:49]
	v_mfma_f32_16x16x32_bf16 v[14:17], v[142:145], v[162:165], v[14:17]
	v_add_u32_e32 v142, 0xf800, v203
	ds_read2_b64 v[138:141], v142 offset0:192 offset1:196
	ds_read2_b64 v[142:145], v142 offset0:200 offset1:204
	s_waitcnt lgkmcnt(3)
	v_mfma_f32_16x16x32_bf16 v[42:45], v[146:149], v[150:153], v[42:45]
	v_mfma_f32_16x16x32_bf16 v[10:13], v[146:149], v[134:137], v[10:13]
	s_waitcnt lgkmcnt(2)
	v_mfma_f32_16x16x32_bf16 v[42:45], v[158:161], v[154:157], v[42:45]
	v_mfma_f32_16x16x32_bf16 v[10:13], v[158:161], v[162:165], v[10:13]
	v_add_u32_e32 v158, 0x3800, v206
	ds_read2_b64 v[146:149], v158 offset0:224 offset1:228
	ds_read2_b64 v[158:161], v158 offset0:232 offset1:236
	s_waitcnt lgkmcnt(3)
	v_mfma_f32_16x16x32_bf16 v[38:41], v[138:141], v[150:153], v[38:41]
	v_mfma_f32_16x16x32_bf16 v[6:9], v[138:141], v[134:137], v[6:9]
	s_waitcnt lgkmcnt(2)
	v_mfma_f32_16x16x32_bf16 v[38:41], v[142:145], v[154:157], v[38:41]
	v_mfma_f32_16x16x32_bf16 v[6:9], v[142:145], v[162:165], v[6:9]
	s_waitcnt lgkmcnt(1)
	v_mfma_f32_16x16x32_bf16 v[34:37], v[146:149], v[150:153], v[34:37]
	v_mfma_f32_16x16x32_bf16 v[2:5], v[146:149], v[134:137], v[2:5]
	s_waitcnt lgkmcnt(0)
	v_mfma_f32_16x16x32_bf16 v[34:37], v[158:161], v[154:157], v[34:37]
	v_mfma_f32_16x16x32_bf16 v[2:5], v[158:161], v[162:165], v[2:5]
	v_mov_b32_e32 v203, v191
	v_mov_b32_e32 v191, v241
	s_andn2_b64 vcc, exec, s[6:7]
	s_mov_b64 s[0:1], -1
	s_cbranch_vccz .LBB0_584
	s_branch .LBB0_585

.LBB0_655:
	s_add_u32 s2, s68, 0xfff80080
	s_addc_u32 s17, s69, -1
	s_add_i32 s26, 0, 0x10000
	v_add_u32_e32 v156, s26, v141
	ds_read_b128 v[144:147], v156
	ds_read_b128 v[148:151], v156 offset:1024
	ds_read_b128 v[152:155], v156 offset:2048
	ds_read_b128 v[156:159], v156 offset:3072
	s_cmp_eq_u32 s44, 28
	s_cselect_b32 s73, s55, s17
	s_cselect_b32 s72, s83, s2
	s_cselect_b32 s71, s24, s92
	s_cselect_b32 s70, s25, s43
	v_lshl_add_u64 v[164:165], s[68:69], 0, v[136:137]
	s_add_i32 m0, s58, 0xc000
	ds_read_b128 v[160:163], v143
	ds_read_b128 v[188:191], v143 offset:1024
	ds_read_b128 v[192:195], v143 offset:2048
	ds_read_b128 v[196:199], v143 offset:3072
	ds_read_b128 v[200:203], v143 offset:4096
	ds_read_b128 v[216:219], v143 offset:5120
	ds_read_b128 v[220:223], v143 offset:6144
	ds_read_b128 v[224:227], v143 offset:7168
	global_load_lds_dwordx4 v[164:165], off
	v_lshl_add_u64 v[164:165], s[68:69], 0, v[138:139]
	s_add_i32 m0, s58, 0xe000
	s_nop 0
	global_load_lds_dwordx4 v[164:165], off
	s_waitcnt lgkmcnt(8)
	s_barrier
	s_waitcnt lgkmcnt(7)
	v_mfma_f32_16x16x32_bf16 v[126:129], v[144:147], v[160:163], v[126:129]
	v_mfma_f32_16x16x32_bf16 v[122:125], v[152:155], v[160:163], v[122:125]
	s_waitcnt lgkmcnt(5)
	v_mfma_f32_16x16x32_bf16 v[118:121], v[144:147], v[192:195], v[118:121]
	v_mfma_f32_16x16x32_bf16 v[114:117], v[152:155], v[192:195], v[114:117]
	s_waitcnt lgkmcnt(3)
	v_mfma_f32_16x16x32_bf16 v[102:105], v[144:147], v[200:203], v[102:105]
	v_mfma_f32_16x16x32_bf16 v[98:101], v[152:155], v[200:203], v[98:101]
	s_waitcnt lgkmcnt(1)
	v_mfma_f32_16x16x32_bf16 v[86:89], v[144:147], v[220:223], v[86:89]
	v_mfma_f32_16x16x32_bf16 v[82:85], v[152:155], v[220:223], v[82:85]
	v_mfma_f32_16x16x32_bf16 v[126:129], v[148:151], v[188:191], v[126:129]
	v_mfma_f32_16x16x32_bf16 v[122:125], v[156:159], v[188:191], v[122:125]
	v_mfma_f32_16x16x32_bf16 v[118:121], v[148:151], v[196:199], v[118:121]
	v_mfma_f32_16x16x32_bf16 v[114:117], v[156:159], v[196:199], v[114:117]
	v_mfma_f32_16x16x32_bf16 v[102:105], v[148:151], v[216:219], v[102:105]
	v_mfma_f32_16x16x32_bf16 v[98:101], v[156:159], v[216:219], v[98:101]
	s_waitcnt lgkmcnt(0)
	v_mfma_f32_16x16x32_bf16 v[86:89], v[148:151], v[224:227], v[86:89]
	v_mfma_f32_16x16x32_bf16 v[82:85], v[156:159], v[224:227], v[82:85]
	s_barrier
	s_add_i32 s2, 0, 0x14000
	v_add_u32_e32 v164, s2, v141
	s_add_i32 s17, s26, s3
	ds_read_b128 v[228:231], v164
	ds_read_b128 v[232:235], v164 offset:1024
	ds_read_b128 v[236:239], v164 offset:2048
	ds_read_b128 v[240:243], v164 offset:3072
	v_lshl_add_u64 v[164:165], s[70:71], 0, v[0:1]
	s_mov_b32 m0, s17
	v_lshl_add_u64 v[204:205], s[70:71], 0, v[130:131]
	global_load_lds_dwordx4 v[164:165], off
	s_add_i32 m0, s17, 0x2000
	s_nop 0
	global_load_lds_dwordx4 v[204:205], off
	s_barrier
	s_waitcnt lgkmcnt(3)
	v_mfma_f32_16x16x32_bf16 v[110:113], v[228:231], v[160:163], v[110:113]
	s_waitcnt lgkmcnt(1)
	v_mfma_f32_16x16x32_bf16 v[106:109], v[236:239], v[160:163], v[106:109]
	v_mfma_f32_16x16x32_bf16 v[94:97], v[228:231], v[192:195], v[94:97]
	v_mfma_f32_16x16x32_bf16 v[90:93], v[236:239], v[192:195], v[90:93]
	v_mfma_f32_16x16x32_bf16 v[78:81], v[228:231], v[200:203], v[78:81]
	v_mfma_f32_16x16x32_bf16 v[74:77], v[236:239], v[200:203], v[74:77]
	v_mfma_f32_16x16x32_bf16 v[70:73], v[228:231], v[220:223], v[70:73]
	v_mfma_f32_16x16x32_bf16 v[66:69], v[236:239], v[220:223], v[66:69]
	v_mfma_f32_16x16x32_bf16 v[110:113], v[232:235], v[188:191], v[110:113]
	s_waitcnt lgkmcnt(0)
	v_mfma_f32_16x16x32_bf16 v[106:109], v[240:243], v[188:191], v[106:109]
	v_mfma_f32_16x16x32_bf16 v[94:97], v[232:235], v[196:199], v[94:97]
	v_mfma_f32_16x16x32_bf16 v[90:93], v[240:243], v[196:199], v[90:93]
	v_mfma_f32_16x16x32_bf16 v[78:81], v[232:235], v[216:219], v[78:81]
	v_mfma_f32_16x16x32_bf16 v[74:77], v[240:243], v[216:219], v[74:77]
	v_mfma_f32_16x16x32_bf16 v[70:73], v[232:235], v[224:227], v[70:73]
	v_mfma_f32_16x16x32_bf16 v[66:69], v[240:243], v[224:227], v[66:69]
	s_mov_b32 m0, s58
	v_lshl_add_u64 v[244:245], s[72:73], 0, v[134:135]
	s_barrier
	ds_read_b128 v[160:163], v143 offset:16384
	ds_read_b128 v[188:191], v143 offset:17408
	ds_read_b128 v[192:195], v143 offset:18432
	ds_read_b128 v[196:199], v143 offset:19456
	ds_read_b128 v[200:203], v143 offset:20480
	ds_read_b128 v[216:219], v143 offset:21504
	ds_read_b128 v[220:223], v143 offset:22528
	ds_read_b128 v[224:227], v143 offset:23552
	global_load_lds_dwordx4 v[244:245], off
	v_lshl_add_u64 v[246:247], s[72:73], 0, v[132:133]
	s_mov_b32 m0, s74
	s_nop 0
	global_load_lds_dwordx4 v[246:247], off
	s_barrier
	s_waitcnt lgkmcnt(7)
	v_mfma_f32_16x16x32_bf16 v[62:65], v[144:147], v[160:163], v[62:65]
	v_mfma_f32_16x16x32_bf16 v[58:61], v[152:155], v[160:163], v[58:61]
	s_waitcnt lgkmcnt(5)
	v_mfma_f32_16x16x32_bf16 v[54:57], v[144:147], v[192:195], v[54:57]
	v_mfma_f32_16x16x32_bf16 v[50:53], v[152:155], v[192:195], v[50:53]
	s_waitcnt lgkmcnt(3)
	v_mfma_f32_16x16x32_bf16 v[38:41], v[144:147], v[200:203], v[38:41]
	v_mfma_f32_16x16x32_bf16 v[34:37], v[152:155], v[200:203], v[34:37]
	s_waitcnt lgkmcnt(1)
	v_mfma_f32_16x16x32_bf16 v[22:25], v[144:147], v[220:223], v[22:25]
	v_mfma_f32_16x16x32_bf16 v[18:21], v[152:155], v[220:223], v[18:21]
	v_mfma_f32_16x16x32_bf16 v[62:65], v[148:151], v[188:191], v[62:65]
	v_mfma_f32_16x16x32_bf16 v[58:61], v[156:159], v[188:191], v[58:61]
	v_mfma_f32_16x16x32_bf16 v[54:57], v[148:151], v[196:199], v[54:57]
	v_mfma_f32_16x16x32_bf16 v[50:53], v[156:159], v[196:199], v[50:53]
	v_mfma_f32_16x16x32_bf16 v[38:41], v[148:151], v[216:219], v[38:41]
	v_mfma_f32_16x16x32_bf16 v[34:37], v[156:159], v[216:219], v[34:37]
	s_waitcnt lgkmcnt(0)
	v_mfma_f32_16x16x32_bf16 v[22:25], v[148:151], v[224:227], v[22:25]
	v_mfma_f32_16x16x32_bf16 v[18:21], v[156:159], v[224:227], v[18:21]
	s_barrier
	s_add_u32 s26, s70, 0x80000
	s_addc_u32 s27, s71, 0
	s_add_i32 s2, s2, s3
	v_lshl_add_u64 v[144:145], s[26:27], 0, v[0:1]
	s_mov_b32 m0, s2
	s_nop 0
	global_load_lds_dwordx4 v[144:145], off
	v_lshl_add_u64 v[144:145], s[26:27], 0, v[130:131]
	s_add_i32 m0, s2, 0x2000
	s_nop 0
	global_load_lds_dwordx4 v[144:145], off
	s_waitcnt vmcnt(6)
	s_barrier
	v_mfma_f32_16x16x32_bf16 v[46:49], v[228:231], v[160:163], v[46:49]
	v_mfma_f32_16x16x32_bf16 v[42:45], v[236:239], v[160:163], v[42:45]
	v_mfma_f32_16x16x32_bf16 v[30:33], v[228:231], v[192:195], v[30:33]
	v_mfma_f32_16x16x32_bf16 v[26:29], v[236:239], v[192:195], v[26:29]
	v_mfma_f32_16x16x32_bf16 v[14:17], v[228:231], v[200:203], v[14:17]
	v_mfma_f32_16x16x32_bf16 v[10:13], v[236:239], v[200:203], v[10:13]
	v_mfma_f32_16x16x32_bf16 v[6:9], v[228:231], v[220:223], v[6:9]
	v_mfma_f32_16x16x32_bf16 v[2:5], v[236:239], v[220:223], v[2:5]
	v_mfma_f32_16x16x32_bf16 v[46:49], v[232:235], v[188:191], v[46:49]
	v_mfma_f32_16x16x32_bf16 v[42:45], v[240:243], v[188:191], v[42:45]
	v_mfma_f32_16x16x32_bf16 v[30:33], v[232:235], v[196:199], v[30:33]
	v_mfma_f32_16x16x32_bf16 v[26:29], v[240:243], v[196:199], v[26:29]
	v_mfma_f32_16x16x32_bf16 v[14:17], v[232:235], v[216:219], v[14:17]
	v_mfma_f32_16x16x32_bf16 v[10:13], v[240:243], v[216:219], v[10:13]
	v_mfma_f32_16x16x32_bf16 v[6:9], v[232:235], v[224:227], v[6:9]
	v_mfma_f32_16x16x32_bf16 v[2:5], v[240:243], v[224:227], v[2:5]
	s_add_i32 s2, 0, 0x18000
	v_add_u32_e32 v156, s2, v141
	s_barrier
	ds_read_b128 v[144:147], v156
	ds_read_b128 v[148:151], v156 offset:1024
	ds_read_b128 v[152:155], v156 offset:2048
	ds_read_b128 v[156:159], v156 offset:3072
	s_add_u32 s26, s72, 0x80000
	s_addc_u32 s27, s73, 0
	s_mov_b32 m0, s75
	v_lshl_add_u64 v[228:229], s[26:27], 0, v[134:135]
	ds_read_b128 v[160:163], v143 offset:32768
	ds_read_b128 v[188:191], v143 offset:33792
	ds_read_b128 v[192:195], v143 offset:34816
	ds_read_b128 v[196:199], v143 offset:35840
	ds_read_b128 v[200:203], v143 offset:36864
	ds_read_b128 v[216:219], v143 offset:37888
	ds_read_b128 v[220:223], v143 offset:38912
	ds_read_b128 v[224:227], v143 offset:39936
	global_load_lds_dwordx4 v[228:229], off
	v_lshl_add_u64 v[228:229], s[26:27], 0, v[132:133]
	s_mov_b32 m0, s79
	s_nop 0
	global_load_lds_dwordx4 v[228:229], off
	s_waitcnt lgkmcnt(8)
	s_barrier
	s_waitcnt lgkmcnt(7)
	v_mfma_f32_16x16x32_bf16 v[126:129], v[144:147], v[160:163], v[126:129]
	v_mfma_f32_16x16x32_bf16 v[122:125], v[152:155], v[160:163], v[122:125]
	s_waitcnt lgkmcnt(5)
	v_mfma_f32_16x16x32_bf16 v[118:121], v[144:147], v[192:195], v[118:121]
	v_mfma_f32_16x16x32_bf16 v[114:117], v[152:155], v[192:195], v[114:117]
	s_waitcnt lgkmcnt(3)
	v_mfma_f32_16x16x32_bf16 v[102:105], v[144:147], v[200:203], v[102:105]
	v_mfma_f32_16x16x32_bf16 v[98:101], v[152:155], v[200:203], v[98:101]
	s_waitcnt lgkmcnt(1)
	v_mfma_f32_16x16x32_bf16 v[86:89], v[144:147], v[220:223], v[86:89]
	v_mfma_f32_16x16x32_bf16 v[82:85], v[152:155], v[220:223], v[82:85]
	v_mfma_f32_16x16x32_bf16 v[126:129], v[148:151], v[188:191], v[126:129]
	v_mfma_f32_16x16x32_bf16 v[122:125], v[156:159], v[188:191], v[122:125]
	v_mfma_f32_16x16x32_bf16 v[118:121], v[148:151], v[196:199], v[118:121]
	v_mfma_f32_16x16x32_bf16 v[114:117], v[156:159], v[196:199], v[114:117]
	v_mfma_f32_16x16x32_bf16 v[102:105], v[148:151], v[216:219], v[102:105]
	v_mfma_f32_16x16x32_bf16 v[98:101], v[156:159], v[216:219], v[98:101]
	s_waitcnt lgkmcnt(0)
	v_mfma_f32_16x16x32_bf16 v[86:89], v[148:151], v[224:227], v[86:89]
	v_mfma_f32_16x16x32_bf16 v[82:85], v[156:159], v[224:227], v[82:85]
	s_barrier
	s_add_i32 s17, 0, 0x1c000
	s_add_i32 s2, s2, s3
	v_add_u32_e32 v206, s17, v141
	v_lshl_add_u64 v[164:165], v[164:165], 0, s[28:29]
	s_mov_b32 m0, s2
	ds_read_b128 v[228:231], v206
	ds_read_b128 v[232:235], v206 offset:1024
	ds_read_b128 v[236:239], v206 offset:2048
	ds_read_b128 v[240:243], v206 offset:3072
	global_load_lds_dwordx4 v[164:165], off
	v_lshl_add_u64 v[164:165], v[204:205], 0, s[28:29]
	s_add_i32 m0, s2, 0x2000
	s_nop 0
	global_load_lds_dwordx4 v[164:165], off
	s_barrier
	s_waitcnt lgkmcnt(3)
	v_mfma_f32_16x16x32_bf16 v[110:113], v[228:231], v[160:163], v[110:113]
	s_waitcnt lgkmcnt(1)
	v_mfma_f32_16x16x32_bf16 v[106:109], v[236:239], v[160:163], v[106:109]
	v_mfma_f32_16x16x32_bf16 v[94:97], v[228:231], v[192:195], v[94:97]
	v_mfma_f32_16x16x32_bf16 v[90:93], v[236:239], v[192:195], v[90:93]
	v_mfma_f32_16x16x32_bf16 v[78:81], v[228:231], v[200:203], v[78:81]
	v_mfma_f32_16x16x32_bf16 v[74:77], v[236:239], v[200:203], v[74:77]
	v_mfma_f32_16x16x32_bf16 v[70:73], v[228:231], v[220:223], v[70:73]
	v_mfma_f32_16x16x32_bf16 v[66:69], v[236:239], v[220:223], v[66:69]
	v_mfma_f32_16x16x32_bf16 v[110:113], v[232:235], v[188:191], v[110:113]
	s_waitcnt lgkmcnt(0)
	v_mfma_f32_16x16x32_bf16 v[106:109], v[240:243], v[188:191], v[106:109]
	v_mfma_f32_16x16x32_bf16 v[94:97], v[232:235], v[196:199], v[94:97]
	v_mfma_f32_16x16x32_bf16 v[90:93], v[240:243], v[196:199], v[90:93]
	v_mfma_f32_16x16x32_bf16 v[78:81], v[232:235], v[216:219], v[78:81]
	v_mfma_f32_16x16x32_bf16 v[74:77], v[240:243], v[216:219], v[74:77]
	v_mfma_f32_16x16x32_bf16 v[70:73], v[232:235], v[224:227], v[70:73]
	v_mfma_f32_16x16x32_bf16 v[66:69], v[240:243], v[224:227], v[66:69]
	s_mov_b32 m0, s80
	v_lshl_add_u64 v[164:165], v[244:245], 0, s[28:29]
	s_barrier
	ds_read_b128 v[160:163], v143 offset:49152
	ds_read_b128 v[188:191], v143 offset:50176
	ds_read_b128 v[192:195], v143 offset:51200
	ds_read_b128 v[196:199], v143 offset:52224
	ds_read_b128 v[200:203], v143 offset:53248
	ds_read_b128 v[216:219], v143 offset:54272
	ds_read_b128 v[220:223], v143 offset:55296
	ds_read_b128 v[224:227], v143 offset:56320
	global_load_lds_dwordx4 v[164:165], off
	v_lshl_add_u64 v[164:165], v[246:247], 0, s[28:29]
	s_mov_b32 m0, s81
	s_nop 0
	global_load_lds_dwordx4 v[164:165], off
	s_barrier
	s_waitcnt lgkmcnt(7)
	v_mfma_f32_16x16x32_bf16 v[62:65], v[144:147], v[160:163], v[62:65]
	v_mfma_f32_16x16x32_bf16 v[58:61], v[152:155], v[160:163], v[58:61]
	s_waitcnt lgkmcnt(5)
	v_mfma_f32_16x16x32_bf16 v[54:57], v[144:147], v[192:195], v[54:57]
	v_mfma_f32_16x16x32_bf16 v[50:53], v[152:155], v[192:195], v[50:53]
	s_waitcnt lgkmcnt(3)
	v_mfma_f32_16x16x32_bf16 v[38:41], v[144:147], v[200:203], v[38:41]
	v_mfma_f32_16x16x32_bf16 v[34:37], v[152:155], v[200:203], v[34:37]
	s_waitcnt lgkmcnt(1)
	v_mfma_f32_16x16x32_bf16 v[22:25], v[144:147], v[220:223], v[22:25]
	v_mfma_f32_16x16x32_bf16 v[18:21], v[152:155], v[220:223], v[18:21]
	v_mfma_f32_16x16x32_bf16 v[62:65], v[148:151], v[188:191], v[62:65]
	v_mfma_f32_16x16x32_bf16 v[58:61], v[156:159], v[188:191], v[58:61]
	v_mfma_f32_16x16x32_bf16 v[54:57], v[148:151], v[196:199], v[54:57]
	v_mfma_f32_16x16x32_bf16 v[50:53], v[156:159], v[196:199], v[50:53]
	v_mfma_f32_16x16x32_bf16 v[38:41], v[148:151], v[216:219], v[38:41]
	v_mfma_f32_16x16x32_bf16 v[34:37], v[156:159], v[216:219], v[34:37]
	s_waitcnt lgkmcnt(0)
	v_mfma_f32_16x16x32_bf16 v[22:25], v[148:151], v[224:227], v[22:25]
	v_mfma_f32_16x16x32_bf16 v[18:21], v[156:159], v[224:227], v[18:21]
	s_barrier
	s_add_u32 s26, s70, 0x80080
	s_addc_u32 s27, s71, 0
	s_add_i32 s2, s17, s3
	v_lshl_add_u64 v[144:145], s[26:27], 0, v[0:1]
	s_mov_b32 m0, s2
	s_nop 0
	global_load_lds_dwordx4 v[144:145], off
	v_lshl_add_u64 v[144:145], s[26:27], 0, v[130:131]
	s_add_i32 m0, s2, 0x2000
	s_nop 0
	global_load_lds_dwordx4 v[144:145], off
	s_waitcnt vmcnt(6)
	s_barrier
	v_mfma_f32_16x16x32_bf16 v[46:49], v[228:231], v[160:163], v[46:49]
	v_mfma_f32_16x16x32_bf16 v[42:45], v[236:239], v[160:163], v[42:45]
	v_mfma_f32_16x16x32_bf16 v[30:33], v[228:231], v[192:195], v[30:33]
	v_mfma_f32_16x16x32_bf16 v[26:29], v[236:239], v[192:195], v[26:29]
	v_mfma_f32_16x16x32_bf16 v[14:17], v[228:231], v[200:203], v[14:17]
	v_mfma_f32_16x16x32_bf16 v[10:13], v[236:239], v[200:203], v[10:13]
	v_mfma_f32_16x16x32_bf16 v[6:9], v[228:231], v[220:223], v[6:9]
	v_mfma_f32_16x16x32_bf16 v[2:5], v[236:239], v[220:223], v[2:5]
	v_mfma_f32_16x16x32_bf16 v[46:49], v[232:235], v[188:191], v[46:49]
	v_mfma_f32_16x16x32_bf16 v[42:45], v[240:243], v[188:191], v[42:45]
	v_mfma_f32_16x16x32_bf16 v[30:33], v[232:235], v[196:199], v[30:33]
	v_mfma_f32_16x16x32_bf16 v[26:29], v[240:243], v[196:199], v[26:29]
	v_mfma_f32_16x16x32_bf16 v[14:17], v[232:235], v[216:219], v[14:17]
	v_mfma_f32_16x16x32_bf16 v[10:13], v[240:243], v[216:219], v[10:13]
	v_mfma_f32_16x16x32_bf16 v[6:9], v[232:235], v[224:227], v[6:9]
	v_mfma_f32_16x16x32_bf16 v[2:5], v[240:243], v[224:227], v[2:5]
	s_add_i32 s44, s44, 2
	s_add_u32 s68, s68, 0x100
	s_addc_u32 s69, s69, 0
	s_add_u32 s43, s43, 0x100
	s_addc_u32 s92, s92, 0
	s_cmp_gt_u32 s44, 29
	s_barrier
	s_cbranch_scc0 .LBB0_655
	v_lshl_add_u32 v144, s47, 8, v140
	v_lshl_or_b32 v146, s46, 8, v142
	v_ashrrev_i32_e32 v145, 31, v144
	v_cvt_pk_bf16_f32 v126, v126, v127
	v_cvt_pk_bf16_f32 v127, v128, v129
	v_cvt_pk_bf16_f32 v128, v122, v123
	v_lshlrev_b64 v[122:123], 12, v[144:145]
	v_ashrrev_i32_e32 v147, 31, v146
	v_cvt_pk_bf16_f32 v129, v124, v125
	v_lshl_add_u64 v[122:123], s[22:23], 0, v[122:123]
	v_lshlrev_b64 v[124:125], 1, v[146:147]
	v_lshl_add_u64 v[122:123], v[122:123], 0, v[124:125]
	v_cvt_pk_bf16_f32 v110, v110, v111
	v_cvt_pk_bf16_f32 v111, v112, v113
	v_cvt_pk_bf16_f32 v112, v106, v107
	v_cvt_pk_bf16_f32 v113, v108, v109
	global_store_dwordx4 v[122:123], v[110:113], off offset:256
	v_cvt_pk_bf16_f32 v94, v94, v95
	v_cvt_pk_bf16_f32 v95, v96, v97
	v_or_b32_e32 v110, 16, v144
	v_ashrrev_i32_e32 v111, 31, v110
	v_lshlrev_b64 v[110:111], 12, v[110:111]
	v_lshl_add_u64 v[110:111], s[22:23], 0, v[110:111]
	v_lshl_add_u64 v[110:111], v[110:111], 0, v[124:125]
	v_cvt_pk_bf16_f32 v96, v90, v91
	v_cvt_pk_bf16_f32 v97, v92, v93
	global_store_dwordx4 v[110:111], v[94:97], off offset:256
	s_mov_b32 s2, 0x80000
	v_cvt_pk_bf16_f32 v62, v62, v63
	v_or_b32_e32 v94, 32, v144
	v_ashrrev_i32_e32 v95, 31, v94
	v_cvt_pk_bf16_f32 v63, v64, v65
	v_cvt_pk_bf16_f32 v65, v60, v61
	s_mov_b64 s[4:5], 0x80000
	v_add_co_u32_e32 v60, vcc, s2, v122
	v_lshlrev_b64 v[94:95], 12, v[94:95]
	v_cvt_pk_bf16_f32 v64, v58, v59
	v_lshl_add_u64 v[58:59], v[122:123], 0, s[4:5]
	v_addc_co_u32_e32 v61, vcc, 0, v123, vcc
	v_cvt_pk_bf16_f32 v46, v46, v47
	v_cvt_pk_bf16_f32 v47, v48, v49
	v_cvt_pk_bf16_f32 v48, v42, v43
	v_cvt_pk_bf16_f32 v49, v44, v45
	s_mov_b32 s2, 0x90000
	v_lshl_add_u64 v[94:95], s[22:23], 0, v[94:95]
	global_store_dwordx4 v[58:59], v[46:49], off offset:256
	s_mov_b64 s[4:5], 0x90000
	v_lshl_add_u64 v[94:95], v[94:95], 0, v[124:125]
	v_add_co_u32_e32 v48, vcc, s2, v122
	v_cvt_pk_bf16_f32 v78, v78, v79
	v_cvt_pk_bf16_f32 v79, v80, v81
	v_cvt_pk_bf16_f32 v80, v74, v75
	v_cvt_pk_bf16_f32 v81, v76, v77
	v_lshl_add_u64 v[46:47], v[122:123], 0, s[4:5]
	v_addc_co_u32_e32 v49, vcc, 0, v123, vcc
	v_cvt_pk_bf16_f32 v30, v30, v31
	v_cvt_pk_bf16_f32 v31, v32, v33
	v_cvt_pk_bf16_f32 v32, v26, v27
	v_cvt_pk_bf16_f32 v33, v28, v29
	s_mov_b32 s2, 0xa0000
	global_store_dwordx4 v[94:95], v[78:81], off offset:256
	global_store_dwordx4 v[46:47], v[30:33], off offset:256
	s_mov_b64 s[4:5], 0xa0000
	v_or_b32_e32 v78, 48, v144
	v_add_co_u32_e32 v32, vcc, s2, v122
	v_ashrrev_i32_e32 v79, 31, v78
	v_lshl_add_u64 v[30:31], v[122:123], 0, s[4:5]
	v_addc_co_u32_e32 v33, vcc, 0, v123, vcc
	v_cvt_pk_bf16_f32 v14, v14, v15
	v_cvt_pk_bf16_f32 v15, v16, v17
	v_cvt_pk_bf16_f32 v16, v10, v11
	v_cvt_pk_bf16_f32 v17, v12, v13
	s_mov_b32 s2, 0xb0000
	v_lshlrev_b64 v[78:79], 12, v[78:79]
	global_store_dwordx4 v[30:31], v[14:17], off offset:256
	v_lshl_add_u64 v[78:79], s[22:23], 0, v[78:79]
	s_mov_b64 s[4:5], 0xb0000
	v_add_co_u32_e32 v16, vcc, s2, v122
	v_cvt_pk_bf16_f32 v106, v118, v119
	s_nop 0
	v_addc_co_u32_e32 v17, vcc, 0, v123, vcc
	v_cvt_pk_bf16_f32 v107, v120, v121
	v_cvt_pk_bf16_f32 v108, v114, v115
	v_cvt_pk_bf16_f32 v109, v116, v117
	v_cvt_pk_bf16_f32 v90, v102, v103
	v_cvt_pk_bf16_f32 v91, v104, v105
	v_cvt_pk_bf16_f32 v92, v98, v99
	v_cvt_pk_bf16_f32 v93, v100, v101
	v_cvt_pk_bf16_f32 v74, v86, v87
	v_cvt_pk_bf16_f32 v75, v88, v89
	v_cvt_pk_bf16_f32 v76, v82, v83
	v_cvt_pk_bf16_f32 v77, v84, v85
	v_lshl_add_u64 v[78:79], v[78:79], 0, v[124:125]
	v_cvt_pk_bf16_f32 v70, v70, v71
	v_cvt_pk_bf16_f32 v71, v72, v73
	v_cvt_pk_bf16_f32 v72, v66, v67
	v_cvt_pk_bf16_f32 v73, v68, v69
	v_cvt_pk_bf16_f32 v42, v54, v55
	v_cvt_pk_bf16_f32 v43, v56, v57
	v_cvt_pk_bf16_f32 v44, v50, v51
	v_cvt_pk_bf16_f32 v45, v52, v53
	v_cvt_pk_bf16_f32 v26, v38, v39
	v_cvt_pk_bf16_f32 v27, v40, v41
	v_cvt_pk_bf16_f32 v28, v34, v35
	v_cvt_pk_bf16_f32 v29, v36, v37
	v_cvt_pk_bf16_f32 v10, v22, v23
	v_cvt_pk_bf16_f32 v11, v24, v25
	v_cvt_pk_bf16_f32 v12, v18, v19
	v_cvt_pk_bf16_f32 v13, v20, v21
	v_lshl_add_u64 v[14:15], v[122:123], 0, s[4:5]
	v_cvt_pk_bf16_f32 v6, v6, v7
	v_cvt_pk_bf16_f32 v7, v8, v9
	v_cvt_pk_bf16_f32 v8, v2, v3
	v_cvt_pk_bf16_f32 v9, v4, v5
	s_and_b64 vcc, exec, s[0:1]
	s_mov_b32 s46, s42
	s_mov_b32 s47, s54
	s_mov_b64 s[70:71], s[64:65]
	s_mov_b64 s[68:69], s[62:63]
	global_store_dwordx4 v[122:123], v[126:129], off
	global_store_dwordx4 v[110:111], v[106:109], off
	global_store_dwordx4 v[94:95], v[90:93], off
	global_store_dwordx4 v[78:79], v[74:77], off
	global_store_dwordx4 v[78:79], v[70:73], off offset:256
	global_store_dwordx4 v[60:61], v[62:65], off
	global_store_dwordx4 v[48:49], v[42:45], off
	global_store_dwordx4 v[32:33], v[26:29], off
	global_store_dwordx4 v[16:17], v[10:13], off
	global_store_dwordx4 v[14:15], v[6:9], off offset:256
	s_cbranch_vccz .LBB0_652
	v_readlane_b32 s0, v254, 12
	s_waitcnt vmcnt(0)
	v_readlane_b32 s1, v254, 13
	v_readlane_b32 s84, v251, 38
	s_andn2_b64 vcc, exec, s[0:1]
	v_readlane_b32 s85, v251, 39
	v_readlane_b32 s86, v251, 40
	v_readlane_b32 s87, v251, 41
	s_cbranch_vccnz .LBB0_659
	s_barrier

.LBB0_724:
	s_add_u32 s2, s68, 0xfff80080
	s_addc_u32 s17, s69, -1
	s_add_i32 s26, 0, 0x10000
	v_add_u32_e32 v156, s26, v141
	ds_read_b128 v[144:147], v156
	ds_read_b128 v[148:151], v156 offset:1024
	ds_read_b128 v[152:155], v156 offset:2048
	ds_read_b128 v[156:159], v156 offset:3072
	s_cmp_eq_u32 s83, 28
	s_cselect_b32 s73, s55, s17
	s_cselect_b32 s72, s81, s2
	s_cselect_b32 s71, s24, s82
	s_cselect_b32 s70, s25, s43
	v_lshl_add_u64 v[164:165], s[68:69], 0, v[136:137]
	s_add_i32 m0, s58, 0xc000
	ds_read_b128 v[160:163], v143
	ds_read_b128 v[188:191], v143 offset:1024
	ds_read_b128 v[192:195], v143 offset:2048
	ds_read_b128 v[196:199], v143 offset:3072
	ds_read_b128 v[200:203], v143 offset:4096
	ds_read_b128 v[216:219], v143 offset:5120
	ds_read_b128 v[220:223], v143 offset:6144
	ds_read_b128 v[224:227], v143 offset:7168
	global_load_lds_dwordx4 v[164:165], off
	v_lshl_add_u64 v[164:165], s[68:69], 0, v[138:139]
	s_add_i32 m0, s58, 0xe000
	s_nop 0
	global_load_lds_dwordx4 v[164:165], off
	s_waitcnt lgkmcnt(8)
	s_barrier
	s_waitcnt lgkmcnt(7)
	v_mfma_f32_16x16x32_bf16 v[126:129], v[144:147], v[160:163], v[126:129]
	v_mfma_f32_16x16x32_bf16 v[122:125], v[152:155], v[160:163], v[122:125]
	s_waitcnt lgkmcnt(5)
	v_mfma_f32_16x16x32_bf16 v[118:121], v[144:147], v[192:195], v[118:121]
	v_mfma_f32_16x16x32_bf16 v[114:117], v[152:155], v[192:195], v[114:117]
	s_waitcnt lgkmcnt(3)
	v_mfma_f32_16x16x32_bf16 v[102:105], v[144:147], v[200:203], v[102:105]
	v_mfma_f32_16x16x32_bf16 v[98:101], v[152:155], v[200:203], v[98:101]
	s_waitcnt lgkmcnt(1)
	v_mfma_f32_16x16x32_bf16 v[86:89], v[144:147], v[220:223], v[86:89]
	v_mfma_f32_16x16x32_bf16 v[82:85], v[152:155], v[220:223], v[82:85]
	v_mfma_f32_16x16x32_bf16 v[126:129], v[148:151], v[188:191], v[126:129]
	v_mfma_f32_16x16x32_bf16 v[122:125], v[156:159], v[188:191], v[122:125]
	v_mfma_f32_16x16x32_bf16 v[118:121], v[148:151], v[196:199], v[118:121]
	v_mfma_f32_16x16x32_bf16 v[114:117], v[156:159], v[196:199], v[114:117]
	v_mfma_f32_16x16x32_bf16 v[102:105], v[148:151], v[216:219], v[102:105]
	v_mfma_f32_16x16x32_bf16 v[98:101], v[156:159], v[216:219], v[98:101]
	s_waitcnt lgkmcnt(0)
	v_mfma_f32_16x16x32_bf16 v[86:89], v[148:151], v[224:227], v[86:89]
	v_mfma_f32_16x16x32_bf16 v[82:85], v[156:159], v[224:227], v[82:85]
	s_barrier
	s_add_i32 s2, 0, 0x14000
	v_add_u32_e32 v164, s2, v141
	s_add_i32 s17, s26, s3
	ds_read_b128 v[228:231], v164
	ds_read_b128 v[232:235], v164 offset:1024
	ds_read_b128 v[236:239], v164 offset:2048
	ds_read_b128 v[240:243], v164 offset:3072
	v_lshl_add_u64 v[164:165], s[70:71], 0, v[0:1]
	s_mov_b32 m0, s17
	v_lshl_add_u64 v[204:205], s[70:71], 0, v[130:131]
	global_load_lds_dwordx4 v[164:165], off
	s_add_i32 m0, s17, 0x2000
	s_nop 0
	global_load_lds_dwordx4 v[204:205], off
	s_barrier
	s_waitcnt lgkmcnt(3)
	v_mfma_f32_16x16x32_bf16 v[110:113], v[228:231], v[160:163], v[110:113]
	s_waitcnt lgkmcnt(1)
	v_mfma_f32_16x16x32_bf16 v[106:109], v[236:239], v[160:163], v[106:109]
	v_mfma_f32_16x16x32_bf16 v[94:97], v[228:231], v[192:195], v[94:97]
	v_mfma_f32_16x16x32_bf16 v[90:93], v[236:239], v[192:195], v[90:93]
	v_mfma_f32_16x16x32_bf16 v[78:81], v[228:231], v[200:203], v[78:81]
	v_mfma_f32_16x16x32_bf16 v[74:77], v[236:239], v[200:203], v[74:77]
	v_mfma_f32_16x16x32_bf16 v[70:73], v[228:231], v[220:223], v[70:73]
	v_mfma_f32_16x16x32_bf16 v[66:69], v[236:239], v[220:223], v[66:69]
	v_mfma_f32_16x16x32_bf16 v[110:113], v[232:235], v[188:191], v[110:113]
	s_waitcnt lgkmcnt(0)
	v_mfma_f32_16x16x32_bf16 v[106:109], v[240:243], v[188:191], v[106:109]
	v_mfma_f32_16x16x32_bf16 v[94:97], v[232:235], v[196:199], v[94:97]
	v_mfma_f32_16x16x32_bf16 v[90:93], v[240:243], v[196:199], v[90:93]
	v_mfma_f32_16x16x32_bf16 v[78:81], v[232:235], v[216:219], v[78:81]
	v_mfma_f32_16x16x32_bf16 v[74:77], v[240:243], v[216:219], v[74:77]
	v_mfma_f32_16x16x32_bf16 v[70:73], v[232:235], v[224:227], v[70:73]
	v_mfma_f32_16x16x32_bf16 v[66:69], v[240:243], v[224:227], v[66:69]
	s_mov_b32 m0, s58
	v_lshl_add_u64 v[244:245], s[72:73], 0, v[134:135]
	s_barrier
	ds_read_b128 v[160:163], v143 offset:16384
	ds_read_b128 v[188:191], v143 offset:17408
	ds_read_b128 v[192:195], v143 offset:18432
	ds_read_b128 v[196:199], v143 offset:19456
	ds_read_b128 v[200:203], v143 offset:20480
	ds_read_b128 v[216:219], v143 offset:21504
	ds_read_b128 v[220:223], v143 offset:22528
	ds_read_b128 v[224:227], v143 offset:23552
	global_load_lds_dwordx4 v[244:245], off
	v_lshl_add_u64 v[246:247], s[72:73], 0, v[132:133]
	s_mov_b32 m0, s74
	s_nop 0
	global_load_lds_dwordx4 v[246:247], off
	s_barrier
	s_waitcnt lgkmcnt(7)
	v_mfma_f32_16x16x32_bf16 v[62:65], v[144:147], v[160:163], v[62:65]
	v_mfma_f32_16x16x32_bf16 v[58:61], v[152:155], v[160:163], v[58:61]
	s_waitcnt lgkmcnt(5)
	v_mfma_f32_16x16x32_bf16 v[54:57], v[144:147], v[192:195], v[54:57]
	v_mfma_f32_16x16x32_bf16 v[50:53], v[152:155], v[192:195], v[50:53]
	s_waitcnt lgkmcnt(3)
	v_mfma_f32_16x16x32_bf16 v[38:41], v[144:147], v[200:203], v[38:41]
	v_mfma_f32_16x16x32_bf16 v[34:37], v[152:155], v[200:203], v[34:37]
	s_waitcnt lgkmcnt(1)
	v_mfma_f32_16x16x32_bf16 v[22:25], v[144:147], v[220:223], v[22:25]
	v_mfma_f32_16x16x32_bf16 v[18:21], v[152:155], v[220:223], v[18:21]
	v_mfma_f32_16x16x32_bf16 v[62:65], v[148:151], v[188:191], v[62:65]
	v_mfma_f32_16x16x32_bf16 v[58:61], v[156:159], v[188:191], v[58:61]
	v_mfma_f32_16x16x32_bf16 v[54:57], v[148:151], v[196:199], v[54:57]
	v_mfma_f32_16x16x32_bf16 v[50:53], v[156:159], v[196:199], v[50:53]
	v_mfma_f32_16x16x32_bf16 v[38:41], v[148:151], v[216:219], v[38:41]
	v_mfma_f32_16x16x32_bf16 v[34:37], v[156:159], v[216:219], v[34:37]
	s_waitcnt lgkmcnt(0)
	v_mfma_f32_16x16x32_bf16 v[22:25], v[148:151], v[224:227], v[22:25]
	v_mfma_f32_16x16x32_bf16 v[18:21], v[156:159], v[224:227], v[18:21]
	s_barrier
	s_add_u32 s44, s70, 0x80000
	s_addc_u32 s45, s71, 0
	s_add_i32 s2, s2, s3
	v_lshl_add_u64 v[144:145], s[44:45], 0, v[0:1]
	s_mov_b32 m0, s2
	s_nop 0
	global_load_lds_dwordx4 v[144:145], off
	v_lshl_add_u64 v[144:145], s[44:45], 0, v[130:131]
	s_add_i32 m0, s2, 0x2000
	s_nop 0
	global_load_lds_dwordx4 v[144:145], off
	s_waitcnt vmcnt(6)
	s_barrier
	v_mfma_f32_16x16x32_bf16 v[46:49], v[228:231], v[160:163], v[46:49]
	v_mfma_f32_16x16x32_bf16 v[42:45], v[236:239], v[160:163], v[42:45]
	v_mfma_f32_16x16x32_bf16 v[30:33], v[228:231], v[192:195], v[30:33]
	v_mfma_f32_16x16x32_bf16 v[26:29], v[236:239], v[192:195], v[26:29]
	v_mfma_f32_16x16x32_bf16 v[14:17], v[228:231], v[200:203], v[14:17]
	v_mfma_f32_16x16x32_bf16 v[10:13], v[236:239], v[200:203], v[10:13]
	v_mfma_f32_16x16x32_bf16 v[6:9], v[228:231], v[220:223], v[6:9]
	v_mfma_f32_16x16x32_bf16 v[2:5], v[236:239], v[220:223], v[2:5]
	v_mfma_f32_16x16x32_bf16 v[46:49], v[232:235], v[188:191], v[46:49]
	v_mfma_f32_16x16x32_bf16 v[42:45], v[240:243], v[188:191], v[42:45]
	v_mfma_f32_16x16x32_bf16 v[30:33], v[232:235], v[196:199], v[30:33]
	v_mfma_f32_16x16x32_bf16 v[26:29], v[240:243], v[196:199], v[26:29]
	v_mfma_f32_16x16x32_bf16 v[14:17], v[232:235], v[216:219], v[14:17]
	v_mfma_f32_16x16x32_bf16 v[10:13], v[240:243], v[216:219], v[10:13]
	v_mfma_f32_16x16x32_bf16 v[6:9], v[232:235], v[224:227], v[6:9]
	v_mfma_f32_16x16x32_bf16 v[2:5], v[240:243], v[224:227], v[2:5]
	s_add_i32 s2, 0, 0x18000
	v_add_u32_e32 v156, s2, v141
	s_barrier
	ds_read_b128 v[144:147], v156
	ds_read_b128 v[148:151], v156 offset:1024
	ds_read_b128 v[152:155], v156 offset:2048
	ds_read_b128 v[156:159], v156 offset:3072
	s_add_u32 s44, s72, 0x80000
	s_addc_u32 s45, s73, 0
	s_mov_b32 m0, s75
	v_lshl_add_u64 v[228:229], s[44:45], 0, v[134:135]
	ds_read_b128 v[160:163], v143 offset:32768
	ds_read_b128 v[188:191], v143 offset:33792
	ds_read_b128 v[192:195], v143 offset:34816
	ds_read_b128 v[196:199], v143 offset:35840
	ds_read_b128 v[200:203], v143 offset:36864
	ds_read_b128 v[216:219], v143 offset:37888
	ds_read_b128 v[220:223], v143 offset:38912
	ds_read_b128 v[224:227], v143 offset:39936
	global_load_lds_dwordx4 v[228:229], off
	v_lshl_add_u64 v[228:229], s[44:45], 0, v[132:133]
	s_mov_b32 m0, s77
	s_nop 0
	global_load_lds_dwordx4 v[228:229], off
	s_waitcnt lgkmcnt(8)
	s_barrier
	s_waitcnt lgkmcnt(7)
	v_mfma_f32_16x16x32_bf16 v[126:129], v[144:147], v[160:163], v[126:129]
	v_mfma_f32_16x16x32_bf16 v[122:125], v[152:155], v[160:163], v[122:125]
	s_waitcnt lgkmcnt(5)
	v_mfma_f32_16x16x32_bf16 v[118:121], v[144:147], v[192:195], v[118:121]
	v_mfma_f32_16x16x32_bf16 v[114:117], v[152:155], v[192:195], v[114:117]
	s_waitcnt lgkmcnt(3)
	v_mfma_f32_16x16x32_bf16 v[102:105], v[144:147], v[200:203], v[102:105]
	v_mfma_f32_16x16x32_bf16 v[98:101], v[152:155], v[200:203], v[98:101]
	s_waitcnt lgkmcnt(1)
	v_mfma_f32_16x16x32_bf16 v[86:89], v[144:147], v[220:223], v[86:89]
	v_mfma_f32_16x16x32_bf16 v[82:85], v[152:155], v[220:223], v[82:85]
	v_mfma_f32_16x16x32_bf16 v[126:129], v[148:151], v[188:191], v[126:129]
	v_mfma_f32_16x16x32_bf16 v[122:125], v[156:159], v[188:191], v[122:125]
	v_mfma_f32_16x16x32_bf16 v[118:121], v[148:151], v[196:199], v[118:121]
	v_mfma_f32_16x16x32_bf16 v[114:117], v[156:159], v[196:199], v[114:117]
	v_mfma_f32_16x16x32_bf16 v[102:105], v[148:151], v[216:219], v[102:105]
	v_mfma_f32_16x16x32_bf16 v[98:101], v[156:159], v[216:219], v[98:101]
	s_waitcnt lgkmcnt(0)
	v_mfma_f32_16x16x32_bf16 v[86:89], v[148:151], v[224:227], v[86:89]
	v_mfma_f32_16x16x32_bf16 v[82:85], v[156:159], v[224:227], v[82:85]
	s_barrier
	s_add_i32 s17, 0, 0x1c000
	s_add_i32 s2, s2, s3
	v_add_u32_e32 v206, s17, v141
	v_lshl_add_u64 v[164:165], v[164:165], 0, s[28:29]
	s_mov_b32 m0, s2
	ds_read_b128 v[228:231], v206
	ds_read_b128 v[232:235], v206 offset:1024
	ds_read_b128 v[236:239], v206 offset:2048
	ds_read_b128 v[240:243], v206 offset:3072
	global_load_lds_dwordx4 v[164:165], off
	v_lshl_add_u64 v[164:165], v[204:205], 0, s[28:29]
	s_add_i32 m0, s2, 0x2000
	s_nop 0
	global_load_lds_dwordx4 v[164:165], off
	s_barrier
	s_waitcnt lgkmcnt(3)
	v_mfma_f32_16x16x32_bf16 v[110:113], v[228:231], v[160:163], v[110:113]
	s_waitcnt lgkmcnt(1)
	v_mfma_f32_16x16x32_bf16 v[106:109], v[236:239], v[160:163], v[106:109]
	v_mfma_f32_16x16x32_bf16 v[94:97], v[228:231], v[192:195], v[94:97]
	v_mfma_f32_16x16x32_bf16 v[90:93], v[236:239], v[192:195], v[90:93]
	v_mfma_f32_16x16x32_bf16 v[78:81], v[228:231], v[200:203], v[78:81]
	v_mfma_f32_16x16x32_bf16 v[74:77], v[236:239], v[200:203], v[74:77]
	v_mfma_f32_16x16x32_bf16 v[70:73], v[228:231], v[220:223], v[70:73]
	v_mfma_f32_16x16x32_bf16 v[66:69], v[236:239], v[220:223], v[66:69]
	v_mfma_f32_16x16x32_bf16 v[110:113], v[232:235], v[188:191], v[110:113]
	s_waitcnt lgkmcnt(0)
	v_mfma_f32_16x16x32_bf16 v[106:109], v[240:243], v[188:191], v[106:109]
	v_mfma_f32_16x16x32_bf16 v[94:97], v[232:235], v[196:199], v[94:97]
	v_mfma_f32_16x16x32_bf16 v[90:93], v[240:243], v[196:199], v[90:93]
	v_mfma_f32_16x16x32_bf16 v[78:81], v[232:235], v[216:219], v[78:81]
	v_mfma_f32_16x16x32_bf16 v[74:77], v[240:243], v[216:219], v[74:77]
	v_mfma_f32_16x16x32_bf16 v[70:73], v[232:235], v[224:227], v[70:73]
	v_mfma_f32_16x16x32_bf16 v[66:69], v[240:243], v[224:227], v[66:69]
	s_mov_b32 m0, s78
	v_lshl_add_u64 v[164:165], v[244:245], 0, s[28:29]
	s_barrier
	ds_read_b128 v[160:163], v143 offset:49152
	ds_read_b128 v[188:191], v143 offset:50176
	ds_read_b128 v[192:195], v143 offset:51200
	ds_read_b128 v[196:199], v143 offset:52224
	ds_read_b128 v[200:203], v143 offset:53248
	ds_read_b128 v[216:219], v143 offset:54272
	ds_read_b128 v[220:223], v143 offset:55296
	ds_read_b128 v[224:227], v143 offset:56320
	global_load_lds_dwordx4 v[164:165], off
	v_lshl_add_u64 v[164:165], v[246:247], 0, s[28:29]
	s_mov_b32 m0, s79
	s_nop 0
	global_load_lds_dwordx4 v[164:165], off
	s_barrier
	s_waitcnt lgkmcnt(7)
	v_mfma_f32_16x16x32_bf16 v[62:65], v[144:147], v[160:163], v[62:65]
	v_mfma_f32_16x16x32_bf16 v[58:61], v[152:155], v[160:163], v[58:61]
	s_waitcnt lgkmcnt(5)
	v_mfma_f32_16x16x32_bf16 v[54:57], v[144:147], v[192:195], v[54:57]
	v_mfma_f32_16x16x32_bf16 v[50:53], v[152:155], v[192:195], v[50:53]
	s_waitcnt lgkmcnt(3)
	v_mfma_f32_16x16x32_bf16 v[38:41], v[144:147], v[200:203], v[38:41]
	v_mfma_f32_16x16x32_bf16 v[34:37], v[152:155], v[200:203], v[34:37]
	s_waitcnt lgkmcnt(1)
	v_mfma_f32_16x16x32_bf16 v[22:25], v[144:147], v[220:223], v[22:25]
	v_mfma_f32_16x16x32_bf16 v[18:21], v[152:155], v[220:223], v[18:21]
	v_mfma_f32_16x16x32_bf16 v[62:65], v[148:151], v[188:191], v[62:65]
	v_mfma_f32_16x16x32_bf16 v[58:61], v[156:159], v[188:191], v[58:61]
	v_mfma_f32_16x16x32_bf16 v[54:57], v[148:151], v[196:199], v[54:57]
	v_mfma_f32_16x16x32_bf16 v[50:53], v[156:159], v[196:199], v[50:53]
	v_mfma_f32_16x16x32_bf16 v[38:41], v[148:151], v[216:219], v[38:41]
	v_mfma_f32_16x16x32_bf16 v[34:37], v[156:159], v[216:219], v[34:37]
	s_waitcnt lgkmcnt(0)
	v_mfma_f32_16x16x32_bf16 v[22:25], v[148:151], v[224:227], v[22:25]
	v_mfma_f32_16x16x32_bf16 v[18:21], v[156:159], v[224:227], v[18:21]
	s_barrier
	s_add_u32 s44, s70, 0x80080
	s_addc_u32 s45, s71, 0
	s_add_i32 s2, s17, s3
	v_lshl_add_u64 v[144:145], s[44:45], 0, v[0:1]
	s_mov_b32 m0, s2
	s_nop 0
	global_load_lds_dwordx4 v[144:145], off
	v_lshl_add_u64 v[144:145], s[44:45], 0, v[130:131]
	s_add_i32 m0, s2, 0x2000
	s_nop 0
	global_load_lds_dwordx4 v[144:145], off
	s_waitcnt vmcnt(6)
	s_barrier
	v_mfma_f32_16x16x32_bf16 v[46:49], v[228:231], v[160:163], v[46:49]
	v_mfma_f32_16x16x32_bf16 v[42:45], v[236:239], v[160:163], v[42:45]
	v_mfma_f32_16x16x32_bf16 v[30:33], v[228:231], v[192:195], v[30:33]
	v_mfma_f32_16x16x32_bf16 v[26:29], v[236:239], v[192:195], v[26:29]
	v_mfma_f32_16x16x32_bf16 v[14:17], v[228:231], v[200:203], v[14:17]
	v_mfma_f32_16x16x32_bf16 v[10:13], v[236:239], v[200:203], v[10:13]
	v_mfma_f32_16x16x32_bf16 v[6:9], v[228:231], v[220:223], v[6:9]
	v_mfma_f32_16x16x32_bf16 v[2:5], v[236:239], v[220:223], v[2:5]
	v_mfma_f32_16x16x32_bf16 v[46:49], v[232:235], v[188:191], v[46:49]
	v_mfma_f32_16x16x32_bf16 v[42:45], v[240:243], v[188:191], v[42:45]
	v_mfma_f32_16x16x32_bf16 v[30:33], v[232:235], v[196:199], v[30:33]
	v_mfma_f32_16x16x32_bf16 v[26:29], v[240:243], v[196:199], v[26:29]
	v_mfma_f32_16x16x32_bf16 v[14:17], v[232:235], v[216:219], v[14:17]
	v_mfma_f32_16x16x32_bf16 v[10:13], v[240:243], v[216:219], v[10:13]
	v_mfma_f32_16x16x32_bf16 v[6:9], v[232:235], v[224:227], v[6:9]
	v_mfma_f32_16x16x32_bf16 v[2:5], v[240:243], v[224:227], v[2:5]
	s_add_i32 s83, s83, 2
	s_add_u32 s68, s68, 0x100
	s_addc_u32 s69, s69, 0
	s_add_u32 s43, s43, 0x100
	s_addc_u32 s82, s82, 0
	s_cmp_gt_u32 s83, 29
	s_barrier
	s_cbranch_scc0 .LBB0_724
	v_lshl_add_u32 v146, s47, 8, v140
	v_lshl_or_b32 v144, s46, 8, v142
	v_cvt_pk_bf16_f32 v126, v126, v127
	v_cvt_pk_bf16_f32 v127, v128, v129
	v_cvt_pk_bf16_f32 v128, v122, v123
	v_mov_b64_e32 v[122:123], s[22:23]
	v_ashrrev_i32_e32 v145, 31, v144
	v_cvt_pk_bf16_f32 v70, v70, v71
	v_cvt_pk_bf16_f32 v71, v72, v73
	v_cvt_pk_bf16_f32 v72, v66, v67
	v_add_u32_e32 v66, 0x80, v146
	v_cvt_pk_bf16_f32 v129, v124, v125
	v_mad_i64_i32 v[124:125], s[24:25], v146, s48, v[122:123]
	v_lshlrev_b64 v[144:145], 1, v[144:145]
	v_cvt_pk_bf16_f32 v62, v62, v63
	v_cvt_pk_bf16_f32 v63, v64, v65
	v_cvt_pk_bf16_f32 v64, v58, v59
	v_mad_i64_i32 v[58:59], s[24:25], v66, s48, v[122:123]
	v_lshl_add_u64 v[124:125], v[124:125], 0, v[144:145]
	v_cvt_pk_bf16_f32 v110, v110, v111
	v_cvt_pk_bf16_f32 v111, v112, v113
	v_cvt_pk_bf16_f32 v112, v106, v107
	v_cvt_pk_bf16_f32 v113, v108, v109
	v_lshl_add_u64 v[58:59], v[58:59], 0, v[144:145]
	v_cvt_pk_bf16_f32 v46, v46, v47
	v_cvt_pk_bf16_f32 v47, v48, v49
	v_cvt_pk_bf16_f32 v48, v42, v43
	v_cvt_pk_bf16_f32 v49, v44, v45
	global_store_dwordx4 v[124:125], v[110:113], off offset:256
	global_store_dwordx4 v[58:59], v[46:49], off offset:256
	v_cvt_pk_bf16_f32 v94, v94, v95
	v_or_b32_e32 v110, 16, v146
	v_add_u32_e32 v46, 0x90, v146
	v_mad_i64_i32 v[110:111], s[24:25], v110, s48, v[122:123]
	v_mad_i64_i32 v[46:47], s[24:25], v46, s48, v[122:123]
	v_lshl_add_u64 v[110:111], v[110:111], 0, v[144:145]
	v_cvt_pk_bf16_f32 v95, v96, v97
	v_cvt_pk_bf16_f32 v96, v90, v91
	v_cvt_pk_bf16_f32 v97, v92, v93
	v_lshl_add_u64 v[46:47], v[46:47], 0, v[144:145]
	v_cvt_pk_bf16_f32 v30, v30, v31
	v_cvt_pk_bf16_f32 v31, v32, v33
	v_cvt_pk_bf16_f32 v32, v26, v27
	v_cvt_pk_bf16_f32 v33, v28, v29
	global_store_dwordx4 v[110:111], v[94:97], off offset:256
	global_store_dwordx4 v[46:47], v[30:33], off offset:256
	v_cvt_pk_bf16_f32 v78, v78, v79
	v_or_b32_e32 v94, 32, v146
	v_add_u32_e32 v30, 0xa0, v146
	v_mad_i64_i32 v[94:95], s[24:25], v94, s48, v[122:123]
	v_mad_i64_i32 v[30:31], s[24:25], v30, s48, v[122:123]
	v_lshl_add_u64 v[94:95], v[94:95], 0, v[144:145]
	v_cvt_pk_bf16_f32 v79, v80, v81
	v_cvt_pk_bf16_f32 v80, v74, v75
	v_cvt_pk_bf16_f32 v81, v76, v77
	v_lshl_add_u64 v[30:31], v[30:31], 0, v[144:145]
	v_cvt_pk_bf16_f32 v14, v14, v15
	v_cvt_pk_bf16_f32 v15, v16, v17
	v_cvt_pk_bf16_f32 v16, v10, v11
	v_cvt_pk_bf16_f32 v17, v12, v13
	global_store_dwordx4 v[94:95], v[78:81], off offset:256
	global_store_dwordx4 v[30:31], v[14:17], off offset:256
	v_cvt_pk_bf16_f32 v106, v118, v119
	v_or_b32_e32 v78, 48, v146
	v_add_u32_e32 v14, 0xb0, v146
	v_mad_i64_i32 v[78:79], s[24:25], v78, s48, v[122:123]
	v_mad_i64_i32 v[14:15], s[24:25], v14, s48, v[122:123]
	v_cvt_pk_bf16_f32 v107, v120, v121
	v_cvt_pk_bf16_f32 v108, v114, v115
	v_cvt_pk_bf16_f32 v109, v116, v117
	v_cvt_pk_bf16_f32 v90, v102, v103
	v_cvt_pk_bf16_f32 v91, v104, v105
	v_cvt_pk_bf16_f32 v92, v98, v99
	v_cvt_pk_bf16_f32 v93, v100, v101
	v_cvt_pk_bf16_f32 v74, v86, v87
	v_cvt_pk_bf16_f32 v75, v88, v89
	v_cvt_pk_bf16_f32 v76, v82, v83
	v_cvt_pk_bf16_f32 v77, v84, v85
	v_lshl_add_u64 v[78:79], v[78:79], 0, v[144:145]
	v_cvt_pk_bf16_f32 v73, v68, v69
	v_cvt_pk_bf16_f32 v65, v60, v61
	v_cvt_pk_bf16_f32 v42, v54, v55
	v_cvt_pk_bf16_f32 v43, v56, v57
	v_cvt_pk_bf16_f32 v44, v50, v51
	v_cvt_pk_bf16_f32 v45, v52, v53
	v_cvt_pk_bf16_f32 v26, v38, v39
	v_cvt_pk_bf16_f32 v27, v40, v41
	v_cvt_pk_bf16_f32 v28, v34, v35
	v_cvt_pk_bf16_f32 v29, v36, v37
	v_cvt_pk_bf16_f32 v10, v22, v23
	v_cvt_pk_bf16_f32 v11, v24, v25
	v_cvt_pk_bf16_f32 v12, v18, v19
	v_cvt_pk_bf16_f32 v13, v20, v21
	v_lshl_add_u64 v[14:15], v[14:15], 0, v[144:145]
	v_cvt_pk_bf16_f32 v6, v6, v7
	v_cvt_pk_bf16_f32 v7, v8, v9
	v_cvt_pk_bf16_f32 v8, v2, v3
	v_cvt_pk_bf16_f32 v9, v4, v5
	s_and_b64 vcc, exec, s[0:1]
	s_mov_b32 s46, s42
	s_mov_b32 s47, s54
	s_mov_b64 s[70:71], s[64:65]
	s_mov_b64 s[68:69], s[62:63]
	global_store_dwordx4 v[124:125], v[126:129], off
	global_store_dwordx4 v[110:111], v[106:109], off
	global_store_dwordx4 v[94:95], v[90:93], off
	global_store_dwordx4 v[78:79], v[74:77], off
	global_store_dwordx4 v[78:79], v[70:73], off offset:256
	global_store_dwordx4 v[58:59], v[62:65], off
	global_store_dwordx4 v[46:47], v[42:45], off
	global_store_dwordx4 v[30:31], v[26:29], off
	global_store_dwordx4 v[14:15], v[10:13], off
	global_store_dwordx4 v[14:15], v[6:9], off offset:256
	s_cbranch_vccz .LBB0_721
	v_readlane_b32 s0, v254, 12
	s_waitcnt vmcnt(0)
	v_readlane_b32 s1, v254, 13
	s_andn2_b64 vcc, exec, s[0:1]
	s_cbranch_vccnz .LBB0_728
	s_barrier

.LBB0_977:
	s_add_u32 s2, s70, 0xfffc0080
	s_addc_u32 s17, s71, -1
	s_add_i32 s26, 0, 0x10000
	v_add_u32_e32 v152, s26, v163
	ds_read_b128 v[130:133], v152
	ds_read_b128 v[134:137], v152 offset:1024
	ds_read_b128 v[148:151], v152 offset:2048
	ds_read_b128 v[152:155], v152 offset:3072
	s_cmp_eq_u32 s44, 12
	s_cselect_b32 s75, s41, s17
	s_cselect_b32 s74, s24, s2
	s_cselect_b32 s73, s25, vcc_hi
	s_cselect_b32 s72, s93, vcc_lo
	v_lshl_add_u64 v[160:161], s[70:71], 0, v[144:145]
	s_add_i32 m0, s58, 0xc000
	ds_read_b128 v[156:159], v165
	ds_read_b128 v[188:191], v165 offset:1024
	ds_read_b128 v[192:195], v165 offset:2048
	ds_read_b128 v[196:199], v165 offset:3072
	ds_read_b128 v[200:203], v165 offset:4096
	ds_read_b128 v[216:219], v165 offset:5120
	ds_read_b128 v[220:223], v165 offset:6144
	ds_read_b128 v[224:227], v165 offset:7168
	global_load_lds_dwordx4 v[160:161], off
	v_lshl_add_u64 v[160:161], s[70:71], 0, v[146:147]
	s_add_i32 m0, s58, 0xe000
	s_nop 0
	global_load_lds_dwordx4 v[160:161], off
	s_waitcnt lgkmcnt(8)
	s_barrier
	s_waitcnt lgkmcnt(7)
	v_mfma_f32_16x16x32_bf16 v[126:129], v[130:133], v[156:159], v[126:129]
	v_mfma_f32_16x16x32_bf16 v[122:125], v[148:151], v[156:159], v[122:125]
	s_waitcnt lgkmcnt(5)
	v_mfma_f32_16x16x32_bf16 v[110:113], v[130:133], v[192:195], v[110:113]
	v_mfma_f32_16x16x32_bf16 v[106:109], v[148:151], v[192:195], v[106:109]
	s_waitcnt lgkmcnt(3)
	v_mfma_f32_16x16x32_bf16 v[94:97], v[130:133], v[200:203], v[94:97]
	v_mfma_f32_16x16x32_bf16 v[90:93], v[148:151], v[200:203], v[90:93]
	s_waitcnt lgkmcnt(1)
	v_mfma_f32_16x16x32_bf16 v[78:81], v[130:133], v[220:223], v[78:81]
	v_mfma_f32_16x16x32_bf16 v[74:77], v[148:151], v[220:223], v[74:77]
	v_mfma_f32_16x16x32_bf16 v[126:129], v[134:137], v[188:191], v[126:129]
	v_mfma_f32_16x16x32_bf16 v[122:125], v[152:155], v[188:191], v[122:125]
	v_mfma_f32_16x16x32_bf16 v[110:113], v[134:137], v[196:199], v[110:113]
	v_mfma_f32_16x16x32_bf16 v[106:109], v[152:155], v[196:199], v[106:109]
	v_mfma_f32_16x16x32_bf16 v[94:97], v[134:137], v[216:219], v[94:97]
	v_mfma_f32_16x16x32_bf16 v[90:93], v[152:155], v[216:219], v[90:93]
	s_waitcnt lgkmcnt(0)
	v_mfma_f32_16x16x32_bf16 v[78:81], v[134:137], v[224:227], v[78:81]
	v_mfma_f32_16x16x32_bf16 v[74:77], v[152:155], v[224:227], v[74:77]
	s_barrier
	s_add_i32 s2, 0, 0x14000
	v_add_u32_e32 v160, s2, v163
	s_add_i32 s17, s26, s3
	ds_read_b128 v[228:231], v160
	ds_read_b128 v[232:235], v160 offset:1024
	ds_read_b128 v[236:239], v160 offset:2048
	ds_read_b128 v[240:243], v160 offset:3072
	v_lshl_add_u64 v[160:161], s[72:73], 0, v[0:1]
	s_mov_b32 m0, s17
	v_lshl_add_u64 v[204:205], s[72:73], 0, v[138:139]
	global_load_lds_dwordx4 v[160:161], off
	s_add_i32 m0, s17, 0x2000
	s_nop 0
	global_load_lds_dwordx4 v[204:205], off
	s_barrier
	s_waitcnt lgkmcnt(3)
	v_mfma_f32_16x16x32_bf16 v[118:121], v[228:231], v[156:159], v[118:121]
	s_waitcnt lgkmcnt(1)
	v_mfma_f32_16x16x32_bf16 v[114:117], v[236:239], v[156:159], v[114:117]
	v_mfma_f32_16x16x32_bf16 v[102:105], v[228:231], v[192:195], v[102:105]
	v_mfma_f32_16x16x32_bf16 v[98:101], v[236:239], v[192:195], v[98:101]
	v_mfma_f32_16x16x32_bf16 v[86:89], v[228:231], v[200:203], v[86:89]
	v_mfma_f32_16x16x32_bf16 v[82:85], v[236:239], v[200:203], v[82:85]
	v_mfma_f32_16x16x32_bf16 v[70:73], v[228:231], v[220:223], v[70:73]
	v_mfma_f32_16x16x32_bf16 v[66:69], v[236:239], v[220:223], v[66:69]
	v_mfma_f32_16x16x32_bf16 v[118:121], v[232:235], v[188:191], v[118:121]
	s_waitcnt lgkmcnt(0)
	v_mfma_f32_16x16x32_bf16 v[114:117], v[240:243], v[188:191], v[114:117]
	v_mfma_f32_16x16x32_bf16 v[102:105], v[232:235], v[196:199], v[102:105]
	v_mfma_f32_16x16x32_bf16 v[98:101], v[240:243], v[196:199], v[98:101]
	v_mfma_f32_16x16x32_bf16 v[86:89], v[232:235], v[216:219], v[86:89]
	v_mfma_f32_16x16x32_bf16 v[82:85], v[240:243], v[216:219], v[82:85]
	v_mfma_f32_16x16x32_bf16 v[70:73], v[232:235], v[224:227], v[70:73]
	v_mfma_f32_16x16x32_bf16 v[66:69], v[240:243], v[224:227], v[66:69]
	s_mov_b32 m0, s58
	v_lshl_add_u64 v[244:245], s[74:75], 0, v[142:143]
	s_barrier
	ds_read_b128 v[156:159], v165 offset:16384
	ds_read_b128 v[188:191], v165 offset:17408
	ds_read_b128 v[192:195], v165 offset:18432
	ds_read_b128 v[196:199], v165 offset:19456
	ds_read_b128 v[200:203], v165 offset:20480
	ds_read_b128 v[216:219], v165 offset:21504
	ds_read_b128 v[220:223], v165 offset:22528
	ds_read_b128 v[224:227], v165 offset:23552
	global_load_lds_dwordx4 v[244:245], off
	v_lshl_add_u64 v[246:247], s[74:75], 0, v[140:141]
	s_mov_b32 m0, s76
	s_nop 0
	global_load_lds_dwordx4 v[246:247], off
	s_barrier
	s_waitcnt lgkmcnt(7)
	v_mfma_f32_16x16x32_bf16 v[62:65], v[130:133], v[156:159], v[62:65]
	v_mfma_f32_16x16x32_bf16 v[58:61], v[148:151], v[156:159], v[58:61]
	s_waitcnt lgkmcnt(5)
	v_mfma_f32_16x16x32_bf16 v[46:49], v[130:133], v[192:195], v[46:49]
	v_mfma_f32_16x16x32_bf16 v[42:45], v[148:151], v[192:195], v[42:45]
	s_waitcnt lgkmcnt(3)
	v_mfma_f32_16x16x32_bf16 v[30:33], v[130:133], v[200:203], v[30:33]
	v_mfma_f32_16x16x32_bf16 v[26:29], v[148:151], v[200:203], v[26:29]
	s_waitcnt lgkmcnt(1)
	v_mfma_f32_16x16x32_bf16 v[14:17], v[130:133], v[220:223], v[14:17]
	v_mfma_f32_16x16x32_bf16 v[10:13], v[148:151], v[220:223], v[10:13]
	v_mfma_f32_16x16x32_bf16 v[62:65], v[134:137], v[188:191], v[62:65]
	v_mfma_f32_16x16x32_bf16 v[58:61], v[152:155], v[188:191], v[58:61]
	v_mfma_f32_16x16x32_bf16 v[46:49], v[134:137], v[196:199], v[46:49]
	v_mfma_f32_16x16x32_bf16 v[42:45], v[152:155], v[196:199], v[42:45]
	v_mfma_f32_16x16x32_bf16 v[30:33], v[134:137], v[216:219], v[30:33]
	v_mfma_f32_16x16x32_bf16 v[26:29], v[152:155], v[216:219], v[26:29]
	s_waitcnt lgkmcnt(0)
	v_mfma_f32_16x16x32_bf16 v[14:17], v[134:137], v[224:227], v[14:17]
	v_mfma_f32_16x16x32_bf16 v[10:13], v[152:155], v[224:227], v[10:13]
	s_barrier
	s_add_u32 s26, s72, 0x40000
	s_addc_u32 s27, s73, 0
	s_add_i32 s2, s2, s3
	v_lshl_add_u64 v[130:131], s[26:27], 0, v[0:1]
	s_mov_b32 m0, s2
	s_nop 0
	global_load_lds_dwordx4 v[130:131], off
	v_lshl_add_u64 v[130:131], s[26:27], 0, v[138:139]
	s_add_i32 m0, s2, 0x2000
	s_nop 0
	global_load_lds_dwordx4 v[130:131], off
	s_waitcnt vmcnt(6)
	s_barrier
	v_mfma_f32_16x16x32_bf16 v[54:57], v[228:231], v[156:159], v[54:57]
	v_mfma_f32_16x16x32_bf16 v[50:53], v[236:239], v[156:159], v[50:53]
	v_mfma_f32_16x16x32_bf16 v[38:41], v[228:231], v[192:195], v[38:41]
	v_mfma_f32_16x16x32_bf16 v[34:37], v[236:239], v[192:195], v[34:37]
	v_mfma_f32_16x16x32_bf16 v[22:25], v[228:231], v[200:203], v[22:25]
	v_mfma_f32_16x16x32_bf16 v[18:21], v[236:239], v[200:203], v[18:21]
	v_mfma_f32_16x16x32_bf16 v[6:9], v[228:231], v[220:223], v[6:9]
	v_mfma_f32_16x16x32_bf16 v[2:5], v[236:239], v[220:223], v[2:5]
	v_mfma_f32_16x16x32_bf16 v[54:57], v[232:235], v[188:191], v[54:57]
	v_mfma_f32_16x16x32_bf16 v[50:53], v[240:243], v[188:191], v[50:53]
	v_mfma_f32_16x16x32_bf16 v[38:41], v[232:235], v[196:199], v[38:41]
	v_mfma_f32_16x16x32_bf16 v[34:37], v[240:243], v[196:199], v[34:37]
	v_mfma_f32_16x16x32_bf16 v[22:25], v[232:235], v[216:219], v[22:25]
	v_mfma_f32_16x16x32_bf16 v[18:21], v[240:243], v[216:219], v[18:21]
	v_mfma_f32_16x16x32_bf16 v[6:9], v[232:235], v[224:227], v[6:9]
	v_mfma_f32_16x16x32_bf16 v[2:5], v[240:243], v[224:227], v[2:5]
	s_add_i32 s2, 0, 0x18000
	v_add_u32_e32 v152, s2, v163
	s_barrier
	ds_read_b128 v[130:133], v152
	ds_read_b128 v[134:137], v152 offset:1024
	ds_read_b128 v[148:151], v152 offset:2048
	ds_read_b128 v[152:155], v152 offset:3072
	s_add_u32 s26, s74, 0x40000
	s_addc_u32 s27, s75, 0
	s_mov_b32 m0, s77
	v_lshl_add_u64 v[228:229], s[26:27], 0, v[142:143]
	ds_read_b128 v[156:159], v165 offset:32768
	ds_read_b128 v[188:191], v165 offset:33792
	ds_read_b128 v[192:195], v165 offset:34816
	ds_read_b128 v[196:199], v165 offset:35840
	ds_read_b128 v[200:203], v165 offset:36864
	ds_read_b128 v[216:219], v165 offset:37888
	ds_read_b128 v[220:223], v165 offset:38912
	ds_read_b128 v[224:227], v165 offset:39936
	global_load_lds_dwordx4 v[228:229], off
	v_lshl_add_u64 v[228:229], s[26:27], 0, v[140:141]
	s_mov_b32 m0, s78
	s_nop 0
	global_load_lds_dwordx4 v[228:229], off
	s_waitcnt lgkmcnt(8)
	s_barrier
	s_waitcnt lgkmcnt(7)
	v_mfma_f32_16x16x32_bf16 v[126:129], v[130:133], v[156:159], v[126:129]
	v_mfma_f32_16x16x32_bf16 v[122:125], v[148:151], v[156:159], v[122:125]
	s_waitcnt lgkmcnt(5)
	v_mfma_f32_16x16x32_bf16 v[110:113], v[130:133], v[192:195], v[110:113]
	v_mfma_f32_16x16x32_bf16 v[106:109], v[148:151], v[192:195], v[106:109]
	s_waitcnt lgkmcnt(3)
	v_mfma_f32_16x16x32_bf16 v[94:97], v[130:133], v[200:203], v[94:97]
	v_mfma_f32_16x16x32_bf16 v[90:93], v[148:151], v[200:203], v[90:93]
	s_waitcnt lgkmcnt(1)
	v_mfma_f32_16x16x32_bf16 v[78:81], v[130:133], v[220:223], v[78:81]
	v_mfma_f32_16x16x32_bf16 v[74:77], v[148:151], v[220:223], v[74:77]
	v_mfma_f32_16x16x32_bf16 v[126:129], v[134:137], v[188:191], v[126:129]
	v_mfma_f32_16x16x32_bf16 v[122:125], v[152:155], v[188:191], v[122:125]
	v_mfma_f32_16x16x32_bf16 v[110:113], v[134:137], v[196:199], v[110:113]
	v_mfma_f32_16x16x32_bf16 v[106:109], v[152:155], v[196:199], v[106:109]
	v_mfma_f32_16x16x32_bf16 v[94:97], v[134:137], v[216:219], v[94:97]
	v_mfma_f32_16x16x32_bf16 v[90:93], v[152:155], v[216:219], v[90:93]
	s_waitcnt lgkmcnt(0)
	v_mfma_f32_16x16x32_bf16 v[78:81], v[134:137], v[224:227], v[78:81]
	v_mfma_f32_16x16x32_bf16 v[74:77], v[152:155], v[224:227], v[74:77]
	s_barrier
	s_add_i32 s17, 0, 0x1c000
	s_add_i32 s2, s2, s3
	v_add_u32_e32 v206, s17, v163
	v_lshl_add_u64 v[160:161], v[160:161], 0, s[28:29]
	s_mov_b32 m0, s2
	ds_read_b128 v[228:231], v206
	ds_read_b128 v[232:235], v206 offset:1024
	ds_read_b128 v[236:239], v206 offset:2048
	ds_read_b128 v[240:243], v206 offset:3072
	global_load_lds_dwordx4 v[160:161], off
	v_lshl_add_u64 v[160:161], v[204:205], 0, s[28:29]
	s_add_i32 m0, s2, 0x2000
	s_nop 0
	global_load_lds_dwordx4 v[160:161], off
	s_barrier
	s_waitcnt lgkmcnt(3)
	v_mfma_f32_16x16x32_bf16 v[118:121], v[228:231], v[156:159], v[118:121]
	s_waitcnt lgkmcnt(1)
	v_mfma_f32_16x16x32_bf16 v[114:117], v[236:239], v[156:159], v[114:117]
	v_mfma_f32_16x16x32_bf16 v[102:105], v[228:231], v[192:195], v[102:105]
	v_mfma_f32_16x16x32_bf16 v[98:101], v[236:239], v[192:195], v[98:101]
	v_mfma_f32_16x16x32_bf16 v[86:89], v[228:231], v[200:203], v[86:89]
	v_mfma_f32_16x16x32_bf16 v[82:85], v[236:239], v[200:203], v[82:85]
	v_mfma_f32_16x16x32_bf16 v[70:73], v[228:231], v[220:223], v[70:73]
	v_mfma_f32_16x16x32_bf16 v[66:69], v[236:239], v[220:223], v[66:69]
	v_mfma_f32_16x16x32_bf16 v[118:121], v[232:235], v[188:191], v[118:121]
	s_waitcnt lgkmcnt(0)
	v_mfma_f32_16x16x32_bf16 v[114:117], v[240:243], v[188:191], v[114:117]
	v_mfma_f32_16x16x32_bf16 v[102:105], v[232:235], v[196:199], v[102:105]
	v_mfma_f32_16x16x32_bf16 v[98:101], v[240:243], v[196:199], v[98:101]
	v_mfma_f32_16x16x32_bf16 v[86:89], v[232:235], v[216:219], v[86:89]
	v_mfma_f32_16x16x32_bf16 v[82:85], v[240:243], v[216:219], v[82:85]
	v_mfma_f32_16x16x32_bf16 v[70:73], v[232:235], v[224:227], v[70:73]
	v_mfma_f32_16x16x32_bf16 v[66:69], v[240:243], v[224:227], v[66:69]
	s_mov_b32 m0, s79
	v_lshl_add_u64 v[160:161], v[244:245], 0, s[28:29]
	s_barrier
	ds_read_b128 v[156:159], v165 offset:49152
	ds_read_b128 v[188:191], v165 offset:50176
	ds_read_b128 v[192:195], v165 offset:51200
	ds_read_b128 v[196:199], v165 offset:52224
	ds_read_b128 v[200:203], v165 offset:53248
	ds_read_b128 v[216:219], v165 offset:54272
	ds_read_b128 v[220:223], v165 offset:55296
	ds_read_b128 v[224:227], v165 offset:56320
	global_load_lds_dwordx4 v[160:161], off
	v_lshl_add_u64 v[160:161], v[246:247], 0, s[28:29]
	s_mov_b32 m0, s83
	s_nop 0
	global_load_lds_dwordx4 v[160:161], off
	s_barrier
	s_waitcnt lgkmcnt(7)
	v_mfma_f32_16x16x32_bf16 v[62:65], v[130:133], v[156:159], v[62:65]
	v_mfma_f32_16x16x32_bf16 v[58:61], v[148:151], v[156:159], v[58:61]
	s_waitcnt lgkmcnt(5)
	v_mfma_f32_16x16x32_bf16 v[46:49], v[130:133], v[192:195], v[46:49]
	v_mfma_f32_16x16x32_bf16 v[42:45], v[148:151], v[192:195], v[42:45]
	s_waitcnt lgkmcnt(3)
	v_mfma_f32_16x16x32_bf16 v[30:33], v[130:133], v[200:203], v[30:33]
	v_mfma_f32_16x16x32_bf16 v[26:29], v[148:151], v[200:203], v[26:29]
	s_waitcnt lgkmcnt(1)
	v_mfma_f32_16x16x32_bf16 v[14:17], v[130:133], v[220:223], v[14:17]
	v_mfma_f32_16x16x32_bf16 v[10:13], v[148:151], v[220:223], v[10:13]
	v_mfma_f32_16x16x32_bf16 v[62:65], v[134:137], v[188:191], v[62:65]
	v_mfma_f32_16x16x32_bf16 v[58:61], v[152:155], v[188:191], v[58:61]
	v_mfma_f32_16x16x32_bf16 v[46:49], v[134:137], v[196:199], v[46:49]
	v_mfma_f32_16x16x32_bf16 v[42:45], v[152:155], v[196:199], v[42:45]
	v_mfma_f32_16x16x32_bf16 v[30:33], v[134:137], v[216:219], v[30:33]
	v_mfma_f32_16x16x32_bf16 v[26:29], v[152:155], v[216:219], v[26:29]
	s_waitcnt lgkmcnt(0)
	v_mfma_f32_16x16x32_bf16 v[14:17], v[134:137], v[224:227], v[14:17]
	v_mfma_f32_16x16x32_bf16 v[10:13], v[152:155], v[224:227], v[10:13]
	s_barrier
	s_add_u32 s26, s72, 0x40080
	s_addc_u32 s27, s73, 0
	s_add_i32 s2, s17, s3
	v_lshl_add_u64 v[130:131], s[26:27], 0, v[0:1]
	s_mov_b32 m0, s2
	s_nop 0
	global_load_lds_dwordx4 v[130:131], off
	v_lshl_add_u64 v[130:131], s[26:27], 0, v[138:139]
	s_add_i32 m0, s2, 0x2000
	s_nop 0
	global_load_lds_dwordx4 v[130:131], off
	s_waitcnt vmcnt(6)
	s_barrier
	v_mfma_f32_16x16x32_bf16 v[54:57], v[228:231], v[156:159], v[54:57]
	v_mfma_f32_16x16x32_bf16 v[50:53], v[236:239], v[156:159], v[50:53]
	v_mfma_f32_16x16x32_bf16 v[38:41], v[228:231], v[192:195], v[38:41]
	v_mfma_f32_16x16x32_bf16 v[34:37], v[236:239], v[192:195], v[34:37]
	v_mfma_f32_16x16x32_bf16 v[22:25], v[228:231], v[200:203], v[22:25]
	v_mfma_f32_16x16x32_bf16 v[18:21], v[236:239], v[200:203], v[18:21]
	v_mfma_f32_16x16x32_bf16 v[6:9], v[228:231], v[220:223], v[6:9]
	v_mfma_f32_16x16x32_bf16 v[2:5], v[236:239], v[220:223], v[2:5]
	v_mfma_f32_16x16x32_bf16 v[54:57], v[232:235], v[188:191], v[54:57]
	v_mfma_f32_16x16x32_bf16 v[50:53], v[240:243], v[188:191], v[50:53]
	v_mfma_f32_16x16x32_bf16 v[38:41], v[232:235], v[196:199], v[38:41]
	v_mfma_f32_16x16x32_bf16 v[34:37], v[240:243], v[196:199], v[34:37]
	v_mfma_f32_16x16x32_bf16 v[22:25], v[232:235], v[216:219], v[22:25]
	v_mfma_f32_16x16x32_bf16 v[18:21], v[240:243], v[216:219], v[18:21]
	v_mfma_f32_16x16x32_bf16 v[6:9], v[232:235], v[224:227], v[6:9]
	v_mfma_f32_16x16x32_bf16 v[2:5], v[240:243], v[224:227], v[2:5]
	s_add_i32 s44, s44, 2
	s_add_u32 s70, s70, 0x100
	s_addc_u32 s71, s71, 0
	s_add_u32 vcc_lo, vcc_lo, 0x100
	s_addc_u32 vcc_hi, vcc_hi, 0
	s_cmp_gt_u32 s44, 13
	s_barrier
	s_cbranch_scc0 .LBB0_977
	v_lshl_add_u32 v152, s47, 8, v162
	v_lshl_or_b32 v130, s46, 8, v164
	v_ashrrev_i32_e32 v153, 31, v152
	v_lshlrev_b64 v[136:137], 11, v[152:153]
	v_ashrrev_i32_e32 v131, 31, v130
	v_lshl_add_u64 v[136:137], s[56:57], 0, v[136:137]
	v_lshlrev_b64 v[150:151], 1, v[130:131]
	v_mov_b64_e32 v[154:155], s[22:23]
	v_lshl_add_u64 v[156:157], v[136:137], 0, v[150:151]
	v_mad_i64_i32 v[136:137], s[24:25], v152, s48, v[154:155]
	v_lshl_add_u64 v[160:161], v[136:137], 0, s[94:95]
	v_lshl_add_u64 v[148:149], v[130:131], 2, s[54:55]
	v_lshl_add_u64 v[136:137], v[160:161], 0, v[150:151]
	global_load_dwordx4 v[132:135], v[148:149], off offset:16
	global_load_dwordx4 v[188:191], v[148:149], off
	global_load_dwordx4 v[192:195], v[156:157], off
	global_load_dwordx4 v[196:199], v[136:137], off
	s_and_b64 vcc, exec, s[6:7]
	s_mov_b32 s46, s92
	s_mov_b32 s47, s40
	s_mov_b64 s[72:73], s[68:69]
	s_mov_b64 s[70:71], s[42:43]
	v_readlane_b32 s93, v251, 60
	s_waitcnt vmcnt(0)
	v_add_f32_e32 v122, v122, v132
	v_add_f32_e32 v126, v126, v188
	v_add_f32_e32 v127, v127, v189
	v_lshlrev_b32_e32 v158, 16, v196
	v_mul_f32_e32 v131, 0xbfb8aa3b, v158
	v_exp_f32_e32 v131, v131
	v_and_b32_e32 v159, 0xffff0000, v196
	v_mul_f32_e32 v126, 0xbfb8aa3b, v126
	v_mul_f32_e32 v127, 0xbfb8aa3b, v127
	v_add_f32_e32 v131, 1.0, v131
	v_rcp_f32_e32 v188, v131
	v_mul_f32_e32 v131, 0xbfb8aa3b, v159
	v_exp_f32_e32 v126, v126
	v_exp_f32_e32 v127, v127
	v_exp_f32_e32 v131, v131
	v_lshlrev_b32_e32 v136, 16, v192
	v_add_f32_e32 v126, 1.0, v126
	v_add_f32_e32 v127, 1.0, v127
	v_add_f32_e32 v131, 1.0, v131
	v_rcp_f32_e32 v126, v126
	v_rcp_f32_e32 v127, v127
	v_rcp_f32_e32 v189, v131
	v_and_b32_e32 v137, 0xffff0000, v192
	v_add_f32_e32 v123, v123, v133
	v_pk_mul_f32 v[126:127], v[126:127], v[136:137]
	v_pk_mul_f32 v[136:137], v[188:189], v[158:159]
	v_mul_f32_e32 v122, 0xbfb8aa3b, v122
	v_pk_mul_f32 v[126:127], v[126:127], v[136:137]
	v_lshlrev_b32_e32 v136, 16, v198
	v_mul_f32_e32 v131, 0xbfb8aa3b, v136
	v_exp_f32_e32 v131, v131
	v_and_b32_e32 v137, 0xffff0000, v198
	v_mul_f32_e32 v123, 0xbfb8aa3b, v123
	v_exp_f32_e32 v122, v122
	v_add_f32_e32 v131, 1.0, v131
	v_rcp_f32_e32 v158, v131
	v_mul_f32_e32 v131, 0xbfb8aa3b, v137
	v_exp_f32_e32 v123, v123
	v_exp_f32_e32 v131, v131
	v_add_f32_e32 v122, 1.0, v122
	v_rcp_f32_e32 v122, v122
	v_add_f32_e32 v123, 1.0, v123
	v_add_f32_e32 v131, 1.0, v131
	v_rcp_f32_e32 v123, v123
	v_rcp_f32_e32 v159, v131
	v_lshlrev_b32_e32 v132, 16, v194
	v_and_b32_e32 v133, 0xffff0000, v194
	v_pk_mul_f32 v[122:123], v[122:123], v[132:133]
	v_pk_mul_f32 v[132:133], v[158:159], v[136:137]
	v_lshlrev_b32_e32 v136, 16, v197
	v_pk_mul_f32 v[132:133], v[122:123], v[132:133]
	v_add_f32_e32 v123, v124, v134
	v_mul_f32_e32 v123, 0xbfb8aa3b, v123
	v_exp_f32_e32 v123, v123
	v_add_f32_e32 v122, v128, v190
	v_mul_f32_e32 v122, 0xbfb8aa3b, v122
	v_exp_f32_e32 v122, v122
	v_add_f32_e32 v123, 1.0, v123
	v_rcp_f32_e32 v124, v123
	v_add_f32_e32 v123, v129, v191
	v_mul_f32_e32 v123, 0xbfb8aa3b, v123
	v_exp_f32_e32 v123, v123
	v_add_f32_e32 v122, 1.0, v122
	v_rcp_f32_e32 v122, v122
	v_lshlrev_b32_e32 v128, 16, v193
	v_add_f32_e32 v123, 1.0, v123
	v_rcp_f32_e32 v123, v123
	v_and_b32_e32 v129, 0xffff0000, v193
	v_and_b32_e32 v137, 0xffff0000, v197
	v_mul_f32_e32 v131, 0xbfb8aa3b, v136
	v_pk_mul_f32 v[122:123], v[122:123], v[128:129]
	v_mul_f32_e32 v128, 0xbfb8aa3b, v137
	v_exp_f32_e32 v131, v131
	v_exp_f32_e32 v128, v128
	v_lshlrev_b32_e32 v134, 16, v199
	v_add_f32_e32 v131, 1.0, v131
	v_add_f32_e32 v128, 1.0, v128
	v_rcp_f32_e32 v158, v131
	v_rcp_f32_e32 v159, v128
	v_mul_f32_e32 v131, 0xbfb8aa3b, v134
	v_exp_f32_e32 v131, v131
	v_pk_mul_f32 v[128:129], v[158:159], v[136:137]
	s_nop 0
	v_pk_mul_f32 v[128:129], v[122:123], v[128:129]
	v_add_f32_e32 v122, v125, v135
	v_mul_f32_e32 v122, 0xbfb8aa3b, v122
	v_exp_f32_e32 v122, v122
	v_and_b32_e32 v123, 0xffff0000, v195
	v_and_b32_e32 v135, 0xffff0000, v199
	v_add_f32_e32 v131, 1.0, v131
	v_add_f32_e32 v122, 1.0, v122
	v_rcp_f32_e32 v125, v122
	v_lshlrev_b32_e32 v122, 16, v195
	v_rcp_f32_e32 v136, v131
	v_pk_mul_f32 v[122:123], v[124:125], v[122:123]
	v_mul_f32_e32 v124, 0xbfb8aa3b, v135
	v_exp_f32_e32 v124, v124
	s_nop 0
	v_add_f32_e32 v124, 1.0, v124
	v_rcp_f32_e32 v137, v124
	s_nop 0
	v_pk_mul_f32 v[124:125], v[136:137], v[134:135]
	s_nop 0
	v_pk_mul_f32 v[134:135], v[122:123], v[124:125]
	v_cvt_pk_bf16_f32 v122, v126, v127
	v_lshlrev_b64 v[126:127], 12, v[152:153]
	v_lshl_add_u64 v[126:127], s[36:37], 0, v[126:127]
	v_cvt_pk_bf16_f32 v123, v128, v129
	v_cvt_pk_bf16_f32 v124, v132, v133
	v_cvt_pk_bf16_f32 v125, v134, v135
	v_lshl_add_u64 v[158:159], v[126:127], 0, v[150:151]
	v_or_b32_e32 v126, 0x80, v130
	global_store_dwordx4 v[158:159], v[122:125], off offset:2048
	v_ashrrev_i32_e32 v127, 31, v126
	global_load_dwordx4 v[130:133], v[148:149], off offset:528
	global_load_dwordx4 v[134:137], v[148:149], off offset:512
	global_load_dwordx4 v[122:125], v[156:157], off offset:256
	v_lshlrev_b64 v[156:157], 1, v[126:127]
	v_lshl_add_u64 v[126:127], v[160:161], 0, v[156:157]
	global_load_dwordx4 v[126:129], v[126:127], off
	s_waitcnt vmcnt(0)
	v_add_f32_e32 v114, v114, v130
	v_add_f32_e32 v118, v118, v134
	v_add_f32_e32 v119, v119, v135
	v_lshlrev_b32_e32 v134, 16, v122
	v_and_b32_e32 v135, 0xffff0000, v122
	v_lshlrev_b32_e32 v160, 16, v126
	v_mul_f32_e32 v122, 0xbfb8aa3b, v160
	v_exp_f32_e32 v122, v122
	v_and_b32_e32 v161, 0xffff0000, v126
	v_mul_f32_e32 v118, 0xbfb8aa3b, v118
	v_mul_f32_e32 v119, 0xbfb8aa3b, v119
	v_add_f32_e32 v122, 1.0, v122
	v_rcp_f32_e32 v188, v122
	v_mul_f32_e32 v122, 0xbfb8aa3b, v161
	v_exp_f32_e32 v118, v118
	v_exp_f32_e32 v119, v119
	v_exp_f32_e32 v122, v122
	v_add_f32_e32 v120, v120, v136
	v_add_f32_e32 v118, 1.0, v118
	v_add_f32_e32 v119, 1.0, v119
	v_add_f32_e32 v122, 1.0, v122
	v_rcp_f32_e32 v118, v118
	v_rcp_f32_e32 v119, v119
	v_rcp_f32_e32 v189, v122
	v_add_f32_e32 v121, v121, v137
	v_mul_f32_e32 v120, 0xbfb8aa3b, v120
	v_pk_mul_f32 v[118:119], v[118:119], v[134:135]
	v_pk_mul_f32 v[134:135], v[188:189], v[160:161]
	v_mul_f32_e32 v121, 0xbfb8aa3b, v121
	v_pk_mul_f32 v[118:119], v[118:119], v[134:135]
	v_lshlrev_b32_e32 v134, 16, v128
	v_mul_f32_e32 v122, 0xbfb8aa3b, v134
	v_exp_f32_e32 v122, v122
	v_exp_f32_e32 v120, v120
	v_exp_f32_e32 v121, v121
	v_and_b32_e32 v135, 0xffff0000, v128
	v_add_f32_e32 v122, 1.0, v122
	v_rcp_f32_e32 v160, v122
	v_mul_f32_e32 v122, 0xbfb8aa3b, v135
	v_add_f32_e32 v115, v115, v131
	v_exp_f32_e32 v122, v122
	v_mul_f32_e32 v114, 0xbfb8aa3b, v114
	v_mul_f32_e32 v115, 0xbfb8aa3b, v115
	v_add_f32_e32 v120, 1.0, v120
	v_add_f32_e32 v121, 1.0, v121
	v_exp_f32_e32 v114, v114
	v_exp_f32_e32 v115, v115
	v_rcp_f32_e32 v120, v120
	v_rcp_f32_e32 v121, v121
	v_add_f32_e32 v122, 1.0, v122
	v_rcp_f32_e32 v161, v122
	v_lshlrev_b32_e32 v122, 16, v123
	v_and_b32_e32 v123, 0xffff0000, v123
	v_lshlrev_b32_e32 v126, 16, v127
	v_and_b32_e32 v127, 0xffff0000, v127
	v_add_f32_e32 v114, 1.0, v114
	v_add_f32_e32 v115, 1.0, v115
	v_lshlrev_b32_e32 v130, 16, v124
	v_and_b32_e32 v131, 0xffff0000, v124
	v_mul_f32_e32 v124, 0xbfb8aa3b, v126
	v_pk_mul_f32 v[120:121], v[120:121], v[122:123]
	v_mul_f32_e32 v122, 0xbfb8aa3b, v127
	v_rcp_f32_e32 v114, v114
	v_rcp_f32_e32 v115, v115
	v_add_f32_e32 v116, v116, v132
	v_exp_f32_e32 v124, v124
	v_exp_f32_e32 v122, v122
	v_add_f32_e32 v117, v117, v133
	v_mul_f32_e32 v116, 0xbfb8aa3b, v116
	v_mul_f32_e32 v117, 0xbfb8aa3b, v117
	v_exp_f32_e32 v116, v116
	v_exp_f32_e32 v117, v117
	v_pk_mul_f32 v[114:115], v[114:115], v[130:131]
	v_pk_mul_f32 v[130:131], v[160:161], v[134:135]
	v_add_f32_e32 v124, 1.0, v124
	v_add_f32_e32 v122, 1.0, v122
	v_pk_mul_f32 v[114:115], v[114:115], v[130:131]
	v_rcp_f32_e32 v130, v124
	v_rcp_f32_e32 v131, v122
	v_add_f32_e32 v116, 1.0, v116
	v_add_f32_e32 v117, 1.0, v117
	v_rcp_f32_e32 v116, v116
	v_rcp_f32_e32 v117, v117
	v_pk_mul_f32 v[122:123], v[130:131], v[126:127]
	v_lshlrev_b32_e32 v124, 16, v129
	v_pk_mul_f32 v[120:121], v[120:121], v[122:123]
	v_lshlrev_b32_e32 v122, 16, v125
	v_and_b32_e32 v123, 0xffff0000, v125
	v_and_b32_e32 v125, 0xffff0000, v129
	v_mul_f32_e32 v126, 0xbfb8aa3b, v124
	v_pk_mul_f32 v[116:117], v[116:117], v[122:123]
	v_mul_f32_e32 v122, 0xbfb8aa3b, v125
	v_exp_f32_e32 v126, v126
	v_exp_f32_e32 v122, v122
	v_or_b32_e32 v132, 16, v152
	v_ashrrev_i32_e32 v133, 31, v132
	v_add_f32_e32 v126, 1.0, v126
	v_add_f32_e32 v122, 1.0, v122
	v_rcp_f32_e32 v126, v126
	v_rcp_f32_e32 v127, v122
	s_nop 0
	v_pk_mul_f32 v[122:123], v[126:127], v[124:125]
	s_nop 0
	v_pk_mul_f32 v[122:123], v[116:117], v[122:123]
	v_cvt_pk_bf16_f32 v116, v118, v119
	v_cvt_pk_bf16_f32 v117, v120, v121
	v_cvt_pk_bf16_f32 v118, v114, v115
	v_cvt_pk_bf16_f32 v119, v122, v123
	global_store_dwordx4 v[158:159], v[116:119], off offset:2304
	global_load_dwordx4 v[114:117], v[148:149], off offset:16
	s_nop 0
	global_load_dwordx4 v[120:123], v[148:149], off
	v_lshlrev_b64 v[118:119], 11, v[132:133]
	v_lshl_add_u64 v[118:119], s[56:57], 0, v[118:119]
	v_lshl_add_u64 v[134:135], v[118:119], 0, v[150:151]
	v_mad_i64_i32 v[118:119], s[24:25], v132, s48, v[154:155]
	v_lshl_add_u64 v[118:119], v[118:119], 0, s[94:95]
	v_lshl_add_u64 v[128:129], v[118:119], 0, v[150:151]
	global_load_dwordx4 v[124:127], v[134:135], off
	v_lshl_add_u64 v[118:119], v[118:119], 0, v[156:157]
	global_load_dwordx4 v[128:131], v[128:129], off
	s_waitcnt vmcnt(0)
	v_add_f32_e32 v106, v106, v114
	v_add_f32_e32 v110, v110, v120
	v_add_f32_e32 v111, v111, v121
	v_mul_f32_e32 v110, 0xbfb8aa3b, v110
	v_mul_f32_e32 v111, 0xbfb8aa3b, v111
	v_exp_f32_e32 v110, v110
	v_exp_f32_e32 v111, v111
	v_add_f32_e32 v107, v107, v115
	v_mul_f32_e32 v106, 0xbfb8aa3b, v106
	v_mul_f32_e32 v107, 0xbfb8aa3b, v107
	v_exp_f32_e32 v106, v106
	v_lshlrev_b32_e32 v136, 16, v128
	v_mul_f32_e32 v114, 0xbfb8aa3b, v136
	v_exp_f32_e32 v114, v114
	v_and_b32_e32 v137, 0xffff0000, v128
	v_exp_f32_e32 v107, v107
	v_add_f32_e32 v110, 1.0, v110
	v_add_f32_e32 v114, 1.0, v114
	v_rcp_f32_e32 v158, v114
	v_mul_f32_e32 v114, 0xbfb8aa3b, v137
	v_exp_f32_e32 v114, v114
	v_add_f32_e32 v111, 1.0, v111
	v_rcp_f32_e32 v110, v110
	v_rcp_f32_e32 v111, v111
	v_add_f32_e32 v114, 1.0, v114
	v_rcp_f32_e32 v159, v114
	v_add_f32_e32 v106, 1.0, v106
	v_add_f32_e32 v107, 1.0, v107
	v_rcp_f32_e32 v106, v106
	v_rcp_f32_e32 v107, v107
	v_lshlrev_b32_e32 v120, 16, v124
	v_and_b32_e32 v121, 0xffff0000, v124
	v_pk_mul_f32 v[110:111], v[110:111], v[120:121]
	v_pk_mul_f32 v[120:121], v[158:159], v[136:137]
	v_lshlrev_b32_e32 v114, 16, v126
	v_pk_mul_f32 v[110:111], v[110:111], v[120:121]
	v_and_b32_e32 v115, 0xffff0000, v126
	v_lshlrev_b32_e32 v120, 16, v130
	v_and_b32_e32 v121, 0xffff0000, v130
	v_mul_f32_e32 v124, 0xbfb8aa3b, v120
	v_pk_mul_f32 v[106:107], v[106:107], v[114:115]
	v_mul_f32_e32 v114, 0xbfb8aa3b, v121
	v_exp_f32_e32 v124, v124
	v_exp_f32_e32 v114, v114
	v_add_f32_e32 v124, 1.0, v124
	v_add_f32_e32 v114, 1.0, v114
	v_rcp_f32_e32 v136, v124
	v_rcp_f32_e32 v137, v114
	s_nop 0
	v_pk_mul_f32 v[114:115], v[136:137], v[120:121]
	s_nop 0
	v_pk_mul_f32 v[114:115], v[106:107], v[114:115]
	v_add_f32_e32 v107, v108, v116
	v_mul_f32_e32 v107, 0xbfb8aa3b, v107
	v_exp_f32_e32 v107, v107
	v_add_f32_e32 v106, v112, v122
	v_mul_f32_e32 v106, 0xbfb8aa3b, v106
	v_exp_f32_e32 v106, v106
	v_add_f32_e32 v107, 1.0, v107
	v_rcp_f32_e32 v108, v107
	v_add_f32_e32 v107, v113, v123
	v_mul_f32_e32 v107, 0xbfb8aa3b, v107
	v_exp_f32_e32 v107, v107
	v_add_f32_e32 v106, 1.0, v106
	v_rcp_f32_e32 v106, v106
	v_lshlrev_b32_e32 v112, 16, v125
	v_add_f32_e32 v107, 1.0, v107
	v_rcp_f32_e32 v107, v107
	v_and_b32_e32 v113, 0xffff0000, v125
	v_lshlrev_b32_e32 v120, 16, v129
	v_and_b32_e32 v121, 0xffff0000, v129
	v_mul_f32_e32 v116, 0xbfb8aa3b, v120
	v_pk_mul_f32 v[106:107], v[106:107], v[112:113]
	v_mul_f32_e32 v112, 0xbfb8aa3b, v121
	v_exp_f32_e32 v116, v116
	v_exp_f32_e32 v112, v112
	v_add_f32_e32 v116, 1.0, v116
	v_add_f32_e32 v112, 1.0, v112
	v_rcp_f32_e32 v122, v116
	v_rcp_f32_e32 v123, v112
	v_lshlrev_b32_e32 v116, 16, v131
	v_pk_mul_f32 v[112:113], v[122:123], v[120:121]
	s_nop 0
	v_pk_mul_f32 v[112:113], v[106:107], v[112:113]
	v_add_f32_e32 v106, v109, v117
	v_mul_f32_e32 v106, 0xbfb8aa3b, v106
	v_exp_f32_e32 v106, v106
	v_and_b32_e32 v107, 0xffff0000, v127
	v_and_b32_e32 v117, 0xffff0000, v131
	v_mul_f32_e32 v120, 0xbfb8aa3b, v116
	v_add_f32_e32 v106, 1.0, v106
	v_rcp_f32_e32 v109, v106
	v_lshlrev_b32_e32 v106, 16, v127
	v_exp_f32_e32 v120, v120
	v_pk_mul_f32 v[106:107], v[108:109], v[106:107]
	v_mul_f32_e32 v108, 0xbfb8aa3b, v117
	v_exp_f32_e32 v108, v108
	v_add_f32_e32 v120, 1.0, v120
	v_rcp_f32_e32 v120, v120
	v_add_f32_e32 v108, 1.0, v108
	v_rcp_f32_e32 v121, v108
	s_nop 0
	v_pk_mul_f32 v[108:109], v[120:121], v[116:117]
	s_nop 0
	v_pk_mul_f32 v[116:117], v[106:107], v[108:109]
	v_cvt_pk_bf16_f32 v106, v110, v111
	v_lshlrev_b64 v[110:111], 12, v[132:133]
	v_lshl_add_u64 v[110:111], s[36:37], 0, v[110:111]
	v_cvt_pk_bf16_f32 v107, v112, v113
	v_cvt_pk_bf16_f32 v108, v114, v115
	v_cvt_pk_bf16_f32 v109, v116, v117
	v_lshl_add_u64 v[122:123], v[110:111], 0, v[150:151]
	global_store_dwordx4 v[122:123], v[106:109], off offset:2048
	global_load_dwordx4 v[110:113], v[148:149], off offset:528
	global_load_dwordx4 v[114:117], v[148:149], off offset:512
	s_nop 0
	global_load_dwordx4 v[106:109], v[134:135], off offset:256
	s_waitcnt vmcnt(0)
	v_add_f32_e32 v98, v98, v110
	global_load_dwordx4 v[118:121], v[118:119], off
	v_add_f32_e32 v102, v102, v114
	v_add_f32_e32 v103, v103, v115
	v_lshlrev_b32_e32 v114, 16, v106
	v_and_b32_e32 v115, 0xffff0000, v106
	v_mul_f32_e32 v102, 0xbfb8aa3b, v102
	v_mul_f32_e32 v103, 0xbfb8aa3b, v103
	v_exp_f32_e32 v102, v102
	v_exp_f32_e32 v103, v103
	v_add_f32_e32 v99, v99, v111
	v_mul_f32_e32 v98, 0xbfb8aa3b, v98
	v_add_f32_e32 v102, 1.0, v102
	v_add_f32_e32 v103, 1.0, v103
	v_rcp_f32_e32 v102, v102
	v_rcp_f32_e32 v103, v103
	v_mul_f32_e32 v99, 0xbfb8aa3b, v99
	v_exp_f32_e32 v98, v98
	v_exp_f32_e32 v99, v99
	v_pk_mul_f32 v[102:103], v[102:103], v[114:115]
	v_lshlrev_b32_e32 v110, 16, v108
	v_add_f32_e32 v98, 1.0, v98
	v_add_f32_e32 v99, 1.0, v99
	v_rcp_f32_e32 v98, v98
	v_rcp_f32_e32 v99, v99
	v_and_b32_e32 v111, 0xffff0000, v108
	v_pk_mul_f32 v[98:99], v[98:99], v[110:111]
	s_waitcnt vmcnt(0)
	v_lshlrev_b32_e32 v124, 16, v118
	v_mul_f32_e32 v106, 0xbfb8aa3b, v124
	v_exp_f32_e32 v106, v106
	v_and_b32_e32 v125, 0xffff0000, v118
	v_or_b32_e32 v118, 32, v152
	v_add_f32_e32 v106, 1.0, v106
	v_rcp_f32_e32 v126, v106
	v_mul_f32_e32 v106, 0xbfb8aa3b, v125
	v_exp_f32_e32 v106, v106
	s_nop 0
	v_add_f32_e32 v106, 1.0, v106
	v_rcp_f32_e32 v127, v106
	s_nop 0
	v_pk_mul_f32 v[114:115], v[126:127], v[124:125]
	s_nop 0
	v_pk_mul_f32 v[102:103], v[102:103], v[114:115]
	v_lshlrev_b32_e32 v114, 16, v120
	v_mul_f32_e32 v106, 0xbfb8aa3b, v114
	v_exp_f32_e32 v106, v106
	v_and_b32_e32 v115, 0xffff0000, v120
	v_add_f32_e32 v106, 1.0, v106
	v_rcp_f32_e32 v124, v106
	v_mul_f32_e32 v106, 0xbfb8aa3b, v115
	v_exp_f32_e32 v106, v106
	s_nop 0
	v_add_f32_e32 v106, 1.0, v106
	v_rcp_f32_e32 v125, v106
	v_lshlrev_b32_e32 v106, 16, v119
	v_mul_f32_e32 v108, 0xbfb8aa3b, v106
	v_exp_f32_e32 v108, v108
	v_pk_mul_f32 v[110:111], v[124:125], v[114:115]
	v_add_f32_e32 v108, 1.0, v108
	v_pk_mul_f32 v[110:111], v[98:99], v[110:111]
	v_add_f32_e32 v99, v100, v112
	v_mul_f32_e32 v99, 0xbfb8aa3b, v99
	v_exp_f32_e32 v99, v99
	v_add_f32_e32 v98, v104, v116
	v_mul_f32_e32 v98, 0xbfb8aa3b, v98
	v_exp_f32_e32 v98, v98
	v_add_f32_e32 v99, 1.0, v99
	v_rcp_f32_e32 v100, v99
	v_add_f32_e32 v99, v105, v117
	v_mul_f32_e32 v99, 0xbfb8aa3b, v99
	v_exp_f32_e32 v99, v99
	v_add_f32_e32 v98, 1.0, v98
	v_rcp_f32_e32 v98, v98
	v_lshlrev_b32_e32 v104, 16, v107
	v_add_f32_e32 v99, 1.0, v99
	v_rcp_f32_e32 v99, v99
	v_and_b32_e32 v105, 0xffff0000, v107
	v_and_b32_e32 v107, 0xffff0000, v119
	v_rcp_f32_e32 v114, v108
	v_pk_mul_f32 v[98:99], v[98:99], v[104:105]
	v_mul_f32_e32 v104, 0xbfb8aa3b, v107
	v_exp_f32_e32 v104, v104
	v_ashrrev_i32_e32 v119, 31, v118
	v_add_f32_e32 v104, 1.0, v104
	v_rcp_f32_e32 v115, v104
	s_nop 0
	v_pk_mul_f32 v[104:105], v[114:115], v[106:107]
	s_nop 0
	v_pk_mul_f32 v[104:105], v[98:99], v[104:105]
	v_add_f32_e32 v98, v101, v113
	v_mul_f32_e32 v98, 0xbfb8aa3b, v98
	v_exp_f32_e32 v98, v98
	v_and_b32_e32 v99, 0xffff0000, v109
	v_lshlrev_b32_e32 v106, 16, v121
	v_and_b32_e32 v107, 0xffff0000, v121
	v_add_f32_e32 v98, 1.0, v98
	v_rcp_f32_e32 v101, v98
	v_lshlrev_b32_e32 v98, 16, v109
	v_mul_f32_e32 v108, 0xbfb8aa3b, v106
	v_exp_f32_e32 v108, v108
	v_pk_mul_f32 v[98:99], v[100:101], v[98:99]
	v_mul_f32_e32 v100, 0xbfb8aa3b, v107
	v_exp_f32_e32 v100, v100
	v_add_f32_e32 v108, 1.0, v108
	v_rcp_f32_e32 v108, v108
	v_add_f32_e32 v100, 1.0, v100
	v_rcp_f32_e32 v109, v100
	s_nop 0
	v_pk_mul_f32 v[100:101], v[108:109], v[106:107]
	s_nop 0
	v_pk_mul_f32 v[106:107], v[98:99], v[100:101]
	v_cvt_pk_bf16_f32 v98, v102, v103
	v_cvt_pk_bf16_f32 v99, v104, v105
	v_cvt_pk_bf16_f32 v100, v110, v111
	v_cvt_pk_bf16_f32 v101, v106, v107
	global_store_dwordx4 v[122:123], v[98:101], off offset:2304
	global_load_dwordx4 v[102:105], v[148:149], off offset:16
	global_load_dwordx4 v[106:109], v[148:149], off
	v_lshlrev_b64 v[98:99], 11, v[118:119]
	v_lshl_add_u64 v[98:99], s[56:57], 0, v[98:99]
	v_lshl_add_u64 v[100:101], v[98:99], 0, v[150:151]
	v_mad_i64_i32 v[98:99], s[24:25], v118, s48, v[154:155]
	v_lshl_add_u64 v[98:99], v[98:99], 0, s[94:95]
	v_lshl_add_u64 v[114:115], v[98:99], 0, v[150:151]
	global_load_dwordx4 v[110:113], v[100:101], off
	v_lshl_add_u64 v[98:99], v[98:99], 0, v[156:157]
	global_load_dwordx4 v[114:117], v[114:115], off
	s_waitcnt vmcnt(0)
	v_add_f32_e32 v90, v90, v102
	v_add_f32_e32 v94, v94, v106
	v_add_f32_e32 v95, v95, v107
	v_mul_f32_e32 v94, 0xbfb8aa3b, v94
	v_mul_f32_e32 v95, 0xbfb8aa3b, v95
	v_exp_f32_e32 v94, v94
	v_exp_f32_e32 v95, v95
	v_add_f32_e32 v91, v91, v103
	v_mul_f32_e32 v90, 0xbfb8aa3b, v90
	v_mul_f32_e32 v91, 0xbfb8aa3b, v91
	v_exp_f32_e32 v90, v90
	v_lshlrev_b32_e32 v120, 16, v114
	v_mul_f32_e32 v102, 0xbfb8aa3b, v120
	v_exp_f32_e32 v102, v102
	v_and_b32_e32 v121, 0xffff0000, v114
	v_exp_f32_e32 v91, v91
	v_add_f32_e32 v94, 1.0, v94
	v_add_f32_e32 v102, 1.0, v102
	v_rcp_f32_e32 v122, v102
	v_mul_f32_e32 v102, 0xbfb8aa3b, v121
	v_exp_f32_e32 v102, v102
	v_add_f32_e32 v95, 1.0, v95
	v_rcp_f32_e32 v94, v94
	v_rcp_f32_e32 v95, v95
	v_add_f32_e32 v102, 1.0, v102
	v_rcp_f32_e32 v123, v102
	v_add_f32_e32 v90, 1.0, v90
	v_add_f32_e32 v91, 1.0, v91
	v_rcp_f32_e32 v90, v90
	v_rcp_f32_e32 v91, v91
	v_lshlrev_b32_e32 v106, 16, v110
	v_and_b32_e32 v107, 0xffff0000, v110
	v_pk_mul_f32 v[94:95], v[94:95], v[106:107]
	v_pk_mul_f32 v[106:107], v[122:123], v[120:121]
	v_lshlrev_b32_e32 v102, 16, v112
	v_pk_mul_f32 v[94:95], v[94:95], v[106:107]
	v_and_b32_e32 v103, 0xffff0000, v112
	v_lshlrev_b32_e32 v106, 16, v116
	v_and_b32_e32 v107, 0xffff0000, v116
	v_mul_f32_e32 v110, 0xbfb8aa3b, v106
	v_pk_mul_f32 v[90:91], v[90:91], v[102:103]
	v_mul_f32_e32 v102, 0xbfb8aa3b, v107
	v_exp_f32_e32 v110, v110
	v_exp_f32_e32 v102, v102
	v_add_f32_e32 v110, 1.0, v110
	v_add_f32_e32 v102, 1.0, v102
	v_rcp_f32_e32 v120, v110
	v_rcp_f32_e32 v121, v102
	s_nop 0
	v_pk_mul_f32 v[102:103], v[120:121], v[106:107]
	s_nop 0
	v_pk_mul_f32 v[102:103], v[90:91], v[102:103]
	v_add_f32_e32 v91, v92, v104
	v_mul_f32_e32 v91, 0xbfb8aa3b, v91
	v_exp_f32_e32 v91, v91
	v_add_f32_e32 v90, v96, v108
	v_mul_f32_e32 v90, 0xbfb8aa3b, v90
	v_exp_f32_e32 v90, v90
	v_add_f32_e32 v91, 1.0, v91
	v_rcp_f32_e32 v92, v91
	v_add_f32_e32 v91, v97, v109
	v_mul_f32_e32 v91, 0xbfb8aa3b, v91
	v_exp_f32_e32 v91, v91
	v_add_f32_e32 v90, 1.0, v90
	v_rcp_f32_e32 v90, v90
	v_lshlrev_b32_e32 v96, 16, v111
	v_add_f32_e32 v91, 1.0, v91
	v_rcp_f32_e32 v91, v91
	v_and_b32_e32 v97, 0xffff0000, v111
	v_lshlrev_b32_e32 v106, 16, v115
	v_and_b32_e32 v107, 0xffff0000, v115
	v_mul_f32_e32 v104, 0xbfb8aa3b, v106
	v_pk_mul_f32 v[90:91], v[90:91], v[96:97]
	v_mul_f32_e32 v96, 0xbfb8aa3b, v107
	v_exp_f32_e32 v104, v104
	v_exp_f32_e32 v96, v96
	v_add_f32_e32 v104, 1.0, v104
	v_add_f32_e32 v96, 1.0, v96
	v_rcp_f32_e32 v108, v104
	v_rcp_f32_e32 v109, v96
	v_lshlrev_b32_e32 v104, 16, v117
	v_pk_mul_f32 v[96:97], v[108:109], v[106:107]
	s_nop 0
	v_pk_mul_f32 v[96:97], v[90:91], v[96:97]
	v_add_f32_e32 v90, v93, v105
	v_mul_f32_e32 v90, 0xbfb8aa3b, v90
	v_exp_f32_e32 v90, v90
	v_and_b32_e32 v91, 0xffff0000, v113
	v_and_b32_e32 v105, 0xffff0000, v117
	v_mul_f32_e32 v106, 0xbfb8aa3b, v104
	v_add_f32_e32 v90, 1.0, v90
	v_rcp_f32_e32 v93, v90
	v_lshlrev_b32_e32 v90, 16, v113
	v_exp_f32_e32 v106, v106
	v_pk_mul_f32 v[90:91], v[92:93], v[90:91]
	v_mul_f32_e32 v92, 0xbfb8aa3b, v105
	v_exp_f32_e32 v92, v92
	v_add_f32_e32 v106, 1.0, v106
	v_rcp_f32_e32 v106, v106
	v_add_f32_e32 v92, 1.0, v92
	v_rcp_f32_e32 v107, v92
	s_nop 0
	v_pk_mul_f32 v[92:93], v[106:107], v[104:105]
	s_nop 0
	v_pk_mul_f32 v[104:105], v[90:91], v[92:93]
	v_cvt_pk_bf16_f32 v90, v94, v95
	v_lshlrev_b64 v[94:95], 12, v[118:119]
	v_lshl_add_u64 v[94:95], s[36:37], 0, v[94:95]
	v_cvt_pk_bf16_f32 v91, v96, v97
	v_cvt_pk_bf16_f32 v92, v102, v103
	v_cvt_pk_bf16_f32 v93, v104, v105
	v_lshl_add_u64 v[106:107], v[94:95], 0, v[150:151]
	global_store_dwordx4 v[106:107], v[90:93], off offset:2048
	global_load_dwordx4 v[90:93], v[148:149], off offset:528
	s_nop 0
	global_load_dwordx4 v[94:97], v[148:149], off offset:512
	global_load_dwordx4 v[102:105], v[100:101], off offset:256
	s_waitcnt vmcnt(0)
	v_add_f32_e32 v82, v82, v90
	global_load_dwordx4 v[98:101], v[98:99], off
	v_add_f32_e32 v86, v86, v94
	v_add_f32_e32 v87, v87, v95
	v_mul_f32_e32 v86, 0xbfb8aa3b, v86
	v_mul_f32_e32 v87, 0xbfb8aa3b, v87
	v_exp_f32_e32 v86, v86
	v_exp_f32_e32 v87, v87
	v_add_f32_e32 v83, v83, v91
	v_mul_f32_e32 v82, 0xbfb8aa3b, v82
	v_mul_f32_e32 v83, 0xbfb8aa3b, v83
	v_exp_f32_e32 v82, v82
	v_exp_f32_e32 v83, v83
	v_add_f32_e32 v86, 1.0, v86
	v_add_f32_e32 v87, 1.0, v87
	v_rcp_f32_e32 v86, v86
	v_rcp_f32_e32 v87, v87
	v_add_f32_e32 v82, 1.0, v82
	v_add_f32_e32 v83, 1.0, v83
	v_rcp_f32_e32 v82, v82
	v_rcp_f32_e32 v83, v83
	v_lshlrev_b32_e32 v94, 16, v102
	v_and_b32_e32 v95, 0xffff0000, v102
	v_pk_mul_f32 v[86:87], v[86:87], v[94:95]
	v_and_b32_e32 v91, 0xffff0000, v104
	v_or_b32_e32 v102, 48, v152
	s_waitcnt vmcnt(0)
	v_lshlrev_b32_e32 v108, 16, v98
	v_mul_f32_e32 v90, 0xbfb8aa3b, v108
	v_exp_f32_e32 v90, v90
	v_and_b32_e32 v109, 0xffff0000, v98
	v_add_f32_e32 v90, 1.0, v90
	v_rcp_f32_e32 v110, v90
	v_mul_f32_e32 v90, 0xbfb8aa3b, v109
	v_exp_f32_e32 v90, v90
	s_nop 0
	v_add_f32_e32 v90, 1.0, v90
	v_rcp_f32_e32 v111, v90
	v_lshlrev_b32_e32 v90, 16, v104
	v_pk_mul_f32 v[82:83], v[82:83], v[90:91]
	v_pk_mul_f32 v[94:95], v[110:111], v[108:109]
	s_nop 0
	v_pk_mul_f32 v[86:87], v[86:87], v[94:95]
	v_lshlrev_b32_e32 v94, 16, v100
	v_and_b32_e32 v95, 0xffff0000, v100
	v_mul_f32_e32 v98, 0xbfb8aa3b, v94
	v_mul_f32_e32 v90, 0xbfb8aa3b, v95
	v_exp_f32_e32 v98, v98
	v_exp_f32_e32 v90, v90
	v_add_f32_e32 v98, 1.0, v98
	v_add_f32_e32 v90, 1.0, v90
	v_rcp_f32_e32 v108, v98
	v_rcp_f32_e32 v109, v90
	s_nop 0
	v_pk_mul_f32 v[90:91], v[108:109], v[94:95]
	s_nop 0
	v_pk_mul_f32 v[90:91], v[82:83], v[90:91]
	v_add_f32_e32 v83, v84, v92
	v_mul_f32_e32 v83, 0xbfb8aa3b, v83
	v_exp_f32_e32 v83, v83
	v_add_f32_e32 v82, v88, v96
	v_mul_f32_e32 v82, 0xbfb8aa3b, v82
	v_exp_f32_e32 v82, v82
	v_add_f32_e32 v83, 1.0, v83
	v_rcp_f32_e32 v84, v83
	v_add_f32_e32 v83, v89, v97
	v_mul_f32_e32 v83, 0xbfb8aa3b, v83
	v_exp_f32_e32 v83, v83
	v_add_f32_e32 v82, 1.0, v82
	v_rcp_f32_e32 v82, v82
	v_lshlrev_b32_e32 v88, 16, v103
	v_add_f32_e32 v83, 1.0, v83
	v_rcp_f32_e32 v83, v83
	v_and_b32_e32 v89, 0xffff0000, v103
	v_lshlrev_b32_e32 v94, 16, v99
	v_and_b32_e32 v95, 0xffff0000, v99
	v_mul_f32_e32 v92, 0xbfb8aa3b, v94
	v_pk_mul_f32 v[82:83], v[82:83], v[88:89]
	v_mul_f32_e32 v88, 0xbfb8aa3b, v95
	v_exp_f32_e32 v92, v92
	v_exp_f32_e32 v88, v88
	v_ashrrev_i32_e32 v103, 31, v102
	v_add_f32_e32 v92, 1.0, v92
	v_add_f32_e32 v88, 1.0, v88
	v_rcp_f32_e32 v96, v92
	v_rcp_f32_e32 v97, v88
	v_lshlrev_b32_e32 v92, 16, v101
	v_pk_mul_f32 v[88:89], v[96:97], v[94:95]
	s_nop 0
	v_pk_mul_f32 v[88:89], v[82:83], v[88:89]
	v_add_f32_e32 v82, v85, v93
	v_mul_f32_e32 v82, 0xbfb8aa3b, v82
	v_exp_f32_e32 v82, v82
	v_and_b32_e32 v83, 0xffff0000, v105
	v_and_b32_e32 v93, 0xffff0000, v101
	v_mul_f32_e32 v94, 0xbfb8aa3b, v92
	v_add_f32_e32 v82, 1.0, v82
	v_rcp_f32_e32 v85, v82
	v_lshlrev_b32_e32 v82, 16, v105
	v_exp_f32_e32 v94, v94
	v_pk_mul_f32 v[82:83], v[84:85], v[82:83]
	v_mul_f32_e32 v84, 0xbfb8aa3b, v93
	v_exp_f32_e32 v84, v84
	v_add_f32_e32 v94, 1.0, v94
	v_rcp_f32_e32 v94, v94
	v_add_f32_e32 v84, 1.0, v84
	v_rcp_f32_e32 v95, v84
	s_nop 0
	v_pk_mul_f32 v[84:85], v[94:95], v[92:93]
	s_nop 0
	v_pk_mul_f32 v[92:93], v[82:83], v[84:85]
	v_cvt_pk_bf16_f32 v82, v86, v87
	v_cvt_pk_bf16_f32 v83, v88, v89
	v_cvt_pk_bf16_f32 v84, v90, v91
	v_cvt_pk_bf16_f32 v85, v92, v93
	global_store_dwordx4 v[106:107], v[82:85], off offset:2304
	global_load_dwordx4 v[86:89], v[148:149], off offset:16
	global_load_dwordx4 v[90:93], v[148:149], off
	v_lshlrev_b64 v[82:83], 11, v[102:103]
	v_lshl_add_u64 v[82:83], s[56:57], 0, v[82:83]
	v_lshl_add_u64 v[84:85], v[82:83], 0, v[150:151]
	v_mad_i64_i32 v[82:83], s[24:25], v102, s48, v[154:155]
	v_lshl_add_u64 v[82:83], v[82:83], 0, s[94:95]
	v_lshl_add_u64 v[98:99], v[82:83], 0, v[150:151]
	global_load_dwordx4 v[94:97], v[84:85], off
	v_lshl_add_u64 v[82:83], v[82:83], 0, v[156:157]
	global_load_dwordx4 v[98:101], v[98:99], off
	s_waitcnt vmcnt(0)
	v_add_f32_e32 v74, v74, v86
	v_add_f32_e32 v78, v78, v90
	v_add_f32_e32 v79, v79, v91
	v_mul_f32_e32 v78, 0xbfb8aa3b, v78
	v_mul_f32_e32 v79, 0xbfb8aa3b, v79
	v_exp_f32_e32 v78, v78
	v_exp_f32_e32 v79, v79
	v_add_f32_e32 v75, v75, v87
	v_mul_f32_e32 v74, 0xbfb8aa3b, v74
	v_mul_f32_e32 v75, 0xbfb8aa3b, v75
	v_exp_f32_e32 v74, v74
	v_lshlrev_b32_e32 v104, 16, v98
	v_mul_f32_e32 v86, 0xbfb8aa3b, v104
	v_exp_f32_e32 v86, v86
	v_and_b32_e32 v105, 0xffff0000, v98
	v_exp_f32_e32 v75, v75
	v_add_f32_e32 v78, 1.0, v78
	v_add_f32_e32 v86, 1.0, v86
	v_rcp_f32_e32 v106, v86
	v_mul_f32_e32 v86, 0xbfb8aa3b, v105
	v_exp_f32_e32 v86, v86
	v_add_f32_e32 v79, 1.0, v79
	v_rcp_f32_e32 v78, v78
	v_rcp_f32_e32 v79, v79
	v_add_f32_e32 v86, 1.0, v86
	v_rcp_f32_e32 v107, v86
	v_add_f32_e32 v74, 1.0, v74
	v_add_f32_e32 v75, 1.0, v75
	v_rcp_f32_e32 v74, v74
	v_rcp_f32_e32 v75, v75
	v_lshlrev_b32_e32 v90, 16, v94
	v_and_b32_e32 v91, 0xffff0000, v94
	v_pk_mul_f32 v[78:79], v[78:79], v[90:91]
	v_pk_mul_f32 v[90:91], v[106:107], v[104:105]
	v_lshlrev_b32_e32 v86, 16, v96
	v_pk_mul_f32 v[78:79], v[78:79], v[90:91]
	v_and_b32_e32 v87, 0xffff0000, v96
	v_lshlrev_b32_e32 v90, 16, v100
	v_and_b32_e32 v91, 0xffff0000, v100
	v_mul_f32_e32 v94, 0xbfb8aa3b, v90
	v_pk_mul_f32 v[74:75], v[74:75], v[86:87]
	v_mul_f32_e32 v86, 0xbfb8aa3b, v91
	v_exp_f32_e32 v94, v94
	v_exp_f32_e32 v86, v86
	v_add_f32_e32 v94, 1.0, v94
	v_add_f32_e32 v86, 1.0, v86
	v_rcp_f32_e32 v104, v94
	v_rcp_f32_e32 v105, v86
	s_nop 0
	v_pk_mul_f32 v[86:87], v[104:105], v[90:91]
	s_nop 0
	v_pk_mul_f32 v[86:87], v[74:75], v[86:87]
	v_add_f32_e32 v75, v76, v88
	v_mul_f32_e32 v75, 0xbfb8aa3b, v75
	v_exp_f32_e32 v75, v75
	v_add_f32_e32 v74, v80, v92
	v_mul_f32_e32 v74, 0xbfb8aa3b, v74
	v_exp_f32_e32 v74, v74
	v_add_f32_e32 v75, 1.0, v75
	v_rcp_f32_e32 v76, v75
	v_add_f32_e32 v75, v81, v93
	v_mul_f32_e32 v75, 0xbfb8aa3b, v75
	v_exp_f32_e32 v75, v75
	v_add_f32_e32 v74, 1.0, v74
	v_rcp_f32_e32 v74, v74
	v_lshlrev_b32_e32 v80, 16, v95
	v_add_f32_e32 v75, 1.0, v75
	v_rcp_f32_e32 v75, v75
	v_and_b32_e32 v81, 0xffff0000, v95
	v_lshlrev_b32_e32 v90, 16, v99
	v_and_b32_e32 v91, 0xffff0000, v99
	v_mul_f32_e32 v88, 0xbfb8aa3b, v90
	v_pk_mul_f32 v[74:75], v[74:75], v[80:81]
	v_mul_f32_e32 v80, 0xbfb8aa3b, v91
	v_exp_f32_e32 v88, v88
	v_exp_f32_e32 v80, v80
	v_add_f32_e32 v88, 1.0, v88
	v_add_f32_e32 v80, 1.0, v80
	v_rcp_f32_e32 v92, v88
	v_rcp_f32_e32 v93, v80
	v_lshlrev_b32_e32 v88, 16, v101
	v_pk_mul_f32 v[80:81], v[92:93], v[90:91]
	s_nop 0
	v_pk_mul_f32 v[80:81], v[74:75], v[80:81]
	v_add_f32_e32 v74, v77, v89
	v_mul_f32_e32 v74, 0xbfb8aa3b, v74
	v_exp_f32_e32 v74, v74
	v_and_b32_e32 v75, 0xffff0000, v97
	v_and_b32_e32 v89, 0xffff0000, v101
	v_mul_f32_e32 v90, 0xbfb8aa3b, v88
	v_add_f32_e32 v74, 1.0, v74
	v_rcp_f32_e32 v77, v74
	v_lshlrev_b32_e32 v74, 16, v97
	v_exp_f32_e32 v90, v90
	v_pk_mul_f32 v[74:75], v[76:77], v[74:75]
	v_mul_f32_e32 v76, 0xbfb8aa3b, v89
	v_exp_f32_e32 v76, v76
	v_add_f32_e32 v90, 1.0, v90
	v_rcp_f32_e32 v90, v90
	v_add_f32_e32 v76, 1.0, v76
	v_rcp_f32_e32 v91, v76
	s_nop 0
	v_pk_mul_f32 v[76:77], v[90:91], v[88:89]
	s_nop 0
	v_pk_mul_f32 v[88:89], v[74:75], v[76:77]
	v_cvt_pk_bf16_f32 v74, v78, v79
	v_lshlrev_b64 v[78:79], 12, v[102:103]
	v_lshl_add_u64 v[78:79], s[36:37], 0, v[78:79]
	v_cvt_pk_bf16_f32 v75, v80, v81
	v_cvt_pk_bf16_f32 v76, v86, v87
	v_cvt_pk_bf16_f32 v77, v88, v89
	v_lshl_add_u64 v[90:91], v[78:79], 0, v[150:151]
	global_store_dwordx4 v[90:91], v[74:77], off offset:2048
	global_load_dwordx4 v[74:77], v[148:149], off offset:528
	s_nop 0
	global_load_dwordx4 v[78:81], v[148:149], off offset:512
	global_load_dwordx4 v[86:89], v[84:85], off offset:256
	s_waitcnt vmcnt(0)
	v_add_f32_e32 v66, v66, v74
	global_load_dwordx4 v[82:85], v[82:83], off
	v_add_f32_e32 v70, v70, v78
	v_add_f32_e32 v71, v71, v79
	v_mul_f32_e32 v70, 0xbfb8aa3b, v70
	v_mul_f32_e32 v71, 0xbfb8aa3b, v71
	v_exp_f32_e32 v70, v70
	v_exp_f32_e32 v71, v71
	v_add_f32_e32 v67, v67, v75
	v_mul_f32_e32 v66, 0xbfb8aa3b, v66
	v_mul_f32_e32 v67, 0xbfb8aa3b, v67
	v_exp_f32_e32 v66, v66
	v_exp_f32_e32 v67, v67
	v_add_f32_e32 v70, 1.0, v70
	v_add_f32_e32 v71, 1.0, v71
	v_rcp_f32_e32 v70, v70
	v_rcp_f32_e32 v71, v71
	v_add_f32_e32 v66, 1.0, v66
	v_add_f32_e32 v67, 1.0, v67
	v_rcp_f32_e32 v66, v66
	v_rcp_f32_e32 v67, v67
	v_lshlrev_b32_e32 v78, 16, v86
	v_and_b32_e32 v79, 0xffff0000, v86
	v_pk_mul_f32 v[70:71], v[70:71], v[78:79]
	v_and_b32_e32 v75, 0xffff0000, v88
	v_add_u32_e32 v86, 0x80, v152
	s_waitcnt vmcnt(0)
	v_lshlrev_b32_e32 v92, 16, v82
	v_mul_f32_e32 v74, 0xbfb8aa3b, v92
	v_exp_f32_e32 v74, v74
	v_and_b32_e32 v93, 0xffff0000, v82
	v_add_f32_e32 v74, 1.0, v74
	v_rcp_f32_e32 v94, v74
	v_mul_f32_e32 v74, 0xbfb8aa3b, v93
	v_exp_f32_e32 v74, v74
	s_nop 0
	v_add_f32_e32 v74, 1.0, v74
	v_rcp_f32_e32 v95, v74
	v_lshlrev_b32_e32 v74, 16, v88
	v_pk_mul_f32 v[66:67], v[66:67], v[74:75]
	v_pk_mul_f32 v[78:79], v[94:95], v[92:93]
	s_nop 0
	v_pk_mul_f32 v[70:71], v[70:71], v[78:79]
	v_lshlrev_b32_e32 v78, 16, v84
	v_and_b32_e32 v79, 0xffff0000, v84
	v_mul_f32_e32 v82, 0xbfb8aa3b, v78
	v_mul_f32_e32 v74, 0xbfb8aa3b, v79
	v_exp_f32_e32 v82, v82
	v_exp_f32_e32 v74, v74
	v_add_f32_e32 v82, 1.0, v82
	v_add_f32_e32 v74, 1.0, v74
	v_rcp_f32_e32 v92, v82
	v_rcp_f32_e32 v93, v74
	s_nop 0
	v_pk_mul_f32 v[74:75], v[92:93], v[78:79]
	s_nop 0
	v_pk_mul_f32 v[74:75], v[66:67], v[74:75]
	v_add_f32_e32 v67, v68, v76
	v_mul_f32_e32 v67, 0xbfb8aa3b, v67
	v_exp_f32_e32 v67, v67
	v_add_f32_e32 v66, v72, v80
	v_mul_f32_e32 v66, 0xbfb8aa3b, v66
	v_exp_f32_e32 v66, v66
	v_add_f32_e32 v67, 1.0, v67
	v_rcp_f32_e32 v68, v67
	v_add_f32_e32 v67, v73, v81
	v_mul_f32_e32 v67, 0xbfb8aa3b, v67
	v_exp_f32_e32 v67, v67
	v_add_f32_e32 v66, 1.0, v66
	v_rcp_f32_e32 v66, v66
	v_lshlrev_b32_e32 v72, 16, v87
	v_add_f32_e32 v67, 1.0, v67
	v_rcp_f32_e32 v67, v67
	v_and_b32_e32 v73, 0xffff0000, v87
	v_lshlrev_b32_e32 v78, 16, v83
	v_and_b32_e32 v79, 0xffff0000, v83
	v_mul_f32_e32 v76, 0xbfb8aa3b, v78
	v_pk_mul_f32 v[66:67], v[66:67], v[72:73]
	v_mul_f32_e32 v72, 0xbfb8aa3b, v79
	v_exp_f32_e32 v76, v76
	v_exp_f32_e32 v72, v72
	v_ashrrev_i32_e32 v87, 31, v86
	v_add_f32_e32 v76, 1.0, v76
	v_add_f32_e32 v72, 1.0, v72
	v_rcp_f32_e32 v80, v76
	v_rcp_f32_e32 v81, v72
	v_lshlrev_b32_e32 v76, 16, v85
	v_pk_mul_f32 v[72:73], v[80:81], v[78:79]
	s_nop 0
	v_pk_mul_f32 v[72:73], v[66:67], v[72:73]
	v_add_f32_e32 v66, v69, v77
	v_mul_f32_e32 v66, 0xbfb8aa3b, v66
	v_exp_f32_e32 v66, v66
	v_and_b32_e32 v67, 0xffff0000, v89
	v_and_b32_e32 v77, 0xffff0000, v85
	v_mul_f32_e32 v78, 0xbfb8aa3b, v76
	v_add_f32_e32 v66, 1.0, v66
	v_rcp_f32_e32 v69, v66
	v_lshlrev_b32_e32 v66, 16, v89
	v_exp_f32_e32 v78, v78
	v_pk_mul_f32 v[66:67], v[68:69], v[66:67]
	v_mul_f32_e32 v68, 0xbfb8aa3b, v77
	v_exp_f32_e32 v68, v68
	v_add_f32_e32 v78, 1.0, v78
	v_rcp_f32_e32 v78, v78
	v_add_f32_e32 v68, 1.0, v68
	v_rcp_f32_e32 v79, v68
	s_nop 0
	v_pk_mul_f32 v[68:69], v[78:79], v[76:77]
	s_nop 0
	v_pk_mul_f32 v[76:77], v[66:67], v[68:69]
	v_cvt_pk_bf16_f32 v66, v70, v71
	v_cvt_pk_bf16_f32 v67, v72, v73
	v_cvt_pk_bf16_f32 v68, v74, v75
	v_cvt_pk_bf16_f32 v69, v76, v77
	global_store_dwordx4 v[90:91], v[66:69], off offset:2304
	global_load_dwordx4 v[70:73], v[148:149], off offset:16
	global_load_dwordx4 v[74:77], v[148:149], off
	v_lshlrev_b64 v[66:67], 11, v[86:87]
	v_lshl_add_u64 v[66:67], s[56:57], 0, v[66:67]
	v_lshl_add_u64 v[68:69], v[66:67], 0, v[150:151]
	v_mad_i64_i32 v[66:67], s[24:25], v86, s48, v[154:155]
	v_lshl_add_u64 v[66:67], v[66:67], 0, s[94:95]
	v_lshl_add_u64 v[82:83], v[66:67], 0, v[150:151]
	global_load_dwordx4 v[78:81], v[68:69], off
	v_lshl_add_u64 v[66:67], v[66:67], 0, v[156:157]
	global_load_dwordx4 v[82:85], v[82:83], off
	s_waitcnt vmcnt(0)
	v_add_f32_e32 v58, v58, v70
	v_add_f32_e32 v62, v62, v74
	v_add_f32_e32 v63, v63, v75
	v_mul_f32_e32 v62, 0xbfb8aa3b, v62
	v_mul_f32_e32 v63, 0xbfb8aa3b, v63
	v_exp_f32_e32 v62, v62
	v_exp_f32_e32 v63, v63
	v_add_f32_e32 v59, v59, v71
	v_mul_f32_e32 v58, 0xbfb8aa3b, v58
	v_mul_f32_e32 v59, 0xbfb8aa3b, v59
	v_exp_f32_e32 v58, v58
	v_lshlrev_b32_e32 v88, 16, v82
	v_mul_f32_e32 v70, 0xbfb8aa3b, v88
	v_exp_f32_e32 v70, v70
	v_and_b32_e32 v89, 0xffff0000, v82
	v_exp_f32_e32 v59, v59
	v_add_f32_e32 v62, 1.0, v62
	v_add_f32_e32 v70, 1.0, v70
	v_rcp_f32_e32 v90, v70
	v_mul_f32_e32 v70, 0xbfb8aa3b, v89
	v_exp_f32_e32 v70, v70
	v_add_f32_e32 v63, 1.0, v63
	v_rcp_f32_e32 v62, v62
	v_rcp_f32_e32 v63, v63
	v_add_f32_e32 v70, 1.0, v70
	v_rcp_f32_e32 v91, v70
	v_add_f32_e32 v58, 1.0, v58
	v_add_f32_e32 v59, 1.0, v59
	v_rcp_f32_e32 v58, v58
	v_rcp_f32_e32 v59, v59
	v_lshlrev_b32_e32 v74, 16, v78
	v_and_b32_e32 v75, 0xffff0000, v78
	v_pk_mul_f32 v[62:63], v[62:63], v[74:75]
	v_pk_mul_f32 v[74:75], v[90:91], v[88:89]
	v_lshlrev_b32_e32 v70, 16, v80
	v_pk_mul_f32 v[62:63], v[62:63], v[74:75]
	v_and_b32_e32 v71, 0xffff0000, v80
	v_lshlrev_b32_e32 v74, 16, v84
	v_and_b32_e32 v75, 0xffff0000, v84
	v_mul_f32_e32 v78, 0xbfb8aa3b, v74
	v_pk_mul_f32 v[58:59], v[58:59], v[70:71]
	v_mul_f32_e32 v70, 0xbfb8aa3b, v75
	v_exp_f32_e32 v78, v78
	v_exp_f32_e32 v70, v70
	v_add_f32_e32 v78, 1.0, v78
	v_add_f32_e32 v70, 1.0, v70
	v_rcp_f32_e32 v88, v78
	v_rcp_f32_e32 v89, v70
	s_nop 0
	v_pk_mul_f32 v[70:71], v[88:89], v[74:75]
	s_nop 0
	v_pk_mul_f32 v[70:71], v[58:59], v[70:71]
	v_add_f32_e32 v59, v60, v72
	v_mul_f32_e32 v59, 0xbfb8aa3b, v59
	v_exp_f32_e32 v59, v59
	v_add_f32_e32 v58, v64, v76
	v_mul_f32_e32 v58, 0xbfb8aa3b, v58
	v_exp_f32_e32 v58, v58
	v_add_f32_e32 v59, 1.0, v59
	v_rcp_f32_e32 v60, v59
	v_add_f32_e32 v59, v65, v77
	v_mul_f32_e32 v59, 0xbfb8aa3b, v59
	v_exp_f32_e32 v59, v59
	v_add_f32_e32 v58, 1.0, v58
	v_rcp_f32_e32 v58, v58
	v_lshlrev_b32_e32 v64, 16, v79
	v_add_f32_e32 v59, 1.0, v59
	v_rcp_f32_e32 v59, v59
	v_and_b32_e32 v65, 0xffff0000, v79
	v_lshlrev_b32_e32 v74, 16, v83
	v_and_b32_e32 v75, 0xffff0000, v83
	v_mul_f32_e32 v72, 0xbfb8aa3b, v74
	v_pk_mul_f32 v[58:59], v[58:59], v[64:65]
	v_mul_f32_e32 v64, 0xbfb8aa3b, v75
	v_exp_f32_e32 v72, v72
	v_exp_f32_e32 v64, v64
	v_add_f32_e32 v72, 1.0, v72
	v_add_f32_e32 v64, 1.0, v64
	v_rcp_f32_e32 v76, v72
	v_rcp_f32_e32 v77, v64
	v_lshlrev_b32_e32 v72, 16, v85
	v_pk_mul_f32 v[64:65], v[76:77], v[74:75]
	s_nop 0
	v_pk_mul_f32 v[64:65], v[58:59], v[64:65]
	v_add_f32_e32 v58, v61, v73
	v_mul_f32_e32 v58, 0xbfb8aa3b, v58
	v_exp_f32_e32 v58, v58
	v_and_b32_e32 v59, 0xffff0000, v81
	v_and_b32_e32 v73, 0xffff0000, v85
	v_mul_f32_e32 v74, 0xbfb8aa3b, v72
	v_add_f32_e32 v58, 1.0, v58
	v_rcp_f32_e32 v61, v58
	v_lshlrev_b32_e32 v58, 16, v81
	v_exp_f32_e32 v74, v74
	v_pk_mul_f32 v[58:59], v[60:61], v[58:59]
	v_mul_f32_e32 v60, 0xbfb8aa3b, v73
	v_exp_f32_e32 v60, v60
	v_add_f32_e32 v74, 1.0, v74
	v_rcp_f32_e32 v74, v74
	v_add_f32_e32 v60, 1.0, v60
	v_rcp_f32_e32 v75, v60
	s_nop 0
	v_pk_mul_f32 v[60:61], v[74:75], v[72:73]
	s_nop 0
	v_pk_mul_f32 v[72:73], v[58:59], v[60:61]
	v_cvt_pk_bf16_f32 v58, v62, v63
	v_lshlrev_b64 v[62:63], 12, v[86:87]
	v_lshl_add_u64 v[62:63], s[36:37], 0, v[62:63]
	v_cvt_pk_bf16_f32 v59, v64, v65
	v_cvt_pk_bf16_f32 v60, v70, v71
	v_cvt_pk_bf16_f32 v61, v72, v73
	v_lshl_add_u64 v[74:75], v[62:63], 0, v[150:151]
	global_store_dwordx4 v[74:75], v[58:61], off offset:2048
	global_load_dwordx4 v[58:61], v[148:149], off offset:528
	s_nop 0
	global_load_dwordx4 v[62:65], v[148:149], off offset:512
	global_load_dwordx4 v[70:73], v[68:69], off offset:256
	s_waitcnt vmcnt(0)
	v_add_f32_e32 v50, v50, v58
	global_load_dwordx4 v[66:69], v[66:67], off
	v_add_f32_e32 v54, v54, v62
	v_add_f32_e32 v55, v55, v63
	v_mul_f32_e32 v54, 0xbfb8aa3b, v54
	v_mul_f32_e32 v55, 0xbfb8aa3b, v55
	v_exp_f32_e32 v54, v54
	v_exp_f32_e32 v55, v55
	v_add_f32_e32 v51, v51, v59
	v_mul_f32_e32 v50, 0xbfb8aa3b, v50
	v_mul_f32_e32 v51, 0xbfb8aa3b, v51
	v_exp_f32_e32 v50, v50
	v_exp_f32_e32 v51, v51
	v_add_f32_e32 v54, 1.0, v54
	v_add_f32_e32 v55, 1.0, v55
	v_rcp_f32_e32 v54, v54
	v_rcp_f32_e32 v55, v55
	v_add_f32_e32 v50, 1.0, v50
	v_add_f32_e32 v51, 1.0, v51
	v_rcp_f32_e32 v50, v50
	v_rcp_f32_e32 v51, v51
	v_lshlrev_b32_e32 v62, 16, v70
	v_and_b32_e32 v63, 0xffff0000, v70
	v_pk_mul_f32 v[54:55], v[54:55], v[62:63]
	v_and_b32_e32 v59, 0xffff0000, v72
	v_add_u32_e32 v70, 0x90, v152
	s_waitcnt vmcnt(0)
	v_lshlrev_b32_e32 v76, 16, v66
	v_mul_f32_e32 v58, 0xbfb8aa3b, v76
	v_exp_f32_e32 v58, v58
	v_and_b32_e32 v77, 0xffff0000, v66
	v_add_f32_e32 v58, 1.0, v58
	v_rcp_f32_e32 v78, v58
	v_mul_f32_e32 v58, 0xbfb8aa3b, v77
	v_exp_f32_e32 v58, v58
	s_nop 0
	v_add_f32_e32 v58, 1.0, v58
	v_rcp_f32_e32 v79, v58
	v_lshlrev_b32_e32 v58, 16, v72
	v_pk_mul_f32 v[50:51], v[50:51], v[58:59]
	v_pk_mul_f32 v[62:63], v[78:79], v[76:77]
	s_nop 0
	v_pk_mul_f32 v[54:55], v[54:55], v[62:63]
	v_lshlrev_b32_e32 v62, 16, v68
	v_and_b32_e32 v63, 0xffff0000, v68
	v_mul_f32_e32 v66, 0xbfb8aa3b, v62
	v_mul_f32_e32 v58, 0xbfb8aa3b, v63
	v_exp_f32_e32 v66, v66
	v_exp_f32_e32 v58, v58
	v_add_f32_e32 v66, 1.0, v66
	v_add_f32_e32 v58, 1.0, v58
	v_rcp_f32_e32 v76, v66
	v_rcp_f32_e32 v77, v58
	s_nop 0
	v_pk_mul_f32 v[58:59], v[76:77], v[62:63]
	s_nop 0
	v_pk_mul_f32 v[58:59], v[50:51], v[58:59]
	v_add_f32_e32 v51, v52, v60
	v_mul_f32_e32 v51, 0xbfb8aa3b, v51
	v_exp_f32_e32 v51, v51
	v_add_f32_e32 v50, v56, v64
	v_mul_f32_e32 v50, 0xbfb8aa3b, v50
	v_exp_f32_e32 v50, v50
	v_add_f32_e32 v51, 1.0, v51
	v_rcp_f32_e32 v52, v51
	v_add_f32_e32 v51, v57, v65
	v_mul_f32_e32 v51, 0xbfb8aa3b, v51
	v_exp_f32_e32 v51, v51
	v_add_f32_e32 v50, 1.0, v50
	v_rcp_f32_e32 v50, v50
	v_lshlrev_b32_e32 v56, 16, v71
	v_add_f32_e32 v51, 1.0, v51
	v_rcp_f32_e32 v51, v51
	v_and_b32_e32 v57, 0xffff0000, v71
	v_lshlrev_b32_e32 v62, 16, v67
	v_and_b32_e32 v63, 0xffff0000, v67
	v_mul_f32_e32 v60, 0xbfb8aa3b, v62
	v_pk_mul_f32 v[50:51], v[50:51], v[56:57]
	v_mul_f32_e32 v56, 0xbfb8aa3b, v63
	v_exp_f32_e32 v60, v60
	v_exp_f32_e32 v56, v56
	v_ashrrev_i32_e32 v71, 31, v70
	v_add_f32_e32 v60, 1.0, v60
	v_add_f32_e32 v56, 1.0, v56
	v_rcp_f32_e32 v64, v60
	v_rcp_f32_e32 v65, v56
	v_lshlrev_b32_e32 v60, 16, v69
	v_pk_mul_f32 v[56:57], v[64:65], v[62:63]
	s_nop 0
	v_pk_mul_f32 v[56:57], v[50:51], v[56:57]
	v_add_f32_e32 v50, v53, v61
	v_mul_f32_e32 v50, 0xbfb8aa3b, v50
	v_exp_f32_e32 v50, v50
	v_and_b32_e32 v51, 0xffff0000, v73
	v_and_b32_e32 v61, 0xffff0000, v69
	v_mul_f32_e32 v62, 0xbfb8aa3b, v60
	v_add_f32_e32 v50, 1.0, v50
	v_rcp_f32_e32 v53, v50
	v_lshlrev_b32_e32 v50, 16, v73
	v_exp_f32_e32 v62, v62
	v_pk_mul_f32 v[50:51], v[52:53], v[50:51]
	v_mul_f32_e32 v52, 0xbfb8aa3b, v61
	v_exp_f32_e32 v52, v52
	v_add_f32_e32 v62, 1.0, v62
	v_rcp_f32_e32 v62, v62
	v_add_f32_e32 v52, 1.0, v52
	v_rcp_f32_e32 v63, v52
	s_nop 0
	v_pk_mul_f32 v[52:53], v[62:63], v[60:61]
	s_nop 0
	v_pk_mul_f32 v[60:61], v[50:51], v[52:53]
	v_cvt_pk_bf16_f32 v50, v54, v55
	v_cvt_pk_bf16_f32 v51, v56, v57
	v_cvt_pk_bf16_f32 v52, v58, v59
	v_cvt_pk_bf16_f32 v53, v60, v61
	global_store_dwordx4 v[74:75], v[50:53], off offset:2304
	global_load_dwordx4 v[54:57], v[148:149], off offset:16
	global_load_dwordx4 v[58:61], v[148:149], off
	v_lshlrev_b64 v[50:51], 11, v[70:71]
	v_lshl_add_u64 v[50:51], s[56:57], 0, v[50:51]
	v_lshl_add_u64 v[52:53], v[50:51], 0, v[150:151]
	v_mad_i64_i32 v[50:51], s[24:25], v70, s48, v[154:155]
	v_lshl_add_u64 v[50:51], v[50:51], 0, s[94:95]
	v_lshl_add_u64 v[66:67], v[50:51], 0, v[150:151]
	global_load_dwordx4 v[62:65], v[52:53], off
	v_lshl_add_u64 v[50:51], v[50:51], 0, v[156:157]
	global_load_dwordx4 v[66:69], v[66:67], off
	s_waitcnt vmcnt(0)
	v_add_f32_e32 v42, v42, v54
	v_add_f32_e32 v46, v46, v58
	v_add_f32_e32 v47, v47, v59
	v_mul_f32_e32 v46, 0xbfb8aa3b, v46
	v_mul_f32_e32 v47, 0xbfb8aa3b, v47
	v_exp_f32_e32 v46, v46
	v_exp_f32_e32 v47, v47
	v_add_f32_e32 v43, v43, v55
	v_mul_f32_e32 v42, 0xbfb8aa3b, v42
	v_mul_f32_e32 v43, 0xbfb8aa3b, v43
	v_exp_f32_e32 v42, v42
	v_lshlrev_b32_e32 v72, 16, v66
	v_mul_f32_e32 v54, 0xbfb8aa3b, v72
	v_exp_f32_e32 v54, v54
	v_and_b32_e32 v73, 0xffff0000, v66
	v_exp_f32_e32 v43, v43
	v_add_f32_e32 v46, 1.0, v46
	v_add_f32_e32 v54, 1.0, v54
	v_rcp_f32_e32 v74, v54
	v_mul_f32_e32 v54, 0xbfb8aa3b, v73
	v_exp_f32_e32 v54, v54
	v_add_f32_e32 v47, 1.0, v47
	v_rcp_f32_e32 v46, v46
	v_rcp_f32_e32 v47, v47
	v_add_f32_e32 v54, 1.0, v54
	v_rcp_f32_e32 v75, v54
	v_add_f32_e32 v42, 1.0, v42
	v_add_f32_e32 v43, 1.0, v43
	v_rcp_f32_e32 v42, v42
	v_rcp_f32_e32 v43, v43
	v_lshlrev_b32_e32 v58, 16, v62
	v_and_b32_e32 v59, 0xffff0000, v62
	v_pk_mul_f32 v[46:47], v[46:47], v[58:59]
	v_pk_mul_f32 v[58:59], v[74:75], v[72:73]
	v_lshlrev_b32_e32 v54, 16, v64
	v_pk_mul_f32 v[46:47], v[46:47], v[58:59]
	v_and_b32_e32 v55, 0xffff0000, v64
	v_lshlrev_b32_e32 v58, 16, v68
	v_and_b32_e32 v59, 0xffff0000, v68
	v_mul_f32_e32 v62, 0xbfb8aa3b, v58
	v_pk_mul_f32 v[42:43], v[42:43], v[54:55]
	v_mul_f32_e32 v54, 0xbfb8aa3b, v59
	v_exp_f32_e32 v62, v62
	v_exp_f32_e32 v54, v54
	v_add_f32_e32 v62, 1.0, v62
	v_add_f32_e32 v54, 1.0, v54
	v_rcp_f32_e32 v72, v62
	v_rcp_f32_e32 v73, v54
	s_nop 0
	v_pk_mul_f32 v[54:55], v[72:73], v[58:59]
	s_nop 0
	v_pk_mul_f32 v[54:55], v[42:43], v[54:55]
	v_add_f32_e32 v43, v44, v56
	v_mul_f32_e32 v43, 0xbfb8aa3b, v43
	v_exp_f32_e32 v43, v43
	v_add_f32_e32 v42, v48, v60
	v_mul_f32_e32 v42, 0xbfb8aa3b, v42
	v_exp_f32_e32 v42, v42
	v_add_f32_e32 v43, 1.0, v43
	v_rcp_f32_e32 v44, v43
	v_add_f32_e32 v43, v49, v61
	v_mul_f32_e32 v43, 0xbfb8aa3b, v43
	v_exp_f32_e32 v43, v43
	v_add_f32_e32 v42, 1.0, v42
	v_rcp_f32_e32 v42, v42
	v_lshlrev_b32_e32 v48, 16, v63
	v_add_f32_e32 v43, 1.0, v43
	v_rcp_f32_e32 v43, v43
	v_and_b32_e32 v49, 0xffff0000, v63
	v_lshlrev_b32_e32 v58, 16, v67
	v_and_b32_e32 v59, 0xffff0000, v67
	v_mul_f32_e32 v56, 0xbfb8aa3b, v58
	v_pk_mul_f32 v[42:43], v[42:43], v[48:49]
	v_mul_f32_e32 v48, 0xbfb8aa3b, v59
	v_exp_f32_e32 v56, v56
	v_exp_f32_e32 v48, v48
	v_add_f32_e32 v56, 1.0, v56
	v_add_f32_e32 v48, 1.0, v48
	v_rcp_f32_e32 v60, v56
	v_rcp_f32_e32 v61, v48
	v_lshlrev_b32_e32 v56, 16, v69
	v_pk_mul_f32 v[48:49], v[60:61], v[58:59]
	s_nop 0
	v_pk_mul_f32 v[48:49], v[42:43], v[48:49]
	v_add_f32_e32 v42, v45, v57
	v_mul_f32_e32 v42, 0xbfb8aa3b, v42
	v_exp_f32_e32 v42, v42
	v_and_b32_e32 v43, 0xffff0000, v65
	v_and_b32_e32 v57, 0xffff0000, v69
	v_mul_f32_e32 v58, 0xbfb8aa3b, v56
	v_add_f32_e32 v42, 1.0, v42
	v_rcp_f32_e32 v45, v42
	v_lshlrev_b32_e32 v42, 16, v65
	v_exp_f32_e32 v58, v58
	v_pk_mul_f32 v[42:43], v[44:45], v[42:43]
	v_mul_f32_e32 v44, 0xbfb8aa3b, v57
	v_exp_f32_e32 v44, v44
	v_add_f32_e32 v58, 1.0, v58
	v_rcp_f32_e32 v58, v58
	v_add_f32_e32 v44, 1.0, v44
	v_rcp_f32_e32 v59, v44
	s_nop 0
	v_pk_mul_f32 v[44:45], v[58:59], v[56:57]
	s_nop 0
	v_pk_mul_f32 v[56:57], v[42:43], v[44:45]
	v_cvt_pk_bf16_f32 v42, v46, v47
	v_lshlrev_b64 v[46:47], 12, v[70:71]
	v_lshl_add_u64 v[46:47], s[36:37], 0, v[46:47]
	v_cvt_pk_bf16_f32 v43, v48, v49
	v_cvt_pk_bf16_f32 v44, v54, v55
	v_cvt_pk_bf16_f32 v45, v56, v57
	v_lshl_add_u64 v[58:59], v[46:47], 0, v[150:151]
	global_store_dwordx4 v[58:59], v[42:45], off offset:2048
	global_load_dwordx4 v[42:45], v[148:149], off offset:528
	s_nop 0
	global_load_dwordx4 v[46:49], v[148:149], off offset:512
	global_load_dwordx4 v[54:57], v[52:53], off offset:256
	s_waitcnt vmcnt(0)
	v_add_f32_e32 v34, v34, v42
	global_load_dwordx4 v[50:53], v[50:51], off
	v_add_f32_e32 v38, v38, v46
	v_add_f32_e32 v39, v39, v47
	v_mul_f32_e32 v38, 0xbfb8aa3b, v38
	v_mul_f32_e32 v39, 0xbfb8aa3b, v39
	v_exp_f32_e32 v38, v38
	v_exp_f32_e32 v39, v39
	v_add_f32_e32 v35, v35, v43
	v_mul_f32_e32 v34, 0xbfb8aa3b, v34
	v_mul_f32_e32 v35, 0xbfb8aa3b, v35
	v_exp_f32_e32 v34, v34
	v_exp_f32_e32 v35, v35
	v_add_f32_e32 v38, 1.0, v38
	v_add_f32_e32 v39, 1.0, v39
	v_rcp_f32_e32 v38, v38
	v_rcp_f32_e32 v39, v39
	v_add_f32_e32 v34, 1.0, v34
	v_add_f32_e32 v35, 1.0, v35
	v_rcp_f32_e32 v34, v34
	v_rcp_f32_e32 v35, v35
	v_lshlrev_b32_e32 v46, 16, v54
	v_and_b32_e32 v47, 0xffff0000, v54
	v_pk_mul_f32 v[38:39], v[38:39], v[46:47]
	v_and_b32_e32 v43, 0xffff0000, v56
	v_add_u32_e32 v54, 0xa0, v152
	s_waitcnt vmcnt(0)
	v_lshlrev_b32_e32 v60, 16, v50
	v_mul_f32_e32 v42, 0xbfb8aa3b, v60
	v_exp_f32_e32 v42, v42
	v_and_b32_e32 v61, 0xffff0000, v50
	v_add_f32_e32 v42, 1.0, v42
	v_rcp_f32_e32 v62, v42
	v_mul_f32_e32 v42, 0xbfb8aa3b, v61
	v_exp_f32_e32 v42, v42
	s_nop 0
	v_add_f32_e32 v42, 1.0, v42
	v_rcp_f32_e32 v63, v42
	v_lshlrev_b32_e32 v42, 16, v56
	v_pk_mul_f32 v[34:35], v[34:35], v[42:43]
	v_pk_mul_f32 v[46:47], v[62:63], v[60:61]
	s_nop 0
	v_pk_mul_f32 v[38:39], v[38:39], v[46:47]
	v_lshlrev_b32_e32 v46, 16, v52
	v_and_b32_e32 v47, 0xffff0000, v52
	v_mul_f32_e32 v50, 0xbfb8aa3b, v46
	v_mul_f32_e32 v42, 0xbfb8aa3b, v47
	v_exp_f32_e32 v50, v50
	v_exp_f32_e32 v42, v42
	v_add_f32_e32 v50, 1.0, v50
	v_add_f32_e32 v42, 1.0, v42
	v_rcp_f32_e32 v60, v50
	v_rcp_f32_e32 v61, v42
	s_nop 0
	v_pk_mul_f32 v[42:43], v[60:61], v[46:47]
	s_nop 0
	v_pk_mul_f32 v[42:43], v[34:35], v[42:43]
	v_add_f32_e32 v35, v36, v44
	v_mul_f32_e32 v35, 0xbfb8aa3b, v35
	v_exp_f32_e32 v35, v35
	v_add_f32_e32 v34, v40, v48
	v_mul_f32_e32 v34, 0xbfb8aa3b, v34
	v_exp_f32_e32 v34, v34
	v_add_f32_e32 v35, 1.0, v35
	v_rcp_f32_e32 v36, v35
	v_add_f32_e32 v35, v41, v49
	v_mul_f32_e32 v35, 0xbfb8aa3b, v35
	v_exp_f32_e32 v35, v35
	v_add_f32_e32 v34, 1.0, v34
	v_rcp_f32_e32 v34, v34
	v_lshlrev_b32_e32 v40, 16, v55
	v_add_f32_e32 v35, 1.0, v35
	v_rcp_f32_e32 v35, v35
	v_and_b32_e32 v41, 0xffff0000, v55
	v_lshlrev_b32_e32 v46, 16, v51
	v_and_b32_e32 v47, 0xffff0000, v51
	v_mul_f32_e32 v44, 0xbfb8aa3b, v46
	v_pk_mul_f32 v[34:35], v[34:35], v[40:41]
	v_mul_f32_e32 v40, 0xbfb8aa3b, v47
	v_exp_f32_e32 v44, v44
	v_exp_f32_e32 v40, v40
	v_ashrrev_i32_e32 v55, 31, v54
	v_add_f32_e32 v44, 1.0, v44
	v_add_f32_e32 v40, 1.0, v40
	v_rcp_f32_e32 v48, v44
	v_rcp_f32_e32 v49, v40
	v_lshlrev_b32_e32 v44, 16, v53
	v_pk_mul_f32 v[40:41], v[48:49], v[46:47]
	s_nop 0
	v_pk_mul_f32 v[40:41], v[34:35], v[40:41]
	v_add_f32_e32 v34, v37, v45
	v_mul_f32_e32 v34, 0xbfb8aa3b, v34
	v_exp_f32_e32 v34, v34
	v_and_b32_e32 v35, 0xffff0000, v57
	v_and_b32_e32 v45, 0xffff0000, v53
	v_mul_f32_e32 v46, 0xbfb8aa3b, v44
	v_add_f32_e32 v34, 1.0, v34
	v_rcp_f32_e32 v37, v34
	v_lshlrev_b32_e32 v34, 16, v57
	v_exp_f32_e32 v46, v46
	v_pk_mul_f32 v[34:35], v[36:37], v[34:35]
	v_mul_f32_e32 v36, 0xbfb8aa3b, v45
	v_exp_f32_e32 v36, v36
	v_add_f32_e32 v46, 1.0, v46
	v_rcp_f32_e32 v46, v46
	v_add_f32_e32 v36, 1.0, v36
	v_rcp_f32_e32 v47, v36
	s_nop 0
	v_pk_mul_f32 v[36:37], v[46:47], v[44:45]
	s_nop 0
	v_pk_mul_f32 v[44:45], v[34:35], v[36:37]
	v_cvt_pk_bf16_f32 v34, v38, v39
	v_cvt_pk_bf16_f32 v35, v40, v41
	v_cvt_pk_bf16_f32 v36, v42, v43
	v_cvt_pk_bf16_f32 v37, v44, v45
	global_store_dwordx4 v[58:59], v[34:37], off offset:2304
	global_load_dwordx4 v[38:41], v[148:149], off offset:16
	global_load_dwordx4 v[42:45], v[148:149], off
	v_lshlrev_b64 v[34:35], 11, v[54:55]
	v_lshl_add_u64 v[34:35], s[56:57], 0, v[34:35]
	v_lshl_add_u64 v[36:37], v[34:35], 0, v[150:151]
	v_mad_i64_i32 v[34:35], s[24:25], v54, s48, v[154:155]
	v_lshl_add_u64 v[34:35], v[34:35], 0, s[94:95]
	v_lshl_add_u64 v[50:51], v[34:35], 0, v[150:151]
	global_load_dwordx4 v[46:49], v[36:37], off
	v_lshl_add_u64 v[34:35], v[34:35], 0, v[156:157]
	global_load_dwordx4 v[50:53], v[50:51], off
	s_waitcnt vmcnt(0)
	v_add_f32_e32 v26, v26, v38
	v_add_f32_e32 v30, v30, v42
	v_add_f32_e32 v31, v31, v43
	v_mul_f32_e32 v30, 0xbfb8aa3b, v30
	v_mul_f32_e32 v31, 0xbfb8aa3b, v31
	v_exp_f32_e32 v30, v30
	v_exp_f32_e32 v31, v31
	v_add_f32_e32 v27, v27, v39
	v_mul_f32_e32 v26, 0xbfb8aa3b, v26
	v_mul_f32_e32 v27, 0xbfb8aa3b, v27
	v_exp_f32_e32 v26, v26
	v_lshlrev_b32_e32 v56, 16, v50
	v_mul_f32_e32 v38, 0xbfb8aa3b, v56
	v_exp_f32_e32 v38, v38
	v_and_b32_e32 v57, 0xffff0000, v50
	v_exp_f32_e32 v27, v27
	v_add_f32_e32 v30, 1.0, v30
	v_add_f32_e32 v38, 1.0, v38
	v_rcp_f32_e32 v58, v38
	v_mul_f32_e32 v38, 0xbfb8aa3b, v57
	v_exp_f32_e32 v38, v38
	v_add_f32_e32 v31, 1.0, v31
	v_rcp_f32_e32 v30, v30
	v_rcp_f32_e32 v31, v31
	v_add_f32_e32 v38, 1.0, v38
	v_rcp_f32_e32 v59, v38
	v_add_f32_e32 v26, 1.0, v26
	v_add_f32_e32 v27, 1.0, v27
	v_rcp_f32_e32 v26, v26
	v_rcp_f32_e32 v27, v27
	v_lshlrev_b32_e32 v42, 16, v46
	v_and_b32_e32 v43, 0xffff0000, v46
	v_pk_mul_f32 v[30:31], v[30:31], v[42:43]
	v_pk_mul_f32 v[42:43], v[58:59], v[56:57]
	v_lshlrev_b32_e32 v38, 16, v48
	v_pk_mul_f32 v[30:31], v[30:31], v[42:43]
	v_and_b32_e32 v39, 0xffff0000, v48
	v_lshlrev_b32_e32 v42, 16, v52
	v_and_b32_e32 v43, 0xffff0000, v52
	v_mul_f32_e32 v46, 0xbfb8aa3b, v42
	v_pk_mul_f32 v[26:27], v[26:27], v[38:39]
	v_mul_f32_e32 v38, 0xbfb8aa3b, v43
	v_exp_f32_e32 v46, v46
	v_exp_f32_e32 v38, v38
	v_add_f32_e32 v46, 1.0, v46
	v_add_f32_e32 v38, 1.0, v38
	v_rcp_f32_e32 v56, v46
	v_rcp_f32_e32 v57, v38
	s_nop 0
	v_pk_mul_f32 v[38:39], v[56:57], v[42:43]
	s_nop 0
	v_pk_mul_f32 v[38:39], v[26:27], v[38:39]
	v_add_f32_e32 v27, v28, v40
	v_mul_f32_e32 v27, 0xbfb8aa3b, v27
	v_exp_f32_e32 v27, v27
	v_add_f32_e32 v26, v32, v44
	v_mul_f32_e32 v26, 0xbfb8aa3b, v26
	v_exp_f32_e32 v26, v26
	v_add_f32_e32 v27, 1.0, v27
	v_rcp_f32_e32 v28, v27
	v_add_f32_e32 v27, v33, v45
	v_mul_f32_e32 v27, 0xbfb8aa3b, v27
	v_exp_f32_e32 v27, v27
	v_add_f32_e32 v26, 1.0, v26
	v_rcp_f32_e32 v26, v26
	v_lshlrev_b32_e32 v32, 16, v47
	v_add_f32_e32 v27, 1.0, v27
	v_rcp_f32_e32 v27, v27
	v_and_b32_e32 v33, 0xffff0000, v47
	v_lshlrev_b32_e32 v42, 16, v51
	v_and_b32_e32 v43, 0xffff0000, v51
	v_mul_f32_e32 v40, 0xbfb8aa3b, v42
	v_pk_mul_f32 v[26:27], v[26:27], v[32:33]
	v_mul_f32_e32 v32, 0xbfb8aa3b, v43
	v_exp_f32_e32 v40, v40
	v_exp_f32_e32 v32, v32
	v_add_f32_e32 v40, 1.0, v40
	v_add_f32_e32 v32, 1.0, v32
	v_rcp_f32_e32 v44, v40
	v_rcp_f32_e32 v45, v32
	v_lshlrev_b32_e32 v40, 16, v53
	v_pk_mul_f32 v[32:33], v[44:45], v[42:43]
	s_nop 0
	v_pk_mul_f32 v[32:33], v[26:27], v[32:33]
	v_add_f32_e32 v26, v29, v41
	v_mul_f32_e32 v26, 0xbfb8aa3b, v26
	v_exp_f32_e32 v26, v26
	v_and_b32_e32 v27, 0xffff0000, v49
	v_and_b32_e32 v41, 0xffff0000, v53
	v_mul_f32_e32 v42, 0xbfb8aa3b, v40
	v_add_f32_e32 v26, 1.0, v26
	v_rcp_f32_e32 v29, v26
	v_lshlrev_b32_e32 v26, 16, v49
	v_exp_f32_e32 v42, v42
	v_pk_mul_f32 v[26:27], v[28:29], v[26:27]
	v_mul_f32_e32 v28, 0xbfb8aa3b, v41
	v_exp_f32_e32 v28, v28
	v_add_f32_e32 v42, 1.0, v42
	v_rcp_f32_e32 v42, v42
	v_add_f32_e32 v28, 1.0, v28
	v_rcp_f32_e32 v43, v28
	s_nop 0
	v_pk_mul_f32 v[28:29], v[42:43], v[40:41]
	s_nop 0
	v_pk_mul_f32 v[40:41], v[26:27], v[28:29]
	v_cvt_pk_bf16_f32 v26, v30, v31
	v_lshlrev_b64 v[30:31], 12, v[54:55]
	v_lshl_add_u64 v[30:31], s[36:37], 0, v[30:31]
	v_cvt_pk_bf16_f32 v27, v32, v33
	v_cvt_pk_bf16_f32 v28, v38, v39
	v_cvt_pk_bf16_f32 v29, v40, v41
	v_lshl_add_u64 v[42:43], v[30:31], 0, v[150:151]
	global_store_dwordx4 v[42:43], v[26:29], off offset:2048
	global_load_dwordx4 v[26:29], v[148:149], off offset:528
	s_nop 0
	global_load_dwordx4 v[30:33], v[148:149], off offset:512
	global_load_dwordx4 v[38:41], v[36:37], off offset:256
	s_waitcnt vmcnt(0)
	v_add_f32_e32 v18, v18, v26
	global_load_dwordx4 v[34:37], v[34:35], off
	v_add_f32_e32 v22, v22, v30
	v_add_f32_e32 v23, v23, v31
	v_mul_f32_e32 v22, 0xbfb8aa3b, v22
	v_mul_f32_e32 v23, 0xbfb8aa3b, v23
	v_exp_f32_e32 v22, v22
	v_exp_f32_e32 v23, v23
	v_add_f32_e32 v19, v19, v27
	v_mul_f32_e32 v18, 0xbfb8aa3b, v18
	v_mul_f32_e32 v19, 0xbfb8aa3b, v19
	v_exp_f32_e32 v18, v18
	v_exp_f32_e32 v19, v19
	v_add_f32_e32 v22, 1.0, v22
	v_add_f32_e32 v23, 1.0, v23
	v_rcp_f32_e32 v22, v22
	v_rcp_f32_e32 v23, v23
	v_add_f32_e32 v18, 1.0, v18
	v_add_f32_e32 v19, 1.0, v19
	v_rcp_f32_e32 v18, v18
	v_rcp_f32_e32 v19, v19
	v_lshlrev_b32_e32 v30, 16, v38
	v_and_b32_e32 v31, 0xffff0000, v38
	v_pk_mul_f32 v[22:23], v[22:23], v[30:31]
	v_and_b32_e32 v27, 0xffff0000, v40
	v_add_u32_e32 v38, 0xb0, v152
	s_waitcnt vmcnt(0)
	v_lshlrev_b32_e32 v44, 16, v34
	v_mul_f32_e32 v26, 0xbfb8aa3b, v44
	v_exp_f32_e32 v26, v26
	v_and_b32_e32 v45, 0xffff0000, v34
	v_add_f32_e32 v26, 1.0, v26
	v_rcp_f32_e32 v46, v26
	v_mul_f32_e32 v26, 0xbfb8aa3b, v45
	v_exp_f32_e32 v26, v26
	s_nop 0
	v_add_f32_e32 v26, 1.0, v26
	v_rcp_f32_e32 v47, v26
	v_lshlrev_b32_e32 v26, 16, v40
	v_pk_mul_f32 v[18:19], v[18:19], v[26:27]
	v_pk_mul_f32 v[30:31], v[46:47], v[44:45]
	s_nop 0
	v_pk_mul_f32 v[22:23], v[22:23], v[30:31]
	v_lshlrev_b32_e32 v30, 16, v36
	v_and_b32_e32 v31, 0xffff0000, v36
	v_mul_f32_e32 v34, 0xbfb8aa3b, v30
	v_mul_f32_e32 v26, 0xbfb8aa3b, v31
	v_exp_f32_e32 v34, v34
	v_exp_f32_e32 v26, v26
	v_add_f32_e32 v34, 1.0, v34
	v_add_f32_e32 v26, 1.0, v26
	v_rcp_f32_e32 v44, v34
	v_rcp_f32_e32 v45, v26
	s_nop 0
	v_pk_mul_f32 v[26:27], v[44:45], v[30:31]
	s_nop 0
	v_pk_mul_f32 v[26:27], v[18:19], v[26:27]
	v_add_f32_e32 v19, v20, v28
	v_mul_f32_e32 v19, 0xbfb8aa3b, v19
	v_exp_f32_e32 v19, v19
	v_add_f32_e32 v18, v24, v32
	v_mul_f32_e32 v18, 0xbfb8aa3b, v18
	v_exp_f32_e32 v18, v18
	v_add_f32_e32 v19, 1.0, v19
	v_rcp_f32_e32 v20, v19
	v_add_f32_e32 v19, v25, v33
	v_mul_f32_e32 v19, 0xbfb8aa3b, v19
	v_exp_f32_e32 v19, v19
	v_add_f32_e32 v18, 1.0, v18
	v_rcp_f32_e32 v18, v18
	v_lshlrev_b32_e32 v24, 16, v39
	v_add_f32_e32 v19, 1.0, v19
	v_rcp_f32_e32 v19, v19
	v_and_b32_e32 v25, 0xffff0000, v39
	v_lshlrev_b32_e32 v30, 16, v35
	v_and_b32_e32 v31, 0xffff0000, v35
	v_mul_f32_e32 v28, 0xbfb8aa3b, v30
	v_pk_mul_f32 v[18:19], v[18:19], v[24:25]
	v_mul_f32_e32 v24, 0xbfb8aa3b, v31
	v_exp_f32_e32 v28, v28
	v_exp_f32_e32 v24, v24
	v_ashrrev_i32_e32 v39, 31, v38
	v_add_f32_e32 v28, 1.0, v28
	v_add_f32_e32 v24, 1.0, v24
	v_rcp_f32_e32 v32, v28
	v_rcp_f32_e32 v33, v24
	v_lshlrev_b32_e32 v28, 16, v37
	v_pk_mul_f32 v[24:25], v[32:33], v[30:31]
	s_nop 0
	v_pk_mul_f32 v[24:25], v[18:19], v[24:25]
	v_add_f32_e32 v18, v21, v29
	v_mul_f32_e32 v18, 0xbfb8aa3b, v18
	v_exp_f32_e32 v18, v18
	v_and_b32_e32 v19, 0xffff0000, v41
	v_and_b32_e32 v29, 0xffff0000, v37
	v_mul_f32_e32 v30, 0xbfb8aa3b, v28
	v_add_f32_e32 v18, 1.0, v18
	v_rcp_f32_e32 v21, v18
	v_lshlrev_b32_e32 v18, 16, v41
	v_exp_f32_e32 v30, v30
	v_pk_mul_f32 v[18:19], v[20:21], v[18:19]
	v_mul_f32_e32 v20, 0xbfb8aa3b, v29
	v_exp_f32_e32 v20, v20
	v_add_f32_e32 v30, 1.0, v30
	v_rcp_f32_e32 v30, v30
	v_add_f32_e32 v20, 1.0, v20
	v_rcp_f32_e32 v31, v20
	s_nop 0
	v_pk_mul_f32 v[20:21], v[30:31], v[28:29]
	s_nop 0
	v_pk_mul_f32 v[28:29], v[18:19], v[20:21]
	v_cvt_pk_bf16_f32 v18, v22, v23
	v_cvt_pk_bf16_f32 v19, v24, v25
	v_cvt_pk_bf16_f32 v20, v26, v27
	v_cvt_pk_bf16_f32 v21, v28, v29
	global_store_dwordx4 v[42:43], v[18:21], off offset:2304
	global_load_dwordx4 v[22:25], v[148:149], off offset:16
	global_load_dwordx4 v[26:29], v[148:149], off
	v_lshlrev_b64 v[18:19], 11, v[38:39]
	v_lshl_add_u64 v[18:19], s[56:57], 0, v[18:19]
	v_lshl_add_u64 v[20:21], v[18:19], 0, v[150:151]
	v_mad_i64_i32 v[18:19], s[24:25], v38, s48, v[154:155]
	v_lshl_add_u64 v[18:19], v[18:19], 0, s[94:95]
	v_lshl_add_u64 v[34:35], v[18:19], 0, v[150:151]
	global_load_dwordx4 v[30:33], v[20:21], off
	v_lshl_add_u64 v[18:19], v[18:19], 0, v[156:157]
	global_load_dwordx4 v[34:37], v[34:35], off
	s_waitcnt vmcnt(0)
	v_add_f32_e32 v10, v10, v22
	v_add_f32_e32 v14, v14, v26
	v_add_f32_e32 v15, v15, v27
	v_mul_f32_e32 v14, 0xbfb8aa3b, v14
	v_mul_f32_e32 v15, 0xbfb8aa3b, v15
	v_exp_f32_e32 v14, v14
	v_exp_f32_e32 v15, v15
	v_add_f32_e32 v11, v11, v23
	v_mul_f32_e32 v10, 0xbfb8aa3b, v10
	v_mul_f32_e32 v11, 0xbfb8aa3b, v11
	v_exp_f32_e32 v10, v10
	v_lshlrev_b32_e32 v40, 16, v34
	v_mul_f32_e32 v22, 0xbfb8aa3b, v40
	v_exp_f32_e32 v22, v22
	v_and_b32_e32 v41, 0xffff0000, v34
	v_exp_f32_e32 v11, v11
	v_add_f32_e32 v14, 1.0, v14
	v_add_f32_e32 v22, 1.0, v22
	v_rcp_f32_e32 v42, v22
	v_mul_f32_e32 v22, 0xbfb8aa3b, v41
	v_exp_f32_e32 v22, v22
	v_add_f32_e32 v15, 1.0, v15
	v_rcp_f32_e32 v14, v14
	v_rcp_f32_e32 v15, v15
	v_add_f32_e32 v22, 1.0, v22
	v_rcp_f32_e32 v43, v22
	v_add_f32_e32 v10, 1.0, v10
	v_add_f32_e32 v11, 1.0, v11
	v_rcp_f32_e32 v10, v10
	v_rcp_f32_e32 v11, v11
	v_lshlrev_b32_e32 v26, 16, v30
	v_and_b32_e32 v27, 0xffff0000, v30
	v_pk_mul_f32 v[14:15], v[14:15], v[26:27]
	v_pk_mul_f32 v[26:27], v[42:43], v[40:41]
	v_lshlrev_b32_e32 v22, 16, v32
	v_pk_mul_f32 v[14:15], v[14:15], v[26:27]
	v_and_b32_e32 v23, 0xffff0000, v32
	v_lshlrev_b32_e32 v26, 16, v36
	v_and_b32_e32 v27, 0xffff0000, v36
	v_mul_f32_e32 v30, 0xbfb8aa3b, v26
	v_pk_mul_f32 v[10:11], v[10:11], v[22:23]
	v_mul_f32_e32 v22, 0xbfb8aa3b, v27
	v_exp_f32_e32 v30, v30
	v_exp_f32_e32 v22, v22
	v_add_f32_e32 v30, 1.0, v30
	v_add_f32_e32 v22, 1.0, v22
	v_rcp_f32_e32 v40, v30
	v_rcp_f32_e32 v41, v22
	s_nop 0
	v_pk_mul_f32 v[22:23], v[40:41], v[26:27]
	s_nop 0
	v_pk_mul_f32 v[22:23], v[10:11], v[22:23]
	v_add_f32_e32 v11, v12, v24
	v_mul_f32_e32 v11, 0xbfb8aa3b, v11
	v_exp_f32_e32 v11, v11
	v_add_f32_e32 v10, v16, v28
	v_mul_f32_e32 v10, 0xbfb8aa3b, v10
	v_exp_f32_e32 v10, v10
	v_add_f32_e32 v11, 1.0, v11
	v_rcp_f32_e32 v12, v11
	v_add_f32_e32 v11, v17, v29
	v_mul_f32_e32 v11, 0xbfb8aa3b, v11
	v_exp_f32_e32 v11, v11
	v_add_f32_e32 v10, 1.0, v10
	v_rcp_f32_e32 v10, v10
	v_lshlrev_b32_e32 v16, 16, v31
	v_add_f32_e32 v11, 1.0, v11
	v_rcp_f32_e32 v11, v11
	v_and_b32_e32 v17, 0xffff0000, v31
	v_lshlrev_b32_e32 v26, 16, v35
	v_and_b32_e32 v27, 0xffff0000, v35
	v_mul_f32_e32 v24, 0xbfb8aa3b, v26
	v_pk_mul_f32 v[10:11], v[10:11], v[16:17]
	v_mul_f32_e32 v16, 0xbfb8aa3b, v27
	v_exp_f32_e32 v24, v24
	v_exp_f32_e32 v16, v16
	v_add_f32_e32 v24, 1.0, v24
	v_add_f32_e32 v16, 1.0, v16
	v_rcp_f32_e32 v28, v24
	v_rcp_f32_e32 v29, v16
	v_lshlrev_b32_e32 v24, 16, v37
	v_pk_mul_f32 v[16:17], v[28:29], v[26:27]
	s_nop 0
	v_pk_mul_f32 v[16:17], v[10:11], v[16:17]
	v_add_f32_e32 v10, v13, v25
	v_mul_f32_e32 v10, 0xbfb8aa3b, v10
	v_exp_f32_e32 v10, v10
	v_and_b32_e32 v11, 0xffff0000, v33
	v_and_b32_e32 v25, 0xffff0000, v37
	v_mul_f32_e32 v26, 0xbfb8aa3b, v24
	v_add_f32_e32 v10, 1.0, v10
	v_rcp_f32_e32 v13, v10
	v_lshlrev_b32_e32 v10, 16, v33
	v_exp_f32_e32 v26, v26
	v_pk_mul_f32 v[10:11], v[12:13], v[10:11]
	v_mul_f32_e32 v12, 0xbfb8aa3b, v25
	v_exp_f32_e32 v12, v12
	v_add_f32_e32 v26, 1.0, v26
	v_rcp_f32_e32 v26, v26
	v_add_f32_e32 v12, 1.0, v12
	v_rcp_f32_e32 v27, v12
	s_nop 0
	v_pk_mul_f32 v[12:13], v[26:27], v[24:25]
	s_nop 0
	v_pk_mul_f32 v[24:25], v[10:11], v[12:13]
	v_cvt_pk_bf16_f32 v10, v14, v15
	v_lshlrev_b64 v[14:15], 12, v[38:39]
	v_lshl_add_u64 v[14:15], s[36:37], 0, v[14:15]
	v_cvt_pk_bf16_f32 v11, v16, v17
	v_cvt_pk_bf16_f32 v12, v22, v23
	v_cvt_pk_bf16_f32 v13, v24, v25
	v_lshl_add_u64 v[26:27], v[14:15], 0, v[150:151]
	global_store_dwordx4 v[26:27], v[10:13], off offset:2048
	global_load_dwordx4 v[10:13], v[148:149], off offset:528
	s_nop 0
	global_load_dwordx4 v[14:17], v[148:149], off offset:512
	global_load_dwordx4 v[22:25], v[20:21], off offset:256
	s_waitcnt vmcnt(0)
	v_add_f32_e32 v2, v2, v10
	global_load_dwordx4 v[18:21], v[18:19], off
	v_add_f32_e32 v6, v6, v14
	v_add_f32_e32 v7, v7, v15
	v_mul_f32_e32 v6, 0xbfb8aa3b, v6
	v_mul_f32_e32 v7, 0xbfb8aa3b, v7
	v_exp_f32_e32 v6, v6
	v_exp_f32_e32 v7, v7
	v_add_f32_e32 v3, v3, v11
	v_mul_f32_e32 v2, 0xbfb8aa3b, v2
	v_mul_f32_e32 v3, 0xbfb8aa3b, v3
	v_exp_f32_e32 v2, v2
	v_exp_f32_e32 v3, v3
	v_add_f32_e32 v6, 1.0, v6
	v_add_f32_e32 v7, 1.0, v7
	v_rcp_f32_e32 v6, v6
	v_rcp_f32_e32 v7, v7
	v_add_f32_e32 v2, 1.0, v2
	v_add_f32_e32 v3, 1.0, v3
	v_rcp_f32_e32 v2, v2
	v_rcp_f32_e32 v3, v3
	v_lshlrev_b32_e32 v14, 16, v22
	v_and_b32_e32 v15, 0xffff0000, v22
	v_pk_mul_f32 v[6:7], v[6:7], v[14:15]
	v_and_b32_e32 v11, 0xffff0000, v24
	s_waitcnt vmcnt(0)
	v_lshlrev_b32_e32 v28, 16, v18
	v_mul_f32_e32 v10, 0xbfb8aa3b, v28
	v_exp_f32_e32 v10, v10
	v_and_b32_e32 v29, 0xffff0000, v18
	v_add_f32_e32 v10, 1.0, v10
	v_rcp_f32_e32 v30, v10
	v_mul_f32_e32 v10, 0xbfb8aa3b, v29
	v_exp_f32_e32 v10, v10
	s_nop 0
	v_add_f32_e32 v10, 1.0, v10
	v_rcp_f32_e32 v31, v10
	v_lshlrev_b32_e32 v10, 16, v24
	v_pk_mul_f32 v[2:3], v[2:3], v[10:11]
	v_pk_mul_f32 v[14:15], v[30:31], v[28:29]
	s_nop 0
	v_pk_mul_f32 v[6:7], v[6:7], v[14:15]
	v_lshlrev_b32_e32 v14, 16, v20
	v_and_b32_e32 v15, 0xffff0000, v20
	v_mul_f32_e32 v18, 0xbfb8aa3b, v14
	v_mul_f32_e32 v10, 0xbfb8aa3b, v15
	v_exp_f32_e32 v18, v18
	v_exp_f32_e32 v10, v10
	v_add_f32_e32 v18, 1.0, v18
	v_add_f32_e32 v10, 1.0, v10
	v_rcp_f32_e32 v28, v18
	v_rcp_f32_e32 v29, v10
	s_nop 0
	v_pk_mul_f32 v[10:11], v[28:29], v[14:15]
	s_nop 0
	v_pk_mul_f32 v[10:11], v[2:3], v[10:11]
	v_add_f32_e32 v3, v4, v12
	v_mul_f32_e32 v3, 0xbfb8aa3b, v3
	v_exp_f32_e32 v3, v3
	v_add_f32_e32 v2, v8, v16
	v_mul_f32_e32 v2, 0xbfb8aa3b, v2
	v_exp_f32_e32 v2, v2
	v_add_f32_e32 v3, 1.0, v3
	v_rcp_f32_e32 v4, v3
	v_add_f32_e32 v3, v9, v17
	v_mul_f32_e32 v3, 0xbfb8aa3b, v3
	v_exp_f32_e32 v3, v3
	v_add_f32_e32 v2, 1.0, v2
	v_rcp_f32_e32 v2, v2
	v_lshlrev_b32_e32 v8, 16, v23
	v_add_f32_e32 v3, 1.0, v3
	v_rcp_f32_e32 v3, v3
	v_and_b32_e32 v9, 0xffff0000, v23
	v_lshlrev_b32_e32 v14, 16, v19
	v_and_b32_e32 v15, 0xffff0000, v19
	v_mul_f32_e32 v12, 0xbfb8aa3b, v14
	v_pk_mul_f32 v[2:3], v[2:3], v[8:9]
	v_mul_f32_e32 v8, 0xbfb8aa3b, v15
	v_exp_f32_e32 v12, v12
	v_exp_f32_e32 v8, v8
	v_add_f32_e32 v12, 1.0, v12
	v_add_f32_e32 v8, 1.0, v8
	v_rcp_f32_e32 v16, v12
	v_rcp_f32_e32 v17, v8
	v_lshlrev_b32_e32 v12, 16, v21
	v_pk_mul_f32 v[8:9], v[16:17], v[14:15]
	s_nop 0
	v_pk_mul_f32 v[8:9], v[2:3], v[8:9]
	v_add_f32_e32 v2, v5, v13
	v_mul_f32_e32 v2, 0xbfb8aa3b, v2
	v_exp_f32_e32 v2, v2
	v_and_b32_e32 v3, 0xffff0000, v25
	v_and_b32_e32 v13, 0xffff0000, v21
	v_mul_f32_e32 v14, 0xbfb8aa3b, v12
	v_add_f32_e32 v2, 1.0, v2
	v_rcp_f32_e32 v5, v2
	v_lshlrev_b32_e32 v2, 16, v25
	v_exp_f32_e32 v14, v14
	v_pk_mul_f32 v[2:3], v[4:5], v[2:3]
	v_mul_f32_e32 v4, 0xbfb8aa3b, v13
	v_exp_f32_e32 v4, v4
	v_add_f32_e32 v14, 1.0, v14
	v_rcp_f32_e32 v14, v14
	v_add_f32_e32 v4, 1.0, v4
	v_rcp_f32_e32 v15, v4
	s_nop 0
	v_pk_mul_f32 v[4:5], v[14:15], v[12:13]
	s_nop 0
	v_pk_mul_f32 v[12:13], v[2:3], v[4:5]
	v_cvt_pk_bf16_f32 v2, v6, v7
	v_cvt_pk_bf16_f32 v3, v8, v9
	v_cvt_pk_bf16_f32 v4, v10, v11
	v_cvt_pk_bf16_f32 v5, v12, v13
	global_store_dwordx4 v[26:27], v[2:5], off offset:2304
	s_cbranch_vccz .LBB0_970
	v_readlane_b32 s4, v254, 12
	s_waitcnt vmcnt(0)
	v_readlane_b32 s5, v254, 13
	s_andn2_b64 vcc, exec, s[4:5]
	s_cbranch_vccnz .LBB0_981
	s_barrier

.LBB0_1044:
	s_add_u32 s2, s68, 0xfff80080
	s_addc_u32 s17, s69, -1
	s_add_i32 s26, 0, 0x10000
	v_add_u32_e32 v156, s26, v141
	ds_read_b128 v[144:147], v156
	ds_read_b128 v[148:151], v156 offset:1024
	ds_read_b128 v[152:155], v156 offset:2048
	ds_read_b128 v[156:159], v156 offset:3072
	s_cmp_eq_u32 s44, 28
	s_cselect_b32 s73, s55, s17
	s_cselect_b32 s72, s24, s2
	s_cselect_b32 s71, s25, s92
	s_cselect_b32 s70, s43, s83
	v_lshl_add_u64 v[164:165], s[68:69], 0, v[136:137]
	s_add_i32 m0, s58, 0xc000
	ds_read_b128 v[160:163], v143
	ds_read_b128 v[188:191], v143 offset:1024
	ds_read_b128 v[192:195], v143 offset:2048
	ds_read_b128 v[196:199], v143 offset:3072
	ds_read_b128 v[200:203], v143 offset:4096
	ds_read_b128 v[216:219], v143 offset:5120
	ds_read_b128 v[220:223], v143 offset:6144
	ds_read_b128 v[224:227], v143 offset:7168
	global_load_lds_dwordx4 v[164:165], off
	v_lshl_add_u64 v[164:165], s[68:69], 0, v[138:139]
	s_add_i32 m0, s58, 0xe000
	s_nop 0
	global_load_lds_dwordx4 v[164:165], off
	s_waitcnt lgkmcnt(8)
	s_barrier
	s_waitcnt lgkmcnt(7)
	v_mfma_f32_16x16x32_bf16 v[126:129], v[144:147], v[160:163], v[126:129]
	v_mfma_f32_16x16x32_bf16 v[122:125], v[152:155], v[160:163], v[122:125]
	s_waitcnt lgkmcnt(5)
	v_mfma_f32_16x16x32_bf16 v[118:121], v[144:147], v[192:195], v[118:121]
	v_mfma_f32_16x16x32_bf16 v[114:117], v[152:155], v[192:195], v[114:117]
	s_waitcnt lgkmcnt(3)
	v_mfma_f32_16x16x32_bf16 v[102:105], v[144:147], v[200:203], v[102:105]
	v_mfma_f32_16x16x32_bf16 v[98:101], v[152:155], v[200:203], v[98:101]
	s_waitcnt lgkmcnt(1)
	v_mfma_f32_16x16x32_bf16 v[86:89], v[144:147], v[220:223], v[86:89]
	v_mfma_f32_16x16x32_bf16 v[82:85], v[152:155], v[220:223], v[82:85]
	v_mfma_f32_16x16x32_bf16 v[126:129], v[148:151], v[188:191], v[126:129]
	v_mfma_f32_16x16x32_bf16 v[122:125], v[156:159], v[188:191], v[122:125]
	v_mfma_f32_16x16x32_bf16 v[118:121], v[148:151], v[196:199], v[118:121]
	v_mfma_f32_16x16x32_bf16 v[114:117], v[156:159], v[196:199], v[114:117]
	v_mfma_f32_16x16x32_bf16 v[102:105], v[148:151], v[216:219], v[102:105]
	v_mfma_f32_16x16x32_bf16 v[98:101], v[156:159], v[216:219], v[98:101]
	s_waitcnt lgkmcnt(0)
	v_mfma_f32_16x16x32_bf16 v[86:89], v[148:151], v[224:227], v[86:89]
	v_mfma_f32_16x16x32_bf16 v[82:85], v[156:159], v[224:227], v[82:85]
	s_barrier
	s_add_i32 s2, 0, 0x14000
	v_add_u32_e32 v164, s2, v141
	s_add_i32 s17, s26, s3
	ds_read_b128 v[228:231], v164
	ds_read_b128 v[232:235], v164 offset:1024
	ds_read_b128 v[236:239], v164 offset:2048
	ds_read_b128 v[240:243], v164 offset:3072
	v_lshl_add_u64 v[164:165], s[70:71], 0, v[0:1]
	s_mov_b32 m0, s17
	v_lshl_add_u64 v[204:205], s[70:71], 0, v[130:131]
	global_load_lds_dwordx4 v[164:165], off
	s_add_i32 m0, s17, 0x2000
	s_nop 0
	global_load_lds_dwordx4 v[204:205], off
	s_barrier
	s_waitcnt lgkmcnt(3)
	v_mfma_f32_16x16x32_bf16 v[110:113], v[228:231], v[160:163], v[110:113]
	s_waitcnt lgkmcnt(1)
	v_mfma_f32_16x16x32_bf16 v[106:109], v[236:239], v[160:163], v[106:109]
	v_mfma_f32_16x16x32_bf16 v[94:97], v[228:231], v[192:195], v[94:97]
	v_mfma_f32_16x16x32_bf16 v[90:93], v[236:239], v[192:195], v[90:93]
	v_mfma_f32_16x16x32_bf16 v[78:81], v[228:231], v[200:203], v[78:81]
	v_mfma_f32_16x16x32_bf16 v[74:77], v[236:239], v[200:203], v[74:77]
	v_mfma_f32_16x16x32_bf16 v[70:73], v[228:231], v[220:223], v[70:73]
	v_mfma_f32_16x16x32_bf16 v[66:69], v[236:239], v[220:223], v[66:69]
	v_mfma_f32_16x16x32_bf16 v[110:113], v[232:235], v[188:191], v[110:113]
	s_waitcnt lgkmcnt(0)
	v_mfma_f32_16x16x32_bf16 v[106:109], v[240:243], v[188:191], v[106:109]
	v_mfma_f32_16x16x32_bf16 v[94:97], v[232:235], v[196:199], v[94:97]
	v_mfma_f32_16x16x32_bf16 v[90:93], v[240:243], v[196:199], v[90:93]
	v_mfma_f32_16x16x32_bf16 v[78:81], v[232:235], v[216:219], v[78:81]
	v_mfma_f32_16x16x32_bf16 v[74:77], v[240:243], v[216:219], v[74:77]
	v_mfma_f32_16x16x32_bf16 v[70:73], v[232:235], v[224:227], v[70:73]
	v_mfma_f32_16x16x32_bf16 v[66:69], v[240:243], v[224:227], v[66:69]
	s_mov_b32 m0, s58
	v_lshl_add_u64 v[244:245], s[72:73], 0, v[134:135]
	s_barrier
	ds_read_b128 v[160:163], v143 offset:16384
	ds_read_b128 v[188:191], v143 offset:17408
	ds_read_b128 v[192:195], v143 offset:18432
	ds_read_b128 v[196:199], v143 offset:19456
	ds_read_b128 v[200:203], v143 offset:20480
	ds_read_b128 v[216:219], v143 offset:21504
	ds_read_b128 v[220:223], v143 offset:22528
	ds_read_b128 v[224:227], v143 offset:23552
	global_load_lds_dwordx4 v[244:245], off
	v_lshl_add_u64 v[246:247], s[72:73], 0, v[132:133]
	s_mov_b32 m0, s74
	s_nop 0
	global_load_lds_dwordx4 v[246:247], off
	s_barrier
	s_waitcnt lgkmcnt(7)
	v_mfma_f32_16x16x32_bf16 v[62:65], v[144:147], v[160:163], v[62:65]
	v_mfma_f32_16x16x32_bf16 v[58:61], v[152:155], v[160:163], v[58:61]
	s_waitcnt lgkmcnt(5)
	v_mfma_f32_16x16x32_bf16 v[54:57], v[144:147], v[192:195], v[54:57]
	v_mfma_f32_16x16x32_bf16 v[50:53], v[152:155], v[192:195], v[50:53]
	s_waitcnt lgkmcnt(3)
	v_mfma_f32_16x16x32_bf16 v[38:41], v[144:147], v[200:203], v[38:41]
	v_mfma_f32_16x16x32_bf16 v[34:37], v[152:155], v[200:203], v[34:37]
	s_waitcnt lgkmcnt(1)
	v_mfma_f32_16x16x32_bf16 v[22:25], v[144:147], v[220:223], v[22:25]
	v_mfma_f32_16x16x32_bf16 v[18:21], v[152:155], v[220:223], v[18:21]
	v_mfma_f32_16x16x32_bf16 v[62:65], v[148:151], v[188:191], v[62:65]
	v_mfma_f32_16x16x32_bf16 v[58:61], v[156:159], v[188:191], v[58:61]
	v_mfma_f32_16x16x32_bf16 v[54:57], v[148:151], v[196:199], v[54:57]
	v_mfma_f32_16x16x32_bf16 v[50:53], v[156:159], v[196:199], v[50:53]
	v_mfma_f32_16x16x32_bf16 v[38:41], v[148:151], v[216:219], v[38:41]
	v_mfma_f32_16x16x32_bf16 v[34:37], v[156:159], v[216:219], v[34:37]
	s_waitcnt lgkmcnt(0)
	v_mfma_f32_16x16x32_bf16 v[22:25], v[148:151], v[224:227], v[22:25]
	v_mfma_f32_16x16x32_bf16 v[18:21], v[156:159], v[224:227], v[18:21]
	s_barrier
	s_add_u32 s26, s70, 0x80000
	s_addc_u32 s27, s71, 0
	s_add_i32 s2, s2, s3
	v_lshl_add_u64 v[144:145], s[26:27], 0, v[0:1]
	s_mov_b32 m0, s2
	s_nop 0
	global_load_lds_dwordx4 v[144:145], off
	v_lshl_add_u64 v[144:145], s[26:27], 0, v[130:131]
	s_add_i32 m0, s2, 0x2000
	s_nop 0
	global_load_lds_dwordx4 v[144:145], off
	s_waitcnt vmcnt(6)
	s_barrier
	v_mfma_f32_16x16x32_bf16 v[46:49], v[228:231], v[160:163], v[46:49]
	v_mfma_f32_16x16x32_bf16 v[42:45], v[236:239], v[160:163], v[42:45]
	v_mfma_f32_16x16x32_bf16 v[30:33], v[228:231], v[192:195], v[30:33]
	v_mfma_f32_16x16x32_bf16 v[26:29], v[236:239], v[192:195], v[26:29]
	v_mfma_f32_16x16x32_bf16 v[14:17], v[228:231], v[200:203], v[14:17]
	v_mfma_f32_16x16x32_bf16 v[10:13], v[236:239], v[200:203], v[10:13]
	v_mfma_f32_16x16x32_bf16 v[6:9], v[228:231], v[220:223], v[6:9]
	v_mfma_f32_16x16x32_bf16 v[2:5], v[236:239], v[220:223], v[2:5]
	v_mfma_f32_16x16x32_bf16 v[46:49], v[232:235], v[188:191], v[46:49]
	v_mfma_f32_16x16x32_bf16 v[42:45], v[240:243], v[188:191], v[42:45]
	v_mfma_f32_16x16x32_bf16 v[30:33], v[232:235], v[196:199], v[30:33]
	v_mfma_f32_16x16x32_bf16 v[26:29], v[240:243], v[196:199], v[26:29]
	v_mfma_f32_16x16x32_bf16 v[14:17], v[232:235], v[216:219], v[14:17]
	v_mfma_f32_16x16x32_bf16 v[10:13], v[240:243], v[216:219], v[10:13]
	v_mfma_f32_16x16x32_bf16 v[6:9], v[232:235], v[224:227], v[6:9]
	v_mfma_f32_16x16x32_bf16 v[2:5], v[240:243], v[224:227], v[2:5]
	s_add_i32 s2, 0, 0x18000
	v_add_u32_e32 v156, s2, v141
	s_barrier
	ds_read_b128 v[144:147], v156
	ds_read_b128 v[148:151], v156 offset:1024
	ds_read_b128 v[152:155], v156 offset:2048
	ds_read_b128 v[156:159], v156 offset:3072
	s_add_u32 s26, s72, 0x80000
	s_addc_u32 s27, s73, 0
	s_mov_b32 m0, s75
	v_lshl_add_u64 v[228:229], s[26:27], 0, v[134:135]
	ds_read_b128 v[160:163], v143 offset:32768
	ds_read_b128 v[188:191], v143 offset:33792
	ds_read_b128 v[192:195], v143 offset:34816
	ds_read_b128 v[196:199], v143 offset:35840
	ds_read_b128 v[200:203], v143 offset:36864
	ds_read_b128 v[216:219], v143 offset:37888
	ds_read_b128 v[220:223], v143 offset:38912
	ds_read_b128 v[224:227], v143 offset:39936
	global_load_lds_dwordx4 v[228:229], off
	v_lshl_add_u64 v[228:229], s[26:27], 0, v[132:133]
	s_mov_b32 m0, s79
	s_nop 0
	global_load_lds_dwordx4 v[228:229], off
	s_waitcnt lgkmcnt(8)
	s_barrier
	s_waitcnt lgkmcnt(7)
	v_mfma_f32_16x16x32_bf16 v[126:129], v[144:147], v[160:163], v[126:129]
	v_mfma_f32_16x16x32_bf16 v[122:125], v[152:155], v[160:163], v[122:125]
	s_waitcnt lgkmcnt(5)
	v_mfma_f32_16x16x32_bf16 v[118:121], v[144:147], v[192:195], v[118:121]
	v_mfma_f32_16x16x32_bf16 v[114:117], v[152:155], v[192:195], v[114:117]
	s_waitcnt lgkmcnt(3)
	v_mfma_f32_16x16x32_bf16 v[102:105], v[144:147], v[200:203], v[102:105]
	v_mfma_f32_16x16x32_bf16 v[98:101], v[152:155], v[200:203], v[98:101]
	s_waitcnt lgkmcnt(1)
	v_mfma_f32_16x16x32_bf16 v[86:89], v[144:147], v[220:223], v[86:89]
	v_mfma_f32_16x16x32_bf16 v[82:85], v[152:155], v[220:223], v[82:85]
	v_mfma_f32_16x16x32_bf16 v[126:129], v[148:151], v[188:191], v[126:129]
	v_mfma_f32_16x16x32_bf16 v[122:125], v[156:159], v[188:191], v[122:125]
	v_mfma_f32_16x16x32_bf16 v[118:121], v[148:151], v[196:199], v[118:121]
	v_mfma_f32_16x16x32_bf16 v[114:117], v[156:159], v[196:199], v[114:117]
	v_mfma_f32_16x16x32_bf16 v[102:105], v[148:151], v[216:219], v[102:105]
	v_mfma_f32_16x16x32_bf16 v[98:101], v[156:159], v[216:219], v[98:101]
	s_waitcnt lgkmcnt(0)
	v_mfma_f32_16x16x32_bf16 v[86:89], v[148:151], v[224:227], v[86:89]
	v_mfma_f32_16x16x32_bf16 v[82:85], v[156:159], v[224:227], v[82:85]
	s_barrier
	s_add_i32 s17, 0, 0x1c000
	s_add_i32 s2, s2, s3
	v_add_u32_e32 v206, s17, v141
	v_lshl_add_u64 v[164:165], v[164:165], 0, s[28:29]
	s_mov_b32 m0, s2
	ds_read_b128 v[228:231], v206
	ds_read_b128 v[232:235], v206 offset:1024
	ds_read_b128 v[236:239], v206 offset:2048
	ds_read_b128 v[240:243], v206 offset:3072
	global_load_lds_dwordx4 v[164:165], off
	v_lshl_add_u64 v[164:165], v[204:205], 0, s[28:29]
	s_add_i32 m0, s2, 0x2000
	s_nop 0
	global_load_lds_dwordx4 v[164:165], off
	s_barrier
	s_waitcnt lgkmcnt(3)
	v_mfma_f32_16x16x32_bf16 v[110:113], v[228:231], v[160:163], v[110:113]
	s_waitcnt lgkmcnt(1)
	v_mfma_f32_16x16x32_bf16 v[106:109], v[236:239], v[160:163], v[106:109]
	v_mfma_f32_16x16x32_bf16 v[94:97], v[228:231], v[192:195], v[94:97]
	v_mfma_f32_16x16x32_bf16 v[90:93], v[236:239], v[192:195], v[90:93]
	v_mfma_f32_16x16x32_bf16 v[78:81], v[228:231], v[200:203], v[78:81]
	v_mfma_f32_16x16x32_bf16 v[74:77], v[236:239], v[200:203], v[74:77]
	v_mfma_f32_16x16x32_bf16 v[70:73], v[228:231], v[220:223], v[70:73]
	v_mfma_f32_16x16x32_bf16 v[66:69], v[236:239], v[220:223], v[66:69]
	v_mfma_f32_16x16x32_bf16 v[110:113], v[232:235], v[188:191], v[110:113]
	s_waitcnt lgkmcnt(0)
	v_mfma_f32_16x16x32_bf16 v[106:109], v[240:243], v[188:191], v[106:109]
	v_mfma_f32_16x16x32_bf16 v[94:97], v[232:235], v[196:199], v[94:97]
	v_mfma_f32_16x16x32_bf16 v[90:93], v[240:243], v[196:199], v[90:93]
	v_mfma_f32_16x16x32_bf16 v[78:81], v[232:235], v[216:219], v[78:81]
	v_mfma_f32_16x16x32_bf16 v[74:77], v[240:243], v[216:219], v[74:77]
	v_mfma_f32_16x16x32_bf16 v[70:73], v[232:235], v[224:227], v[70:73]
	v_mfma_f32_16x16x32_bf16 v[66:69], v[240:243], v[224:227], v[66:69]
	s_mov_b32 m0, s80
	v_lshl_add_u64 v[164:165], v[244:245], 0, s[28:29]
	s_barrier
	ds_read_b128 v[160:163], v143 offset:49152
	ds_read_b128 v[188:191], v143 offset:50176
	ds_read_b128 v[192:195], v143 offset:51200
	ds_read_b128 v[196:199], v143 offset:52224
	ds_read_b128 v[200:203], v143 offset:53248
	ds_read_b128 v[216:219], v143 offset:54272
	ds_read_b128 v[220:223], v143 offset:55296
	ds_read_b128 v[224:227], v143 offset:56320
	global_load_lds_dwordx4 v[164:165], off
	v_lshl_add_u64 v[164:165], v[246:247], 0, s[28:29]
	s_mov_b32 m0, s81
	s_nop 0
	global_load_lds_dwordx4 v[164:165], off
	s_barrier
	s_waitcnt lgkmcnt(7)
	v_mfma_f32_16x16x32_bf16 v[62:65], v[144:147], v[160:163], v[62:65]
	v_mfma_f32_16x16x32_bf16 v[58:61], v[152:155], v[160:163], v[58:61]
	s_waitcnt lgkmcnt(5)
	v_mfma_f32_16x16x32_bf16 v[54:57], v[144:147], v[192:195], v[54:57]
	v_mfma_f32_16x16x32_bf16 v[50:53], v[152:155], v[192:195], v[50:53]
	s_waitcnt lgkmcnt(3)
	v_mfma_f32_16x16x32_bf16 v[38:41], v[144:147], v[200:203], v[38:41]
	v_mfma_f32_16x16x32_bf16 v[34:37], v[152:155], v[200:203], v[34:37]
	s_waitcnt lgkmcnt(1)
	v_mfma_f32_16x16x32_bf16 v[22:25], v[144:147], v[220:223], v[22:25]
	v_mfma_f32_16x16x32_bf16 v[18:21], v[152:155], v[220:223], v[18:21]
	v_mfma_f32_16x16x32_bf16 v[62:65], v[148:151], v[188:191], v[62:65]
	v_mfma_f32_16x16x32_bf16 v[58:61], v[156:159], v[188:191], v[58:61]
	v_mfma_f32_16x16x32_bf16 v[54:57], v[148:151], v[196:199], v[54:57]
	v_mfma_f32_16x16x32_bf16 v[50:53], v[156:159], v[196:199], v[50:53]
	v_mfma_f32_16x16x32_bf16 v[38:41], v[148:151], v[216:219], v[38:41]
	v_mfma_f32_16x16x32_bf16 v[34:37], v[156:159], v[216:219], v[34:37]
	s_waitcnt lgkmcnt(0)
	v_mfma_f32_16x16x32_bf16 v[22:25], v[148:151], v[224:227], v[22:25]
	v_mfma_f32_16x16x32_bf16 v[18:21], v[156:159], v[224:227], v[18:21]
	s_barrier
	s_add_u32 s26, s70, 0x80080
	s_addc_u32 s27, s71, 0
	s_add_i32 s2, s17, s3
	v_lshl_add_u64 v[144:145], s[26:27], 0, v[0:1]
	s_mov_b32 m0, s2
	s_nop 0
	global_load_lds_dwordx4 v[144:145], off
	v_lshl_add_u64 v[144:145], s[26:27], 0, v[130:131]
	s_add_i32 m0, s2, 0x2000
	s_nop 0
	global_load_lds_dwordx4 v[144:145], off
	s_waitcnt vmcnt(6)
	s_barrier
	v_mfma_f32_16x16x32_bf16 v[46:49], v[228:231], v[160:163], v[46:49]
	v_mfma_f32_16x16x32_bf16 v[42:45], v[236:239], v[160:163], v[42:45]
	v_mfma_f32_16x16x32_bf16 v[30:33], v[228:231], v[192:195], v[30:33]
	v_mfma_f32_16x16x32_bf16 v[26:29], v[236:239], v[192:195], v[26:29]
	v_mfma_f32_16x16x32_bf16 v[14:17], v[228:231], v[200:203], v[14:17]
	v_mfma_f32_16x16x32_bf16 v[10:13], v[236:239], v[200:203], v[10:13]
	v_mfma_f32_16x16x32_bf16 v[6:9], v[228:231], v[220:223], v[6:9]
	v_mfma_f32_16x16x32_bf16 v[2:5], v[236:239], v[220:223], v[2:5]
	v_mfma_f32_16x16x32_bf16 v[46:49], v[232:235], v[188:191], v[46:49]
	v_mfma_f32_16x16x32_bf16 v[42:45], v[240:243], v[188:191], v[42:45]
	v_mfma_f32_16x16x32_bf16 v[30:33], v[232:235], v[196:199], v[30:33]
	v_mfma_f32_16x16x32_bf16 v[26:29], v[240:243], v[196:199], v[26:29]
	v_mfma_f32_16x16x32_bf16 v[14:17], v[232:235], v[216:219], v[14:17]
	v_mfma_f32_16x16x32_bf16 v[10:13], v[240:243], v[216:219], v[10:13]
	v_mfma_f32_16x16x32_bf16 v[6:9], v[232:235], v[224:227], v[6:9]
	v_mfma_f32_16x16x32_bf16 v[2:5], v[240:243], v[224:227], v[2:5]
	s_add_i32 s44, s44, 2
	s_add_u32 s68, s68, 0x100
	s_addc_u32 s69, s69, 0
	s_add_u32 s83, s83, 0x100
	s_addc_u32 s92, s92, 0
	s_cmp_gt_u32 s44, 29
	s_barrier
	s_cbranch_scc0 .LBB0_1044
	v_lshl_add_u32 v144, s47, 8, v140
	v_lshl_or_b32 v146, s46, 8, v142
	v_ashrrev_i32_e32 v145, 31, v144
	v_cvt_pk_bf16_f32 v126, v126, v127
	v_cvt_pk_bf16_f32 v127, v128, v129
	v_cvt_pk_bf16_f32 v128, v122, v123
	v_lshlrev_b64 v[122:123], 12, v[144:145]
	v_ashrrev_i32_e32 v147, 31, v146
	v_cvt_pk_bf16_f32 v129, v124, v125
	v_lshl_add_u64 v[122:123], s[22:23], 0, v[122:123]
	v_lshlrev_b64 v[124:125], 1, v[146:147]
	v_lshl_add_u64 v[122:123], v[122:123], 0, v[124:125]
	v_cvt_pk_bf16_f32 v110, v110, v111
	v_cvt_pk_bf16_f32 v111, v112, v113
	v_cvt_pk_bf16_f32 v112, v106, v107
	v_cvt_pk_bf16_f32 v113, v108, v109
	global_store_dwordx4 v[122:123], v[110:113], off offset:256
	v_cvt_pk_bf16_f32 v94, v94, v95
	v_cvt_pk_bf16_f32 v95, v96, v97
	v_or_b32_e32 v110, 16, v144
	v_ashrrev_i32_e32 v111, 31, v110
	v_lshlrev_b64 v[110:111], 12, v[110:111]
	v_lshl_add_u64 v[110:111], s[22:23], 0, v[110:111]
	v_lshl_add_u64 v[110:111], v[110:111], 0, v[124:125]
	v_cvt_pk_bf16_f32 v96, v90, v91
	v_cvt_pk_bf16_f32 v97, v92, v93
	global_store_dwordx4 v[110:111], v[94:97], off offset:256
	s_mov_b32 s2, 0x80000
	v_cvt_pk_bf16_f32 v62, v62, v63
	v_or_b32_e32 v94, 32, v144
	v_ashrrev_i32_e32 v95, 31, v94
	v_cvt_pk_bf16_f32 v63, v64, v65
	v_cvt_pk_bf16_f32 v65, v60, v61
	s_mov_b64 s[4:5], 0x80000
	v_add_co_u32_e32 v60, vcc, s2, v122
	v_lshlrev_b64 v[94:95], 12, v[94:95]
	v_cvt_pk_bf16_f32 v64, v58, v59
	v_lshl_add_u64 v[58:59], v[122:123], 0, s[4:5]
	v_addc_co_u32_e32 v61, vcc, 0, v123, vcc
	v_cvt_pk_bf16_f32 v46, v46, v47
	v_cvt_pk_bf16_f32 v47, v48, v49
	v_cvt_pk_bf16_f32 v48, v42, v43
	v_cvt_pk_bf16_f32 v49, v44, v45
	s_mov_b32 s2, 0x90000
	v_lshl_add_u64 v[94:95], s[22:23], 0, v[94:95]
	global_store_dwordx4 v[58:59], v[46:49], off offset:256
	s_mov_b64 s[4:5], 0x90000
	v_lshl_add_u64 v[94:95], v[94:95], 0, v[124:125]
	v_add_co_u32_e32 v48, vcc, s2, v122
	v_cvt_pk_bf16_f32 v78, v78, v79
	v_cvt_pk_bf16_f32 v79, v80, v81
	v_cvt_pk_bf16_f32 v80, v74, v75
	v_cvt_pk_bf16_f32 v81, v76, v77
	v_lshl_add_u64 v[46:47], v[122:123], 0, s[4:5]
	v_addc_co_u32_e32 v49, vcc, 0, v123, vcc
	v_cvt_pk_bf16_f32 v30, v30, v31
	v_cvt_pk_bf16_f32 v31, v32, v33
	v_cvt_pk_bf16_f32 v32, v26, v27
	v_cvt_pk_bf16_f32 v33, v28, v29
	s_mov_b32 s2, 0xa0000
	global_store_dwordx4 v[94:95], v[78:81], off offset:256
	global_store_dwordx4 v[46:47], v[30:33], off offset:256
	s_mov_b64 s[4:5], 0xa0000
	v_or_b32_e32 v78, 48, v144
	v_add_co_u32_e32 v32, vcc, s2, v122
	v_ashrrev_i32_e32 v79, 31, v78
	v_lshl_add_u64 v[30:31], v[122:123], 0, s[4:5]
	v_addc_co_u32_e32 v33, vcc, 0, v123, vcc
	v_cvt_pk_bf16_f32 v14, v14, v15
	v_cvt_pk_bf16_f32 v15, v16, v17
	v_cvt_pk_bf16_f32 v16, v10, v11
	v_cvt_pk_bf16_f32 v17, v12, v13
	s_mov_b32 s2, 0xb0000
	v_lshlrev_b64 v[78:79], 12, v[78:79]
	global_store_dwordx4 v[30:31], v[14:17], off offset:256
	v_lshl_add_u64 v[78:79], s[22:23], 0, v[78:79]
	s_mov_b64 s[4:5], 0xb0000
	v_add_co_u32_e32 v16, vcc, s2, v122
	v_cvt_pk_bf16_f32 v106, v118, v119
	s_nop 0
	v_addc_co_u32_e32 v17, vcc, 0, v123, vcc
	v_cvt_pk_bf16_f32 v107, v120, v121
	v_cvt_pk_bf16_f32 v108, v114, v115
	v_cvt_pk_bf16_f32 v109, v116, v117
	v_cvt_pk_bf16_f32 v90, v102, v103
	v_cvt_pk_bf16_f32 v91, v104, v105
	v_cvt_pk_bf16_f32 v92, v98, v99
	v_cvt_pk_bf16_f32 v93, v100, v101
	v_cvt_pk_bf16_f32 v74, v86, v87
	v_cvt_pk_bf16_f32 v75, v88, v89
	v_cvt_pk_bf16_f32 v76, v82, v83
	v_cvt_pk_bf16_f32 v77, v84, v85
	v_lshl_add_u64 v[78:79], v[78:79], 0, v[124:125]
	v_cvt_pk_bf16_f32 v70, v70, v71
	v_cvt_pk_bf16_f32 v71, v72, v73
	v_cvt_pk_bf16_f32 v72, v66, v67
	v_cvt_pk_bf16_f32 v73, v68, v69
	v_cvt_pk_bf16_f32 v42, v54, v55
	v_cvt_pk_bf16_f32 v43, v56, v57
	v_cvt_pk_bf16_f32 v44, v50, v51
	v_cvt_pk_bf16_f32 v45, v52, v53
	v_cvt_pk_bf16_f32 v26, v38, v39
	v_cvt_pk_bf16_f32 v27, v40, v41
	v_cvt_pk_bf16_f32 v28, v34, v35
	v_cvt_pk_bf16_f32 v29, v36, v37
	v_cvt_pk_bf16_f32 v10, v22, v23
	v_cvt_pk_bf16_f32 v11, v24, v25
	v_cvt_pk_bf16_f32 v12, v18, v19
	v_cvt_pk_bf16_f32 v13, v20, v21
	v_lshl_add_u64 v[14:15], v[122:123], 0, s[4:5]
	v_cvt_pk_bf16_f32 v6, v6, v7
	v_cvt_pk_bf16_f32 v7, v8, v9
	v_cvt_pk_bf16_f32 v8, v2, v3
	v_cvt_pk_bf16_f32 v9, v4, v5
	s_and_b64 vcc, exec, s[0:1]
	s_mov_b32 s46, s42
	s_mov_b32 s47, s54
	s_mov_b64 s[70:71], s[64:65]
	s_mov_b64 s[68:69], s[62:63]
	global_store_dwordx4 v[122:123], v[126:129], off
	global_store_dwordx4 v[110:111], v[106:109], off
	global_store_dwordx4 v[94:95], v[90:93], off
	global_store_dwordx4 v[78:79], v[74:77], off
	global_store_dwordx4 v[78:79], v[70:73], off offset:256
	global_store_dwordx4 v[60:61], v[62:65], off
	global_store_dwordx4 v[48:49], v[42:45], off
	global_store_dwordx4 v[32:33], v[26:29], off
	global_store_dwordx4 v[16:17], v[10:13], off
	global_store_dwordx4 v[14:15], v[6:9], off offset:256
	s_cbranch_vccz .LBB0_1041
	v_readlane_b32 s0, v254, 12
	s_waitcnt vmcnt(0)
	v_readlane_b32 s1, v254, 13
	v_readlane_b32 s84, v251, 38
	s_andn2_b64 vcc, exec, s[0:1]
	v_readlane_b32 s85, v251, 39
	v_readlane_b32 s86, v251, 40
	v_readlane_b32 s87, v251, 41
	s_cbranch_vccnz .LBB0_1048
	s_barrier
